# K-loops: the three back-to-back waits before each MFMA segment merged into one s_waitcnt vmcnt(8) lgkmcnt(0), on top of the static raise for waves 0-3
# speedup vs baseline: 1.0089x; 1.0089x over previous
; #define PG8_STAGE(bufoff, gbase, voff) do { _Pragma("unroll") for (int _i = 0; _i < 2; ++_i) \
;         __builtin_amdgcn_global_load_lds((const unsigned*)((const char*)(gbase) + (voff)[_i]), (LAS unsigned*)(lds + (bufoff) + ldsw + _i * 8192), 16, 0, 0); } while (0)
; #define PG8_LDA(dst, b, h) do { _Pragma("unroll") for (int m = 0; m < 4; ++m) _Pragma("unroll") for (int k = 0; k < 2; ++k) dst[m][k] = *(const LAS bf16x8*)(lds + PG8_SA(b, h) + aoff + m * 2048 + k * 1024); } while (0)
; #define PG8_LDB(dst, b, h) do { _Pragma("unroll") for (int n = 0; n < 2; ++n) _Pragma("unroll") for (int k = 0; k < 2; ++k) dst[n][k] = *(const LAS bf16x8*)(lds + PG8_SB(b, h) + boff + n * 2048 + k * 1024); } while (0)
; #define PG8_MMA(ai, bj, At, Bt) do { __builtin_amdgcn_s_setprio(1); _Pragma("unroll") for (int m = 0; m < 4; ++m) _Pragma("unroll") for (int n = 0; n < 2; ++n) _Pragma("unroll") for (int k = 0; k < 2; ++k) \
;         acc[ai][bj][m][n] = __builtin_amdgcn_mfma_f32_16x16x32_bf16(Bt[n][k], At[m][k], acc[ai][bj][m][n], 0, 0, 0); __builtin_amdgcn_s_setprio(0); } while (0)
; #define PG8_WAIT_V(n) asm volatile("s_waitcnt vmcnt(" #n ")" ::: "memory")
; #define PG8_WAIT_L(n) asm volatile("s_waitcnt lgkmcnt(" #n ")" ::: "memory")
; #define PG8_BAR __builtin_amdgcn_s_barrier()
; #define PG8_SCHED __builtin_amdgcn_sched_barrier(0)
; template <class Sched, class Epi, bool ALIGN_EPI, bool SP2>
; __device__ __forceinline__ void gemm_phase(LAS unsigned char* lds, const int K, const int lda, const int ldb, const Sched& S, const Epi& E) {
;     ...
;         for (int t = 0; t < nt; t += 2) {
;             const bool last = (t == nt - 2);
;             const char* a1 = cA + (size_t)(t + 1) * kstep;
;             const char* a2 = last ? nA : cA + (size_t)(t + 2) * kstep; const char* b2 = last ? nB : cB + (size_t)(t + 2) * kstep;
;             const char* a3 = a2 + kstep; const char* b3 = b2 + kstep;
;             if constexpr (SP2) {
;             PG8_LDB(B0, 0, 0); PG8_LDB(B1, 0, 1); PG8_SCHED; PG8_LDA(At, 0, 0); PG8_STAGE(PG8_SA(1, 1), a1 + hstepA, voffA);
;             PG8_WAIT_V(8); PG8_WAIT_L(0); PG8_BAR; PG8_MMA(0, 0, At, B0); PG8_MMA(0, 1, At, B1); PG8_BAR; PG8_SCHED;
;             PG8_LDA(At, 0, 1); PG8_STAGE(PG8_SB(0, 0), b2, voffB); PG8_STAGE(PG8_SB(0, 1), b2 + hstepB, voffB); PG8_STAGE(PG8_SA(0, 0), a2, voffA);
.Lprio_skip_155:
.LBB0_155:
	ds_read_b128 v[140:143], v147
	ds_read_b128 v[150:153], v147 offset:1024
	ds_read_b128 v[154:157], v147 offset:2048
	ds_read_b128 v[158:161], v147 offset:3072
	ds_read_b128 v[162:165], v148
	ds_read_b128 v[166:169], v148 offset:1024
	ds_read_b128 v[170:173], v148 offset:2048
	ds_read_b128 v[180:183], v148 offset:3072
	s_add_u32 s22, s20, 0xfff80080
	s_addc_u32 s23, s21, -1
	s_cmp_eq_u32 s75, 28
	s_cselect_b32 s25, s15, s23
	s_cselect_b32 s24, s14, s22
	s_cselect_b32 s23, s17, s74
	s_cselect_b32 s22, s16, s13
	v_lshl_add_u64 v[174:175], s[20:21], 0, v[136:137]
	s_add_i32 m0, s3, 0xc000
	ds_read_b128 v[184:187], v149
	ds_read_b128 v[188:191], v149 offset:1024
	ds_read_b128 v[192:195], v149 offset:2048
	ds_read_b128 v[196:199], v149 offset:3072
	ds_read_b128 v[200:203], v149 offset:4096
	ds_read_b128 v[204:207], v149 offset:5120
	ds_read_b128 v[208:211], v149 offset:6144
	ds_read_b128 v[212:215], v149 offset:7168
	global_load_lds_dwordx4 v[174:175], off
	v_lshl_add_u64 v[174:175], s[20:21], 0, v[138:139]
	s_add_i32 m0, s3, 0xe000
	s_nop 0
	global_load_lds_dwordx4 v[174:175], off
	s_waitcnt vmcnt(8) lgkmcnt(0)
	s_barrier
	v_mfma_f32_16x16x32_bf16 v[124:127], v[140:143], v[184:187], v[124:127]
	v_mfma_f32_16x16x32_bf16 v[120:123], v[154:157], v[184:187], v[120:123]
	v_mfma_f32_16x16x32_bf16 v[108:111], v[140:143], v[192:195], v[108:111]
	v_mfma_f32_16x16x32_bf16 v[104:107], v[154:157], v[192:195], v[104:107]
	v_mfma_f32_16x16x32_bf16 v[92:95], v[140:143], v[200:203], v[92:95]
	v_mfma_f32_16x16x32_bf16 v[88:91], v[154:157], v[200:203], v[88:91]
	v_mfma_f32_16x16x32_bf16 v[76:79], v[140:143], v[208:211], v[76:79]
	v_mfma_f32_16x16x32_bf16 v[72:75], v[154:157], v[208:211], v[72:75]
	v_mfma_f32_16x16x32_bf16 v[124:127], v[150:153], v[188:191], v[124:127]
	v_mfma_f32_16x16x32_bf16 v[120:123], v[158:161], v[188:191], v[120:123]
	v_mfma_f32_16x16x32_bf16 v[108:111], v[150:153], v[196:199], v[108:111]
	v_mfma_f32_16x16x32_bf16 v[104:107], v[158:161], v[196:199], v[104:107]
	v_mfma_f32_16x16x32_bf16 v[92:95], v[150:153], v[204:207], v[92:95]
	v_mfma_f32_16x16x32_bf16 v[88:91], v[158:161], v[204:207], v[88:91]
	v_mfma_f32_16x16x32_bf16 v[76:79], v[150:153], v[212:215], v[76:79]
	v_mfma_f32_16x16x32_bf16 v[72:75], v[158:161], v[212:215], v[72:75]
	v_mfma_f32_16x16x32_bf16 v[116:119], v[162:165], v[184:187], v[116:119]
	v_mfma_f32_16x16x32_bf16 v[112:115], v[170:173], v[184:187], v[112:115]
	v_mfma_f32_16x16x32_bf16 v[100:103], v[162:165], v[192:195], v[100:103]
	v_mfma_f32_16x16x32_bf16 v[96:99], v[170:173], v[192:195], v[96:99]
	v_mfma_f32_16x16x32_bf16 v[84:87], v[162:165], v[200:203], v[84:87]
	v_mfma_f32_16x16x32_bf16 v[80:83], v[170:173], v[200:203], v[80:83]
	v_mfma_f32_16x16x32_bf16 v[68:71], v[162:165], v[208:211], v[68:71]
	v_mfma_f32_16x16x32_bf16 v[64:67], v[170:173], v[208:211], v[64:67]
	v_mfma_f32_16x16x32_bf16 v[116:119], v[166:169], v[188:191], v[116:119]
	v_mfma_f32_16x16x32_bf16 v[112:115], v[180:183], v[188:191], v[112:115]
	v_mfma_f32_16x16x32_bf16 v[100:103], v[166:169], v[196:199], v[100:103]
	v_mfma_f32_16x16x32_bf16 v[96:99], v[180:183], v[196:199], v[96:99]
	v_mfma_f32_16x16x32_bf16 v[84:87], v[166:169], v[204:207], v[84:87]
	v_mfma_f32_16x16x32_bf16 v[80:83], v[180:183], v[204:207], v[80:83]
	v_mfma_f32_16x16x32_bf16 v[68:71], v[166:169], v[212:215], v[68:71]
	v_mfma_f32_16x16x32_bf16 v[64:67], v[180:183], v[212:215], v[64:67]
	s_barrier
	s_add_i32 s78, s35, s2
	v_lshl_add_u64 v[174:175], s[22:23], 0, v[130:131]
	s_mov_b32 m0, s78
	ds_read_b128 v[184:187], v149 offset:16384
	ds_read_b128 v[188:191], v149 offset:17408
	ds_read_b128 v[192:195], v149 offset:18432
	ds_read_b128 v[196:199], v149 offset:19456
	ds_read_b128 v[200:203], v149 offset:20480
	ds_read_b128 v[204:207], v149 offset:21504
	ds_read_b128 v[208:211], v149 offset:22528
	ds_read_b128 v[212:215], v149 offset:23552
	global_load_lds_dwordx4 v[174:175], off
	s_add_i32 m0, s78, 0x2000
	s_add_u32 s78, s22, 0x80000
	v_lshl_add_u64 v[216:217], s[22:23], 0, v[134:135]
	s_addc_u32 s79, s23, 0
	s_add_i32 s84, s50, s2
	global_load_lds_dwordx4 v[216:217], off
	v_lshl_add_u64 v[218:219], s[78:79], 0, v[130:131]
	s_mov_b32 m0, s84
	v_lshl_add_u64 v[220:221], s[24:25], 0, v[132:133]
	global_load_lds_dwordx4 v[218:219], off
	v_lshl_add_u64 v[218:219], s[78:79], 0, v[134:135]
	s_add_i32 m0, s84, 0x2000
	s_nop 0
	global_load_lds_dwordx4 v[218:219], off
	v_lshl_add_u64 v[218:219], s[24:25], 0, v[128:129]
	s_mov_b32 m0, s3
	s_nop 0
	global_load_lds_dwordx4 v[218:219], off
	s_mov_b32 m0, s19
	s_nop 0
	global_load_lds_dwordx4 v[220:221], off
	s_waitcnt vmcnt(8) lgkmcnt(0)
	s_barrier
; #define PG8_STAGE(bufoff, gbase, voff) do { _Pragma("unroll") for (int _i = 0; _i < 2; ++_i) \
;         __builtin_amdgcn_global_load_lds((const unsigned*)((const char*)(gbase) + (voff)[_i]), (LAS unsigned*)(lds + (bufoff) + ldsw + _i * 8192), 16, 0, 0); } while (0)
; #define PG8_LDA(dst, b, h) do { _Pragma("unroll") for (int m = 0; m < 4; ++m) _Pragma("unroll") for (int k = 0; k < 2; ++k) dst[m][k] = *(const LAS bf16x8*)(lds + PG8_SA(b, h) + aoff + m * 2048 + k * 1024); } while (0)
; #define PG8_LDB(dst, b, h) do { _Pragma("unroll") for (int n = 0; n < 2; ++n) _Pragma("unroll") for (int k = 0; k < 2; ++k) dst[n][k] = *(const LAS bf16x8*)(lds + PG8_SB(b, h) + boff + n * 2048 + k * 1024); } while (0)
; #define PG8_MMA(ai, bj, At, Bt) do { __builtin_amdgcn_s_setprio(1); _Pragma("unroll") for (int m = 0; m < 4; ++m) _Pragma("unroll") for (int n = 0; n < 2; ++n) _Pragma("unroll") for (int k = 0; k < 2; ++k) \
;         acc[ai][bj][m][n] = __builtin_amdgcn_mfma_f32_16x16x32_bf16(Bt[n][k], At[m][k], acc[ai][bj][m][n], 0, 0, 0); __builtin_amdgcn_s_setprio(0); } while (0)
; #define PG8_WAIT_V(n) asm volatile("s_waitcnt vmcnt(" #n ")" ::: "memory")
; #define PG8_WAIT_L(n) asm volatile("s_waitcnt lgkmcnt(" #n ")" ::: "memory")
; #define PG8_BAR __builtin_amdgcn_s_barrier()
; #define PG8_SCHED __builtin_amdgcn_sched_barrier(0)
; template <class Sched, class Epi, bool ALIGN_EPI, bool SP2>
; __device__ __forceinline__ void gemm_phase(LAS unsigned char* lds, const int K, const int lda, const int ldb, const Sched& S, const Epi& E) {
;     ...
;             PG8_WAIT_V(8); PG8_WAIT_L(0); PG8_BAR; PG8_MMA(1, 0, At, B0); PG8_MMA(1, 1, At, B1); PG8_BAR; PG8_SCHED;
;             PG8_LDB(B0, 1, 0); PG8_LDB(B1, 1, 1); PG8_SCHED; PG8_LDA(At, 1, 0); PG8_STAGE(PG8_SA(0, 1), a2 + hstepA, voffA);
;             PG8_WAIT_V(8); PG8_WAIT_L(0); PG8_BAR; PG8_MMA(0, 0, At, B0); PG8_MMA(0, 1, At, B1); PG8_BAR; PG8_SCHED;
	v_mfma_f32_16x16x32_bf16 v[60:63], v[140:143], v[184:187], v[60:63]
	v_mfma_f32_16x16x32_bf16 v[56:59], v[154:157], v[184:187], v[56:59]
	v_mfma_f32_16x16x32_bf16 v[44:47], v[140:143], v[192:195], v[44:47]
	v_mfma_f32_16x16x32_bf16 v[40:43], v[154:157], v[192:195], v[40:43]
	v_mfma_f32_16x16x32_bf16 v[28:31], v[140:143], v[200:203], v[28:31]
	v_mfma_f32_16x16x32_bf16 v[24:27], v[154:157], v[200:203], v[24:27]
	v_mfma_f32_16x16x32_bf16 v[12:15], v[140:143], v[208:211], v[12:15]
	v_mfma_f32_16x16x32_bf16 v[8:11], v[154:157], v[208:211], v[8:11]
	v_mfma_f32_16x16x32_bf16 v[60:63], v[150:153], v[188:191], v[60:63]
	v_mfma_f32_16x16x32_bf16 v[56:59], v[158:161], v[188:191], v[56:59]
	v_mfma_f32_16x16x32_bf16 v[44:47], v[150:153], v[196:199], v[44:47]
	v_mfma_f32_16x16x32_bf16 v[40:43], v[158:161], v[196:199], v[40:43]
	v_mfma_f32_16x16x32_bf16 v[28:31], v[150:153], v[204:207], v[28:31]
	v_mfma_f32_16x16x32_bf16 v[24:27], v[158:161], v[204:207], v[24:27]
	v_mfma_f32_16x16x32_bf16 v[12:15], v[150:153], v[212:215], v[12:15]
	v_mfma_f32_16x16x32_bf16 v[8:11], v[158:161], v[212:215], v[8:11]
	v_mfma_f32_16x16x32_bf16 v[52:55], v[162:165], v[184:187], v[52:55]
	v_mfma_f32_16x16x32_bf16 v[48:51], v[170:173], v[184:187], v[48:51]
	v_mfma_f32_16x16x32_bf16 v[36:39], v[162:165], v[192:195], v[36:39]
	v_mfma_f32_16x16x32_bf16 v[32:35], v[170:173], v[192:195], v[32:35]
	v_mfma_f32_16x16x32_bf16 v[20:23], v[162:165], v[200:203], v[20:23]
	v_mfma_f32_16x16x32_bf16 v[16:19], v[170:173], v[200:203], v[16:19]
	v_mfma_f32_16x16x32_bf16 v[4:7], v[162:165], v[208:211], v[4:7]
	v_mfma_f32_16x16x32_bf16 v[0:3], v[170:173], v[208:211], v[0:3]
	v_mfma_f32_16x16x32_bf16 v[52:55], v[166:169], v[188:191], v[52:55]
	v_mfma_f32_16x16x32_bf16 v[48:51], v[180:183], v[188:191], v[48:51]
	v_mfma_f32_16x16x32_bf16 v[36:39], v[166:169], v[196:199], v[36:39]
	v_mfma_f32_16x16x32_bf16 v[32:35], v[180:183], v[196:199], v[32:35]
	v_mfma_f32_16x16x32_bf16 v[20:23], v[166:169], v[204:207], v[20:23]
	v_mfma_f32_16x16x32_bf16 v[16:19], v[180:183], v[204:207], v[16:19]
	v_mfma_f32_16x16x32_bf16 v[4:7], v[166:169], v[212:215], v[4:7]
	v_mfma_f32_16x16x32_bf16 v[0:3], v[180:183], v[212:215], v[0:3]
	s_barrier
	s_add_i32 s78, 0, 0x18000
	s_add_i32 s79, 0, 0x1c000
	v_add_u32_e32 v158, s78, v145
	v_add_u32_e32 v177, s79, v145
	ds_read_b128 v[140:143], v158
	ds_read_b128 v[150:153], v158 offset:1024
	ds_read_b128 v[154:157], v158 offset:2048
	ds_read_b128 v[158:161], v158 offset:3072
	ds_read_b128 v[162:165], v177
	ds_read_b128 v[166:169], v177 offset:1024
	ds_read_b128 v[170:173], v177 offset:2048
	ds_read_b128 v[180:183], v177 offset:3072
	s_add_u32 s24, s24, 0x80000
	s_addc_u32 s25, s25, 0
	s_mov_b32 m0, s26
	v_lshl_add_u64 v[222:223], s[24:25], 0, v[128:129]
	ds_read_b128 v[184:187], v149 offset:32768
	ds_read_b128 v[188:191], v149 offset:33792
	ds_read_b128 v[192:195], v149 offset:34816
	ds_read_b128 v[196:199], v149 offset:35840
	ds_read_b128 v[200:203], v149 offset:36864
	ds_read_b128 v[204:207], v149 offset:37888
	ds_read_b128 v[208:211], v149 offset:38912
	ds_read_b128 v[212:215], v149 offset:39936
	global_load_lds_dwordx4 v[222:223], off
	v_lshl_add_u64 v[222:223], s[24:25], 0, v[132:133]
	s_mov_b32 m0, s27
	s_nop 0
	global_load_lds_dwordx4 v[222:223], off
	s_waitcnt vmcnt(8) lgkmcnt(0)
	s_barrier
	v_mfma_f32_16x16x32_bf16 v[124:127], v[140:143], v[184:187], v[124:127]
	v_mfma_f32_16x16x32_bf16 v[120:123], v[154:157], v[184:187], v[120:123]
	v_mfma_f32_16x16x32_bf16 v[108:111], v[140:143], v[192:195], v[108:111]
	v_mfma_f32_16x16x32_bf16 v[104:107], v[154:157], v[192:195], v[104:107]
	v_mfma_f32_16x16x32_bf16 v[92:95], v[140:143], v[200:203], v[92:95]
	v_mfma_f32_16x16x32_bf16 v[88:91], v[154:157], v[200:203], v[88:91]
	v_mfma_f32_16x16x32_bf16 v[76:79], v[140:143], v[208:211], v[76:79]
	v_mfma_f32_16x16x32_bf16 v[72:75], v[154:157], v[208:211], v[72:75]
	v_mfma_f32_16x16x32_bf16 v[124:127], v[150:153], v[188:191], v[124:127]
	v_mfma_f32_16x16x32_bf16 v[120:123], v[158:161], v[188:191], v[120:123]
	v_mfma_f32_16x16x32_bf16 v[108:111], v[150:153], v[196:199], v[108:111]
	v_mfma_f32_16x16x32_bf16 v[104:107], v[158:161], v[196:199], v[104:107]
	v_mfma_f32_16x16x32_bf16 v[92:95], v[150:153], v[204:207], v[92:95]
	v_mfma_f32_16x16x32_bf16 v[88:91], v[158:161], v[204:207], v[88:91]
	v_mfma_f32_16x16x32_bf16 v[76:79], v[150:153], v[212:215], v[76:79]
	v_mfma_f32_16x16x32_bf16 v[72:75], v[158:161], v[212:215], v[72:75]
	v_mfma_f32_16x16x32_bf16 v[116:119], v[162:165], v[184:187], v[116:119]
	v_mfma_f32_16x16x32_bf16 v[112:115], v[170:173], v[184:187], v[112:115]
	v_mfma_f32_16x16x32_bf16 v[100:103], v[162:165], v[192:195], v[100:103]
	v_mfma_f32_16x16x32_bf16 v[96:99], v[170:173], v[192:195], v[96:99]
	v_mfma_f32_16x16x32_bf16 v[84:87], v[162:165], v[200:203], v[84:87]
	v_mfma_f32_16x16x32_bf16 v[80:83], v[170:173], v[200:203], v[80:83]
	v_mfma_f32_16x16x32_bf16 v[68:71], v[162:165], v[208:211], v[68:71]
	v_mfma_f32_16x16x32_bf16 v[64:67], v[170:173], v[208:211], v[64:67]
	v_mfma_f32_16x16x32_bf16 v[116:119], v[166:169], v[188:191], v[116:119]
	v_mfma_f32_16x16x32_bf16 v[112:115], v[180:183], v[188:191], v[112:115]
	v_mfma_f32_16x16x32_bf16 v[100:103], v[166:169], v[196:199], v[100:103]
	v_mfma_f32_16x16x32_bf16 v[96:99], v[180:183], v[196:199], v[96:99]
	v_mfma_f32_16x16x32_bf16 v[84:87], v[166:169], v[204:207], v[84:87]
	v_mfma_f32_16x16x32_bf16 v[80:83], v[180:183], v[204:207], v[80:83]
	v_mfma_f32_16x16x32_bf16 v[68:71], v[166:169], v[212:215], v[68:71]
	v_mfma_f32_16x16x32_bf16 v[64:67], v[180:183], v[212:215], v[64:67]
	s_barrier
; #define PG8_STAGE(bufoff, gbase, voff) do { _Pragma("unroll") for (int _i = 0; _i < 2; ++_i) \
;         __builtin_amdgcn_global_load_lds((const unsigned*)((const char*)(gbase) + (voff)[_i]), (LAS unsigned*)(lds + (bufoff) + ldsw + _i * 8192), 16, 0, 0); } while (0)
; #define PG8_LDA(dst, b, h) do { _Pragma("unroll") for (int m = 0; m < 4; ++m) _Pragma("unroll") for (int k = 0; k < 2; ++k) dst[m][k] = *(const LAS bf16x8*)(lds + PG8_SA(b, h) + aoff + m * 2048 + k * 1024); } while (0)
; #define PG8_MMA(ai, bj, At, Bt) do { __builtin_amdgcn_s_setprio(1); _Pragma("unroll") for (int m = 0; m < 4; ++m) _Pragma("unroll") for (int n = 0; n < 2; ++n) _Pragma("unroll") for (int k = 0; k < 2; ++k) \
;         acc[ai][bj][m][n] = __builtin_amdgcn_mfma_f32_16x16x32_bf16(Bt[n][k], At[m][k], acc[ai][bj][m][n], 0, 0, 0); __builtin_amdgcn_s_setprio(0); } while (0)
; #define PG8_WAIT_V(n) asm volatile("s_waitcnt vmcnt(" #n ")" ::: "memory")
; #define PG8_WAIT_L(n) asm volatile("s_waitcnt lgkmcnt(" #n ")" ::: "memory")
; #define PG8_BAR __builtin_amdgcn_s_barrier()
; #define PG8_SCHED __builtin_amdgcn_sched_barrier(0)
; template <class Sched, class Epi, bool ALIGN_EPI, bool SP2>
; __device__ __forceinline__ void gemm_phase(LAS unsigned char* lds, const int K, const int lda, const int ldb, const Sched& S, const Epi& E) {
;     ...
;             PG8_LDA(At, 1, 1); PG8_STAGE(PG8_SB(1, 0), b3, voffB); PG8_STAGE(PG8_SB(1, 1), b3 + hstepB, voffB); PG8_STAGE(PG8_SA(1, 0), a3, voffA);
;             PG8_WAIT_V(8); PG8_WAIT_L(0); PG8_BAR; PG8_MMA(1, 0, At, B0); PG8_MMA(1, 1, At, B1); PG8_BAR; PG8_SCHED;
	s_add_i32 s24, s78, s2
	v_lshl_add_u64 v[174:175], v[174:175], 0, s[4:5]
	s_mov_b32 m0, s24
	ds_read_b128 v[184:187], v149 offset:49152
	ds_read_b128 v[188:191], v149 offset:50176
	ds_read_b128 v[192:195], v149 offset:51200
	ds_read_b128 v[196:199], v149 offset:52224
	ds_read_b128 v[200:203], v149 offset:53248
	ds_read_b128 v[204:207], v149 offset:54272
	ds_read_b128 v[208:211], v149 offset:55296
	ds_read_b128 v[212:215], v149 offset:56320
	global_load_lds_dwordx4 v[174:175], off
	s_add_i32 m0, s24, 0x2000
	s_add_u32 s22, s22, 0x80080
	v_lshl_add_u64 v[174:175], v[216:217], 0, s[4:5]
	s_addc_u32 s23, s23, 0
	s_add_i32 s24, s79, s2
	global_load_lds_dwordx4 v[174:175], off
	v_lshl_add_u64 v[174:175], s[22:23], 0, v[130:131]
	s_mov_b32 m0, s24
	s_nop 0
	global_load_lds_dwordx4 v[174:175], off
	v_lshl_add_u64 v[174:175], s[22:23], 0, v[134:135]
	s_add_i32 m0, s24, 0x2000
	s_nop 0
	global_load_lds_dwordx4 v[174:175], off
	v_lshl_add_u64 v[174:175], v[218:219], 0, s[4:5]
	s_mov_b32 m0, s29
	s_nop 0
	global_load_lds_dwordx4 v[174:175], off
	v_lshl_add_u64 v[174:175], v[220:221], 0, s[4:5]
	s_mov_b32 m0, s33
	s_nop 0
	global_load_lds_dwordx4 v[174:175], off
	s_waitcnt vmcnt(8) lgkmcnt(0)
	s_barrier
	v_mfma_f32_16x16x32_bf16 v[60:63], v[140:143], v[184:187], v[60:63]
	v_mfma_f32_16x16x32_bf16 v[56:59], v[154:157], v[184:187], v[56:59]
	v_mfma_f32_16x16x32_bf16 v[44:47], v[140:143], v[192:195], v[44:47]
	v_mfma_f32_16x16x32_bf16 v[40:43], v[154:157], v[192:195], v[40:43]
	v_mfma_f32_16x16x32_bf16 v[28:31], v[140:143], v[200:203], v[28:31]
	v_mfma_f32_16x16x32_bf16 v[24:27], v[154:157], v[200:203], v[24:27]
	v_mfma_f32_16x16x32_bf16 v[12:15], v[140:143], v[208:211], v[12:15]
	v_mfma_f32_16x16x32_bf16 v[8:11], v[154:157], v[208:211], v[8:11]
	v_mfma_f32_16x16x32_bf16 v[60:63], v[150:153], v[188:191], v[60:63]
	v_mfma_f32_16x16x32_bf16 v[56:59], v[158:161], v[188:191], v[56:59]
	v_mfma_f32_16x16x32_bf16 v[44:47], v[150:153], v[196:199], v[44:47]
	v_mfma_f32_16x16x32_bf16 v[40:43], v[158:161], v[196:199], v[40:43]
	v_mfma_f32_16x16x32_bf16 v[28:31], v[150:153], v[204:207], v[28:31]
	v_mfma_f32_16x16x32_bf16 v[24:27], v[158:161], v[204:207], v[24:27]
	v_mfma_f32_16x16x32_bf16 v[12:15], v[150:153], v[212:215], v[12:15]
	v_mfma_f32_16x16x32_bf16 v[8:11], v[158:161], v[212:215], v[8:11]
	v_mfma_f32_16x16x32_bf16 v[52:55], v[162:165], v[184:187], v[52:55]
	v_mfma_f32_16x16x32_bf16 v[48:51], v[170:173], v[184:187], v[48:51]
	v_mfma_f32_16x16x32_bf16 v[36:39], v[162:165], v[192:195], v[36:39]
	v_mfma_f32_16x16x32_bf16 v[32:35], v[170:173], v[192:195], v[32:35]
	v_mfma_f32_16x16x32_bf16 v[20:23], v[162:165], v[200:203], v[20:23]
	v_mfma_f32_16x16x32_bf16 v[16:19], v[170:173], v[200:203], v[16:19]
	v_mfma_f32_16x16x32_bf16 v[4:7], v[162:165], v[208:211], v[4:7]
	v_mfma_f32_16x16x32_bf16 v[0:3], v[170:173], v[208:211], v[0:3]
	v_mfma_f32_16x16x32_bf16 v[52:55], v[166:169], v[188:191], v[52:55]
	v_mfma_f32_16x16x32_bf16 v[48:51], v[180:183], v[188:191], v[48:51]
	v_mfma_f32_16x16x32_bf16 v[36:39], v[166:169], v[196:199], v[36:39]
	v_mfma_f32_16x16x32_bf16 v[32:35], v[180:183], v[196:199], v[32:35]
	v_mfma_f32_16x16x32_bf16 v[20:23], v[166:169], v[204:207], v[20:23]
	v_mfma_f32_16x16x32_bf16 v[16:19], v[180:183], v[204:207], v[16:19]
	v_mfma_f32_16x16x32_bf16 v[4:7], v[166:169], v[212:215], v[4:7]
	v_mfma_f32_16x16x32_bf16 v[0:3], v[180:183], v[212:215], v[0:3]
	s_barrier
	s_add_i32 s75, s75, 2
	s_add_u32 s20, s20, 0x100
	s_addc_u32 s21, s21, 0
	s_add_u32 s13, s13, 0x100
	s_addc_u32 s74, s74, 0
	s_cmp_gt_u32 s75, 29
	s_cbranch_scc0 .LBB0_155
	s_setprio 0
	s_and_b64 vcc, exec, s[6:7]
	s_cbranch_vccz .LBB0_158
	s_barrier

; #define PG8_STAGE(bufoff, gbase, voff) do { _Pragma("unroll") for (int _i = 0; _i < 2; ++_i) \
;         __builtin_amdgcn_global_load_lds((const unsigned*)((const char*)(gbase) + (voff)[_i]), (LAS unsigned*)(lds + (bufoff) + ldsw + _i * 8192), 16, 0, 0); } while (0)
; #define PG8_LDA(dst, b, h) do { _Pragma("unroll") for (int m = 0; m < 4; ++m) _Pragma("unroll") for (int k = 0; k < 2; ++k) dst[m][k] = *(const LAS bf16x8*)(lds + PG8_SA(b, h) + aoff + m * 2048 + k * 1024); } while (0)
; #define PG8_LDB(dst, b, h) do { _Pragma("unroll") for (int n = 0; n < 2; ++n) _Pragma("unroll") for (int k = 0; k < 2; ++k) dst[n][k] = *(const LAS bf16x8*)(lds + PG8_SB(b, h) + boff + n * 2048 + k * 1024); } while (0)
; #define PG8_MMA(ai, bj, At, Bt) do { __builtin_amdgcn_s_setprio(1); _Pragma("unroll") for (int m = 0; m < 4; ++m) _Pragma("unroll") for (int n = 0; n < 2; ++n) _Pragma("unroll") for (int k = 0; k < 2; ++k) \
;         acc[ai][bj][m][n] = __builtin_amdgcn_mfma_f32_16x16x32_bf16(Bt[n][k], At[m][k], acc[ai][bj][m][n], 0, 0, 0); __builtin_amdgcn_s_setprio(0); } while (0)
; #define PG8_WAIT_V(n) asm volatile("s_waitcnt vmcnt(" #n ")" ::: "memory")
; #define PG8_WAIT_L(n) asm volatile("s_waitcnt lgkmcnt(" #n ")" ::: "memory")
; #define PG8_BAR __builtin_amdgcn_s_barrier()
; #define PG8_SCHED __builtin_amdgcn_sched_barrier(0)
; template <class Sched, class Epi, bool ALIGN_EPI, bool SP2>
; __device__ __forceinline__ void gemm_phase(LAS unsigned char* lds, const int K, const int lda, const int ldb, const Sched& S, const Epi& E) {
;     ...
;         for (int t = 0; t < nt; t += 2) {
;             const bool last = (t == nt - 2);
;             const char* a1 = cA + (size_t)(t + 1) * kstep;
;             const char* a2 = last ? nA : cA + (size_t)(t + 2) * kstep; const char* b2 = last ? nB : cB + (size_t)(t + 2) * kstep;
;             const char* a3 = a2 + kstep; const char* b3 = b2 + kstep;
;             if constexpr (SP2) {
;             PG8_LDB(B0, 0, 0); PG8_LDB(B1, 0, 1); PG8_SCHED; PG8_LDA(At, 0, 0); PG8_STAGE(PG8_SA(1, 1), a1 + hstepA, voffA);
;             PG8_WAIT_V(8); PG8_WAIT_L(0); PG8_BAR; PG8_MMA(0, 0, At, B0); PG8_MMA(0, 1, At, B1); PG8_BAR; PG8_SCHED;
;             PG8_LDA(At, 0, 1); PG8_STAGE(PG8_SB(0, 0), b2, voffB); PG8_STAGE(PG8_SB(0, 1), b2 + hstepB, voffB); PG8_STAGE(PG8_SA(0, 0), a2, voffA);
.Lprio_skip_243:
.LBB0_243:
	ds_read_b128 v[124:127], v169
	ds_read_b128 v[132:135], v169 offset:1024
	ds_read_b128 v[136:139], v169 offset:2048
	ds_read_b128 v[140:143], v169 offset:3072
	ds_read_b128 v[144:147], v170
	ds_read_b128 v[156:159], v170 offset:1024
	ds_read_b128 v[160:163], v170 offset:2048
	ds_read_b128 v[182:185], v170 offset:3072
	s_add_u32 s22, s20, 0x100
	s_addc_u32 s23, s21, 0
	s_cmpk_eq_i32 s91, 0x54
	s_cselect_b32 s27, s17, s23
	s_cselect_b32 s26, s16, s22
	s_cselect_b32 s25, s19, s90
	s_cselect_b32 s24, s18, s89
	s_mov_b32 m0, s78
	v_lshl_add_u64 v[164:165], s[20:21], 0, v[152:153]
	ds_read_b128 v[186:189], v171
	ds_read_b128 v[190:193], v171 offset:1024
	ds_read_b128 v[194:197], v171 offset:2048
	ds_read_b128 v[198:201], v171 offset:3072
	ds_read_b128 v[202:205], v171 offset:4096
	ds_read_b128 v[206:209], v171 offset:5120
	ds_read_b128 v[210:213], v171 offset:6144
	ds_read_b128 v[214:217], v171 offset:7168
	global_load_lds_dwordx4 v[164:165], off
	v_lshl_add_u64 v[164:165], s[20:21], 0, v[154:155]
	s_mov_b32 m0, s79
	s_nop 0
	global_load_lds_dwordx4 v[164:165], off
	s_waitcnt vmcnt(8) lgkmcnt(0)
	s_barrier
	v_mfma_f32_16x16x32_bf16 v[128:131], v[124:127], v[186:189], v[128:131]
	v_mfma_f32_16x16x32_bf16 v[120:123], v[136:139], v[186:189], v[120:123]
	v_mfma_f32_16x16x32_bf16 v[108:111], v[124:127], v[194:197], v[108:111]
	v_mfma_f32_16x16x32_bf16 v[104:107], v[136:139], v[194:197], v[104:107]
	v_mfma_f32_16x16x32_bf16 v[92:95], v[124:127], v[202:205], v[92:95]
	v_mfma_f32_16x16x32_bf16 v[88:91], v[136:139], v[202:205], v[88:91]
	v_mfma_f32_16x16x32_bf16 v[76:79], v[124:127], v[210:213], v[76:79]
	v_mfma_f32_16x16x32_bf16 v[72:75], v[136:139], v[210:213], v[72:75]
	v_mfma_f32_16x16x32_bf16 v[128:131], v[132:135], v[190:193], v[128:131]
	v_mfma_f32_16x16x32_bf16 v[120:123], v[140:143], v[190:193], v[120:123]
	v_mfma_f32_16x16x32_bf16 v[108:111], v[132:135], v[198:201], v[108:111]
	v_mfma_f32_16x16x32_bf16 v[104:107], v[140:143], v[198:201], v[104:107]
	v_mfma_f32_16x16x32_bf16 v[92:95], v[132:135], v[206:209], v[92:95]
	v_mfma_f32_16x16x32_bf16 v[88:91], v[140:143], v[206:209], v[88:91]
	v_mfma_f32_16x16x32_bf16 v[76:79], v[132:135], v[214:217], v[76:79]
	v_mfma_f32_16x16x32_bf16 v[72:75], v[140:143], v[214:217], v[72:75]
	v_mfma_f32_16x16x32_bf16 v[116:119], v[144:147], v[186:189], v[116:119]
	v_mfma_f32_16x16x32_bf16 v[112:115], v[160:163], v[186:189], v[112:115]
	v_mfma_f32_16x16x32_bf16 v[100:103], v[144:147], v[194:197], v[100:103]
	v_mfma_f32_16x16x32_bf16 v[96:99], v[160:163], v[194:197], v[96:99]
	v_mfma_f32_16x16x32_bf16 v[84:87], v[144:147], v[202:205], v[84:87]
	v_mfma_f32_16x16x32_bf16 v[80:83], v[160:163], v[202:205], v[80:83]
	v_mfma_f32_16x16x32_bf16 v[68:71], v[144:147], v[210:213], v[68:71]
	v_mfma_f32_16x16x32_bf16 v[64:67], v[160:163], v[210:213], v[64:67]
	v_mfma_f32_16x16x32_bf16 v[116:119], v[156:159], v[190:193], v[116:119]
	v_mfma_f32_16x16x32_bf16 v[112:115], v[182:185], v[190:193], v[112:115]
	v_mfma_f32_16x16x32_bf16 v[100:103], v[156:159], v[198:201], v[100:103]
	v_mfma_f32_16x16x32_bf16 v[96:99], v[182:185], v[198:201], v[96:99]
	v_mfma_f32_16x16x32_bf16 v[84:87], v[156:159], v[206:209], v[84:87]
	v_mfma_f32_16x16x32_bf16 v[80:83], v[182:185], v[206:209], v[80:83]
	v_mfma_f32_16x16x32_bf16 v[68:71], v[156:159], v[214:217], v[68:71]
	v_mfma_f32_16x16x32_bf16 v[64:67], v[182:185], v[214:217], v[64:67]
	s_barrier
	s_mov_b32 m0, s84
	v_lshl_add_u64 v[164:165], s[24:25], 0, v[148:149]
	ds_read_b128 v[186:189], v171 offset:16384
	ds_read_b128 v[190:193], v171 offset:17408
	ds_read_b128 v[194:197], v171 offset:18432
	ds_read_b128 v[198:201], v171 offset:19456
	ds_read_b128 v[202:205], v171 offset:20480
	ds_read_b128 v[206:209], v171 offset:21504
	ds_read_b128 v[210:213], v171 offset:22528
	ds_read_b128 v[214:217], v171 offset:23552
	global_load_lds_dwordx4 v[164:165], off
	s_add_i32 m0, s84, 0x2000
	s_add_u32 s20, s24, 0x160000
	v_lshl_add_u64 v[174:175], s[24:25], 0, v[150:151]
	s_addc_u32 s21, s25, 0
	s_add_i32 s96, s53, s13
	global_load_lds_dwordx4 v[174:175], off
	v_lshl_add_u64 v[218:219], s[20:21], 0, v[148:149]
	s_mov_b32 m0, s96
	v_lshl_add_u64 v[220:221], s[26:27], 0, v[150:151]
	global_load_lds_dwordx4 v[218:219], off
	v_lshl_add_u64 v[218:219], s[20:21], 0, v[150:151]
	s_add_i32 m0, s96, 0x2000
	s_nop 0
	global_load_lds_dwordx4 v[218:219], off
	v_lshl_add_u64 v[218:219], s[26:27], 0, v[148:149]
	s_mov_b32 m0, s28
	s_nop 0
	global_load_lds_dwordx4 v[218:219], off
	s_mov_b32 m0, s29
	s_nop 0
	global_load_lds_dwordx4 v[220:221], off
	s_waitcnt vmcnt(8) lgkmcnt(0)
	s_barrier
; #define PG8_STAGE(bufoff, gbase, voff) do { _Pragma("unroll") for (int _i = 0; _i < 2; ++_i) \
;         __builtin_amdgcn_global_load_lds((const unsigned*)((const char*)(gbase) + (voff)[_i]), (LAS unsigned*)(lds + (bufoff) + ldsw + _i * 8192), 16, 0, 0); } while (0)
; #define PG8_LDA(dst, b, h) do { _Pragma("unroll") for (int m = 0; m < 4; ++m) _Pragma("unroll") for (int k = 0; k < 2; ++k) dst[m][k] = *(const LAS bf16x8*)(lds + PG8_SA(b, h) + aoff + m * 2048 + k * 1024); } while (0)
; #define PG8_LDB(dst, b, h) do { _Pragma("unroll") for (int n = 0; n < 2; ++n) _Pragma("unroll") for (int k = 0; k < 2; ++k) dst[n][k] = *(const LAS bf16x8*)(lds + PG8_SB(b, h) + boff + n * 2048 + k * 1024); } while (0)
; #define PG8_MMA(ai, bj, At, Bt) do { __builtin_amdgcn_s_setprio(1); _Pragma("unroll") for (int m = 0; m < 4; ++m) _Pragma("unroll") for (int n = 0; n < 2; ++n) _Pragma("unroll") for (int k = 0; k < 2; ++k) \
;         acc[ai][bj][m][n] = __builtin_amdgcn_mfma_f32_16x16x32_bf16(Bt[n][k], At[m][k], acc[ai][bj][m][n], 0, 0, 0); __builtin_amdgcn_s_setprio(0); } while (0)
; #define PG8_WAIT_V(n) asm volatile("s_waitcnt vmcnt(" #n ")" ::: "memory")
; #define PG8_WAIT_L(n) asm volatile("s_waitcnt lgkmcnt(" #n ")" ::: "memory")
; #define PG8_BAR __builtin_amdgcn_s_barrier()
; #define PG8_SCHED __builtin_amdgcn_sched_barrier(0)
; template <class Sched, class Epi, bool ALIGN_EPI, bool SP2>
; __device__ __forceinline__ void gemm_phase(LAS unsigned char* lds, const int K, const int lda, const int ldb, const Sched& S, const Epi& E) {
;     ...
;             PG8_WAIT_V(8); PG8_WAIT_L(0); PG8_BAR; PG8_MMA(1, 0, At, B0); PG8_MMA(1, 1, At, B1); PG8_BAR; PG8_SCHED;
;             PG8_LDB(B0, 1, 0); PG8_LDB(B1, 1, 1); PG8_SCHED; PG8_LDA(At, 1, 0); PG8_STAGE(PG8_SA(0, 1), a2 + hstepA, voffA);
;             PG8_WAIT_V(8); PG8_WAIT_L(0); PG8_BAR; PG8_MMA(0, 0, At, B0); PG8_MMA(0, 1, At, B1); PG8_BAR; PG8_SCHED;
	v_mfma_f32_16x16x32_bf16 v[60:63], v[124:127], v[186:189], v[60:63]
	v_mfma_f32_16x16x32_bf16 v[56:59], v[136:139], v[186:189], v[56:59]
	v_mfma_f32_16x16x32_bf16 v[44:47], v[124:127], v[194:197], v[44:47]
	v_mfma_f32_16x16x32_bf16 v[40:43], v[136:139], v[194:197], v[40:43]
	v_mfma_f32_16x16x32_bf16 v[28:31], v[124:127], v[202:205], v[28:31]
	v_mfma_f32_16x16x32_bf16 v[24:27], v[136:139], v[202:205], v[24:27]
	v_mfma_f32_16x16x32_bf16 v[12:15], v[124:127], v[210:213], v[12:15]
	v_mfma_f32_16x16x32_bf16 v[8:11], v[136:139], v[210:213], v[8:11]
	v_mfma_f32_16x16x32_bf16 v[60:63], v[132:135], v[190:193], v[60:63]
	v_mfma_f32_16x16x32_bf16 v[56:59], v[140:143], v[190:193], v[56:59]
	v_mfma_f32_16x16x32_bf16 v[44:47], v[132:135], v[198:201], v[44:47]
	v_mfma_f32_16x16x32_bf16 v[40:43], v[140:143], v[198:201], v[40:43]
	v_mfma_f32_16x16x32_bf16 v[28:31], v[132:135], v[206:209], v[28:31]
	v_mfma_f32_16x16x32_bf16 v[24:27], v[140:143], v[206:209], v[24:27]
	v_mfma_f32_16x16x32_bf16 v[12:15], v[132:135], v[214:217], v[12:15]
	v_mfma_f32_16x16x32_bf16 v[8:11], v[140:143], v[214:217], v[8:11]
	v_mfma_f32_16x16x32_bf16 v[52:55], v[144:147], v[186:189], v[52:55]
	v_mfma_f32_16x16x32_bf16 v[48:51], v[160:163], v[186:189], v[48:51]
	v_mfma_f32_16x16x32_bf16 v[36:39], v[144:147], v[194:197], v[36:39]
	v_mfma_f32_16x16x32_bf16 v[32:35], v[160:163], v[194:197], v[32:35]
	v_mfma_f32_16x16x32_bf16 v[20:23], v[144:147], v[202:205], v[20:23]
	v_mfma_f32_16x16x32_bf16 v[16:19], v[160:163], v[202:205], v[16:19]
	v_mfma_f32_16x16x32_bf16 v[4:7], v[144:147], v[210:213], v[4:7]
	v_mfma_f32_16x16x32_bf16 v[0:3], v[160:163], v[210:213], v[0:3]
	v_mfma_f32_16x16x32_bf16 v[52:55], v[156:159], v[190:193], v[52:55]
	v_mfma_f32_16x16x32_bf16 v[48:51], v[182:185], v[190:193], v[48:51]
	v_mfma_f32_16x16x32_bf16 v[36:39], v[156:159], v[198:201], v[36:39]
	v_mfma_f32_16x16x32_bf16 v[32:35], v[182:185], v[198:201], v[32:35]
	v_mfma_f32_16x16x32_bf16 v[20:23], v[156:159], v[206:209], v[20:23]
	v_mfma_f32_16x16x32_bf16 v[16:19], v[182:185], v[206:209], v[16:19]
	v_mfma_f32_16x16x32_bf16 v[4:7], v[156:159], v[214:217], v[4:7]
	v_mfma_f32_16x16x32_bf16 v[0:3], v[182:185], v[214:217], v[0:3]
	s_barrier
	s_add_i32 s96, 0, 0x18000
	s_add_i32 s97, 0, 0x1c000
	v_add_u32_e32 v140, s96, v167
	v_add_u32_e32 v173, s97, v167
	ds_read_b128 v[124:127], v140
	ds_read_b128 v[132:135], v140 offset:1024
	ds_read_b128 v[136:139], v140 offset:2048
	ds_read_b128 v[140:143], v140 offset:3072
	ds_read_b128 v[144:147], v173
	ds_read_b128 v[156:159], v173 offset:1024
	ds_read_b128 v[160:163], v173 offset:2048
	ds_read_b128 v[182:185], v173 offset:3072
	s_add_u32 s20, s26, 0x160000
	s_addc_u32 s21, s27, 0
	s_mov_b32 m0, s33
	v_lshl_add_u64 v[222:223], s[20:21], 0, v[148:149]
	ds_read_b128 v[186:189], v171 offset:32768
	ds_read_b128 v[190:193], v171 offset:33792
	ds_read_b128 v[194:197], v171 offset:34816
	ds_read_b128 v[198:201], v171 offset:35840
	ds_read_b128 v[202:205], v171 offset:36864
	ds_read_b128 v[206:209], v171 offset:37888
	ds_read_b128 v[210:213], v171 offset:38912
	ds_read_b128 v[214:217], v171 offset:39936
	global_load_lds_dwordx4 v[222:223], off
	v_lshl_add_u64 v[222:223], s[20:21], 0, v[150:151]
	s_mov_b32 m0, s35
	s_nop 0
	global_load_lds_dwordx4 v[222:223], off
	s_waitcnt vmcnt(8) lgkmcnt(0)
	s_barrier
	v_mfma_f32_16x16x32_bf16 v[128:131], v[124:127], v[186:189], v[128:131]
	v_mfma_f32_16x16x32_bf16 v[120:123], v[136:139], v[186:189], v[120:123]
	v_mfma_f32_16x16x32_bf16 v[108:111], v[124:127], v[194:197], v[108:111]
	v_mfma_f32_16x16x32_bf16 v[104:107], v[136:139], v[194:197], v[104:107]
	v_mfma_f32_16x16x32_bf16 v[92:95], v[124:127], v[202:205], v[92:95]
	v_mfma_f32_16x16x32_bf16 v[88:91], v[136:139], v[202:205], v[88:91]
	v_mfma_f32_16x16x32_bf16 v[76:79], v[124:127], v[210:213], v[76:79]
	v_mfma_f32_16x16x32_bf16 v[72:75], v[136:139], v[210:213], v[72:75]
	v_mfma_f32_16x16x32_bf16 v[128:131], v[132:135], v[190:193], v[128:131]
	v_mfma_f32_16x16x32_bf16 v[120:123], v[140:143], v[190:193], v[120:123]
	v_mfma_f32_16x16x32_bf16 v[108:111], v[132:135], v[198:201], v[108:111]
	v_mfma_f32_16x16x32_bf16 v[104:107], v[140:143], v[198:201], v[104:107]
	v_mfma_f32_16x16x32_bf16 v[92:95], v[132:135], v[206:209], v[92:95]
	v_mfma_f32_16x16x32_bf16 v[88:91], v[140:143], v[206:209], v[88:91]
	v_mfma_f32_16x16x32_bf16 v[76:79], v[132:135], v[214:217], v[76:79]
	v_mfma_f32_16x16x32_bf16 v[72:75], v[140:143], v[214:217], v[72:75]
	v_mfma_f32_16x16x32_bf16 v[116:119], v[144:147], v[186:189], v[116:119]
	v_mfma_f32_16x16x32_bf16 v[112:115], v[160:163], v[186:189], v[112:115]
	v_mfma_f32_16x16x32_bf16 v[100:103], v[144:147], v[194:197], v[100:103]
	v_mfma_f32_16x16x32_bf16 v[96:99], v[160:163], v[194:197], v[96:99]
	v_mfma_f32_16x16x32_bf16 v[84:87], v[144:147], v[202:205], v[84:87]
	v_mfma_f32_16x16x32_bf16 v[80:83], v[160:163], v[202:205], v[80:83]
	v_mfma_f32_16x16x32_bf16 v[68:71], v[144:147], v[210:213], v[68:71]
	v_mfma_f32_16x16x32_bf16 v[64:67], v[160:163], v[210:213], v[64:67]
	v_mfma_f32_16x16x32_bf16 v[116:119], v[156:159], v[190:193], v[116:119]
	v_mfma_f32_16x16x32_bf16 v[112:115], v[182:185], v[190:193], v[112:115]
	v_mfma_f32_16x16x32_bf16 v[100:103], v[156:159], v[198:201], v[100:103]
	v_mfma_f32_16x16x32_bf16 v[96:99], v[182:185], v[198:201], v[96:99]
	v_mfma_f32_16x16x32_bf16 v[84:87], v[156:159], v[206:209], v[84:87]
	v_mfma_f32_16x16x32_bf16 v[80:83], v[182:185], v[206:209], v[80:83]
	v_mfma_f32_16x16x32_bf16 v[68:71], v[156:159], v[214:217], v[68:71]
	v_mfma_f32_16x16x32_bf16 v[64:67], v[182:185], v[214:217], v[64:67]
	s_barrier
; #define PG8_STAGE(bufoff, gbase, voff) do { _Pragma("unroll") for (int _i = 0; _i < 2; ++_i) \
;         __builtin_amdgcn_global_load_lds((const unsigned*)((const char*)(gbase) + (voff)[_i]), (LAS unsigned*)(lds + (bufoff) + ldsw + _i * 8192), 16, 0, 0); } while (0)
; #define PG8_LDA(dst, b, h) do { _Pragma("unroll") for (int m = 0; m < 4; ++m) _Pragma("unroll") for (int k = 0; k < 2; ++k) dst[m][k] = *(const LAS bf16x8*)(lds + PG8_SA(b, h) + aoff + m * 2048 + k * 1024); } while (0)
; #define PG8_MMA(ai, bj, At, Bt) do { __builtin_amdgcn_s_setprio(1); _Pragma("unroll") for (int m = 0; m < 4; ++m) _Pragma("unroll") for (int n = 0; n < 2; ++n) _Pragma("unroll") for (int k = 0; k < 2; ++k) \
;         acc[ai][bj][m][n] = __builtin_amdgcn_mfma_f32_16x16x32_bf16(Bt[n][k], At[m][k], acc[ai][bj][m][n], 0, 0, 0); __builtin_amdgcn_s_setprio(0); } while (0)
; #define PG8_WAIT_V(n) asm volatile("s_waitcnt vmcnt(" #n ")" ::: "memory")
; #define PG8_WAIT_L(n) asm volatile("s_waitcnt lgkmcnt(" #n ")" ::: "memory")
; #define PG8_BAR __builtin_amdgcn_s_barrier()
; #define PG8_SCHED __builtin_amdgcn_sched_barrier(0)
; template <class Sched, class Epi, bool ALIGN_EPI, bool SP2>
; __device__ __forceinline__ void gemm_phase(LAS unsigned char* lds, const int K, const int lda, const int ldb, const Sched& S, const Epi& E) {
;     ...
;             PG8_LDA(At, 1, 1); PG8_STAGE(PG8_SB(1, 0), b3, voffB); PG8_STAGE(PG8_SB(1, 1), b3 + hstepB, voffB); PG8_STAGE(PG8_SA(1, 0), a3, voffA);
;             PG8_WAIT_V(8); PG8_WAIT_L(0); PG8_BAR; PG8_MMA(1, 0, At, B0); PG8_MMA(1, 1, At, B1); PG8_BAR; PG8_SCHED;
	s_add_i32 s20, s96, s13
	v_lshl_add_u64 v[164:165], v[164:165], 0, s[6:7]
	s_mov_b32 m0, s20
	ds_read_b128 v[186:189], v171 offset:49152
	ds_read_b128 v[190:193], v171 offset:50176
	ds_read_b128 v[194:197], v171 offset:51200
	ds_read_b128 v[198:201], v171 offset:52224
	ds_read_b128 v[202:205], v171 offset:53248
	ds_read_b128 v[206:209], v171 offset:54272
	ds_read_b128 v[210:213], v171 offset:55296
	ds_read_b128 v[214:217], v171 offset:56320
	global_load_lds_dwordx4 v[164:165], off
	s_add_i32 m0, s20, 0x2000
	s_add_u32 s20, s24, 0x160080
	v_lshl_add_u64 v[164:165], v[174:175], 0, s[6:7]
	s_addc_u32 s21, s25, 0
	s_add_i32 s24, s97, s13
	global_load_lds_dwordx4 v[164:165], off
	v_lshl_add_u64 v[164:165], s[20:21], 0, v[148:149]
	s_mov_b32 m0, s24
	s_nop 0
	global_load_lds_dwordx4 v[164:165], off
	v_lshl_add_u64 v[164:165], s[20:21], 0, v[150:151]
	s_add_i32 m0, s24, 0x2000
	s_nop 0
	global_load_lds_dwordx4 v[164:165], off
	v_lshl_add_u64 v[164:165], v[218:219], 0, s[6:7]
	s_mov_b32 m0, s51
	s_nop 0
	global_load_lds_dwordx4 v[164:165], off
	v_lshl_add_u64 v[164:165], v[220:221], 0, s[6:7]
	s_mov_b32 m0, s52
	s_nop 0
	global_load_lds_dwordx4 v[164:165], off
	s_waitcnt vmcnt(8) lgkmcnt(0)
	s_barrier
	v_mfma_f32_16x16x32_bf16 v[60:63], v[124:127], v[186:189], v[60:63]
	v_mfma_f32_16x16x32_bf16 v[56:59], v[136:139], v[186:189], v[56:59]
	v_mfma_f32_16x16x32_bf16 v[44:47], v[124:127], v[194:197], v[44:47]
	v_mfma_f32_16x16x32_bf16 v[40:43], v[136:139], v[194:197], v[40:43]
	v_mfma_f32_16x16x32_bf16 v[28:31], v[124:127], v[202:205], v[28:31]
	v_mfma_f32_16x16x32_bf16 v[24:27], v[136:139], v[202:205], v[24:27]
	v_mfma_f32_16x16x32_bf16 v[12:15], v[124:127], v[210:213], v[12:15]
	v_mfma_f32_16x16x32_bf16 v[8:11], v[136:139], v[210:213], v[8:11]
	v_mfma_f32_16x16x32_bf16 v[60:63], v[132:135], v[190:193], v[60:63]
	v_mfma_f32_16x16x32_bf16 v[56:59], v[140:143], v[190:193], v[56:59]
	v_mfma_f32_16x16x32_bf16 v[44:47], v[132:135], v[198:201], v[44:47]
	v_mfma_f32_16x16x32_bf16 v[40:43], v[140:143], v[198:201], v[40:43]
	v_mfma_f32_16x16x32_bf16 v[28:31], v[132:135], v[206:209], v[28:31]
	v_mfma_f32_16x16x32_bf16 v[24:27], v[140:143], v[206:209], v[24:27]
	v_mfma_f32_16x16x32_bf16 v[12:15], v[132:135], v[214:217], v[12:15]
	v_mfma_f32_16x16x32_bf16 v[8:11], v[140:143], v[214:217], v[8:11]
	v_mfma_f32_16x16x32_bf16 v[52:55], v[144:147], v[186:189], v[52:55]
	v_mfma_f32_16x16x32_bf16 v[48:51], v[160:163], v[186:189], v[48:51]
	v_mfma_f32_16x16x32_bf16 v[36:39], v[144:147], v[194:197], v[36:39]
	v_mfma_f32_16x16x32_bf16 v[32:35], v[160:163], v[194:197], v[32:35]
	v_mfma_f32_16x16x32_bf16 v[20:23], v[144:147], v[202:205], v[20:23]
	v_mfma_f32_16x16x32_bf16 v[16:19], v[160:163], v[202:205], v[16:19]
	v_mfma_f32_16x16x32_bf16 v[4:7], v[144:147], v[210:213], v[4:7]
	v_mfma_f32_16x16x32_bf16 v[0:3], v[160:163], v[210:213], v[0:3]
	v_mfma_f32_16x16x32_bf16 v[52:55], v[156:159], v[190:193], v[52:55]
	v_mfma_f32_16x16x32_bf16 v[48:51], v[182:185], v[190:193], v[48:51]
	v_mfma_f32_16x16x32_bf16 v[36:39], v[156:159], v[198:201], v[36:39]
	v_mfma_f32_16x16x32_bf16 v[32:35], v[182:185], v[198:201], v[32:35]
	v_mfma_f32_16x16x32_bf16 v[20:23], v[156:159], v[206:209], v[20:23]
	v_mfma_f32_16x16x32_bf16 v[16:19], v[182:185], v[206:209], v[16:19]
	v_mfma_f32_16x16x32_bf16 v[4:7], v[156:159], v[214:217], v[4:7]
	v_mfma_f32_16x16x32_bf16 v[0:3], v[182:185], v[214:217], v[0:3]
	s_barrier
	s_add_i32 s91, s91, 2
	s_add_u32 s89, s89, 0x100
	s_addc_u32 s90, s90, 0
	s_cmpk_gt_u32 s91, 0x55
	s_mov_b64 s[20:21], s[22:23]
	s_cbranch_scc0 .LBB0_243
	s_setprio 0
	s_and_b64 vcc, exec, s[10:11]
	s_cbranch_vccz .LBB0_246
	s_barrier

; #define PG8_STAGE(bufoff, gbase, voff) do { _Pragma("unroll") for (int _i = 0; _i < 2; ++_i) \
;         __builtin_amdgcn_global_load_lds((const unsigned*)((const char*)(gbase) + (voff)[_i]), (LAS unsigned*)(lds + (bufoff) + ldsw + _i * 8192), 16, 0, 0); } while (0)
; #define PG8_LDA(dst, b, h) do { _Pragma("unroll") for (int m = 0; m < 4; ++m) _Pragma("unroll") for (int k = 0; k < 2; ++k) dst[m][k] = *(const LAS bf16x8*)(lds + PG8_SA(b, h) + aoff + m * 2048 + k * 1024); } while (0)
; #define PG8_LDB(dst, b, h) do { _Pragma("unroll") for (int n = 0; n < 2; ++n) _Pragma("unroll") for (int k = 0; k < 2; ++k) dst[n][k] = *(const LAS bf16x8*)(lds + PG8_SB(b, h) + boff + n * 2048 + k * 1024); } while (0)
; #define PG8_MMA(ai, bj, At, Bt) do { __builtin_amdgcn_s_setprio(1); _Pragma("unroll") for (int m = 0; m < 4; ++m) _Pragma("unroll") for (int n = 0; n < 2; ++n) _Pragma("unroll") for (int k = 0; k < 2; ++k) \
;         acc[ai][bj][m][n] = __builtin_amdgcn_mfma_f32_16x16x32_bf16(Bt[n][k], At[m][k], acc[ai][bj][m][n], 0, 0, 0); __builtin_amdgcn_s_setprio(0); } while (0)
; #define PG8_WAIT_V(n) asm volatile("s_waitcnt vmcnt(" #n ")" ::: "memory")
; #define PG8_WAIT_L(n) asm volatile("s_waitcnt lgkmcnt(" #n ")" ::: "memory")
; #define PG8_BAR __builtin_amdgcn_s_barrier()
; #define PG8_SCHED __builtin_amdgcn_sched_barrier(0)
; template <class Sched, class Epi, bool ALIGN_EPI, bool SP2>
; __device__ __forceinline__ void gemm_phase(LAS unsigned char* lds, const int K, const int lda, const int ldb, const Sched& S, const Epi& E) {
;     ...
;         for (int t = 0; t < nt; t += 2) {
;             const bool last = (t == nt - 2);
;             const char* a1 = cA + (size_t)(t + 1) * kstep;
;             const char* a2 = last ? nA : cA + (size_t)(t + 2) * kstep; const char* b2 = last ? nB : cB + (size_t)(t + 2) * kstep;
;             const char* a3 = a2 + kstep; const char* b3 = b2 + kstep;
;             if constexpr (SP2) {
;             PG8_LDB(B0, 0, 0); PG8_LDB(B1, 0, 1); PG8_SCHED; PG8_LDA(At, 0, 0); PG8_STAGE(PG8_SA(1, 1), a1 + hstepA, voffA);
;             PG8_WAIT_V(8); PG8_WAIT_L(0); PG8_BAR; PG8_MMA(0, 0, At, B0); PG8_MMA(0, 1, At, B1); PG8_BAR; PG8_SCHED;
;             PG8_LDA(At, 0, 1); PG8_STAGE(PG8_SB(0, 0), b2, voffB); PG8_STAGE(PG8_SB(0, 1), b2 + hstepB, voffB); PG8_STAGE(PG8_SA(0, 0), a2, voffA);
.Lprio_skip_353:
.LBB0_353:
	s_waitcnt lgkmcnt(0)
	ds_read_b128 v[32:35], v211
	ds_read_b128 v[36:39], v211 offset:1024
	ds_read_b128 v[48:51], v211 offset:2048
	ds_read_b128 v[52:55], v211 offset:3072
	ds_read_b128 v[56:59], v212
	ds_read_b128 v[60:63], v212 offset:1024
	ds_read_b128 v[64:67], v212 offset:2048
	ds_read_b128 v[68:71], v212 offset:3072
	s_add_u32 s8, s26, 0xfff80080
	s_addc_u32 s9, s27, -1
	s_cmp_eq_u32 s7, 28
	s_cselect_b32 s37, s1, s9
	s_cselect_b32 s36, s4, s8
	s_cselect_b32 s29, s21, s6
	s_cselect_b32 s28, vcc_lo, vcc_hi
	v_lshl_add_u64 v[208:209], s[26:27], 0, v[192:193]
	s_add_i32 m0, s89, 0xc000
	ds_read_b128 v[76:79], v213
	ds_read_b128 v[80:83], v213 offset:1024
	ds_read_b128 v[88:91], v213 offset:2048
	ds_read_b128 v[92:95], v213 offset:3072
	ds_read_b128 v[196:199], v213 offset:4096
	ds_read_b128 v[200:203], v213 offset:5120
	ds_read_b128 v[204:207], v213 offset:6144
	ds_read_b128 v[216:219], v213 offset:7168
	global_load_lds_dwordx4 v[208:209], off
	v_lshl_add_u64 v[208:209], s[26:27], 0, v[194:195]
	s_add_i32 m0, s89, 0xe000
	s_nop 0
	global_load_lds_dwordx4 v[208:209], off
	s_waitcnt vmcnt(8) lgkmcnt(0)
	s_barrier
	v_mfma_f32_16x16x32_bf16 v[172:175], v[32:35], v[76:79], v[172:175]
	v_mfma_f32_16x16x32_bf16 v[168:171], v[48:51], v[76:79], v[168:171]
	v_mfma_f32_16x16x32_bf16 v[156:159], v[32:35], v[88:91], v[156:159]
	v_mfma_f32_16x16x32_bf16 v[152:155], v[48:51], v[88:91], v[152:155]
	v_mfma_f32_16x16x32_bf16 v[140:143], v[32:35], v[196:199], v[140:143]
	v_mfma_f32_16x16x32_bf16 v[136:139], v[48:51], v[196:199], v[136:139]
	v_mfma_f32_16x16x32_bf16 v[124:127], v[32:35], v[204:207], v[124:127]
	v_mfma_f32_16x16x32_bf16 v[120:123], v[48:51], v[204:207], v[120:123]
	v_mfma_f32_16x16x32_bf16 v[172:175], v[36:39], v[80:83], v[172:175]
	v_mfma_f32_16x16x32_bf16 v[168:171], v[52:55], v[80:83], v[168:171]
	v_mfma_f32_16x16x32_bf16 v[156:159], v[36:39], v[92:95], v[156:159]
	v_mfma_f32_16x16x32_bf16 v[152:155], v[52:55], v[92:95], v[152:155]
	v_mfma_f32_16x16x32_bf16 v[140:143], v[36:39], v[200:203], v[140:143]
	v_mfma_f32_16x16x32_bf16 v[136:139], v[52:55], v[200:203], v[136:139]
	v_mfma_f32_16x16x32_bf16 v[124:127], v[36:39], v[216:219], v[124:127]
	v_mfma_f32_16x16x32_bf16 v[120:123], v[52:55], v[216:219], v[120:123]
	v_mfma_f32_16x16x32_bf16 v[164:167], v[56:59], v[76:79], v[164:167]
	v_mfma_f32_16x16x32_bf16 v[76:79], v[64:67], v[76:79], v[160:163]
	v_mfma_f32_16x16x32_bf16 v[164:167], v[60:63], v[80:83], v[164:167]
	v_mfma_f32_16x16x32_bf16 v[76:79], v[68:71], v[80:83], v[76:79]
	v_mfma_f32_16x16x32_bf16 v[80:83], v[56:59], v[88:91], v[148:151]
	v_mfma_f32_16x16x32_bf16 v[88:91], v[64:67], v[88:91], v[144:147]
	v_mfma_f32_16x16x32_bf16 v[128:131], v[64:67], v[196:199], v[128:131]
	v_mfma_f32_16x16x32_bf16 v[116:119], v[56:59], v[204:207], v[116:119]
	v_mfma_f32_16x16x32_bf16 v[112:115], v[64:67], v[204:207], v[112:115]
	v_mfma_f32_16x16x32_bf16 v[80:83], v[60:63], v[92:95], v[80:83]
	v_mfma_f32_16x16x32_bf16 v[88:91], v[68:71], v[92:95], v[88:91]
	v_mfma_f32_16x16x32_bf16 v[92:95], v[56:59], v[196:199], v[132:135]
	v_mfma_f32_16x16x32_bf16 v[128:131], v[68:71], v[200:203], v[128:131]
	v_mfma_f32_16x16x32_bf16 v[116:119], v[60:63], v[216:219], v[116:119]
	v_mfma_f32_16x16x32_bf16 v[112:115], v[68:71], v[216:219], v[112:115]
	v_mfma_f32_16x16x32_bf16 v[92:95], v[60:63], v[200:203], v[92:95]
	s_barrier
	s_add_i32 s8, s85, s88
	v_lshl_add_u64 v[208:209], s[28:29], 0, v[186:187]
	s_mov_b32 m0, s8
	ds_read_b128 v[132:135], v213 offset:16384
	ds_read_b128 v[144:147], v213 offset:17408
	ds_read_b128 v[148:151], v213 offset:18432
	ds_read_b128 v[160:163], v213 offset:19456
	ds_read_b128 v[196:199], v213 offset:20480
	ds_read_b128 v[200:203], v213 offset:21504
	ds_read_b128 v[204:207], v213 offset:22528
	ds_read_b128 v[216:219], v213 offset:23552
	global_load_lds_dwordx4 v[208:209], off
	s_add_i32 m0, s8, 0x2000
	s_add_u32 s8, s28, 0x80000
	v_lshl_add_u64 v[228:229], s[28:29], 0, v[190:191]
	s_addc_u32 s9, s29, 0
	s_add_i32 s51, s50, s88
	global_load_lds_dwordx4 v[228:229], off
	v_lshl_add_u64 v[220:221], s[8:9], 0, v[186:187]
	s_mov_b32 m0, s51
	v_lshl_add_u64 v[230:231], s[36:37], 0, v[184:185]
	global_load_lds_dwordx4 v[220:221], off
	v_lshl_add_u64 v[220:221], s[8:9], 0, v[190:191]
	s_add_i32 m0, s51, 0x2000
	v_lshl_add_u64 v[232:233], s[36:37], 0, v[188:189]
	global_load_lds_dwordx4 v[220:221], off
	s_mov_b32 m0, s89
	s_nop 0
	global_load_lds_dwordx4 v[230:231], off
	s_mov_b32 m0, s90
	s_nop 0
	global_load_lds_dwordx4 v[232:233], off
	s_waitcnt vmcnt(8) lgkmcnt(0)
	s_barrier
; #define PG8_STAGE(bufoff, gbase, voff) do { _Pragma("unroll") for (int _i = 0; _i < 2; ++_i) \
;         __builtin_amdgcn_global_load_lds((const unsigned*)((const char*)(gbase) + (voff)[_i]), (LAS unsigned*)(lds + (bufoff) + ldsw + _i * 8192), 16, 0, 0); } while (0)
; #define PG8_LDA(dst, b, h) do { _Pragma("unroll") for (int m = 0; m < 4; ++m) _Pragma("unroll") for (int k = 0; k < 2; ++k) dst[m][k] = *(const LAS bf16x8*)(lds + PG8_SA(b, h) + aoff + m * 2048 + k * 1024); } while (0)
; #define PG8_LDB(dst, b, h) do { _Pragma("unroll") for (int n = 0; n < 2; ++n) _Pragma("unroll") for (int k = 0; k < 2; ++k) dst[n][k] = *(const LAS bf16x8*)(lds + PG8_SB(b, h) + boff + n * 2048 + k * 1024); } while (0)
; #define PG8_MMA(ai, bj, At, Bt) do { __builtin_amdgcn_s_setprio(1); _Pragma("unroll") for (int m = 0; m < 4; ++m) _Pragma("unroll") for (int n = 0; n < 2; ++n) _Pragma("unroll") for (int k = 0; k < 2; ++k) \
;         acc[ai][bj][m][n] = __builtin_amdgcn_mfma_f32_16x16x32_bf16(Bt[n][k], At[m][k], acc[ai][bj][m][n], 0, 0, 0); __builtin_amdgcn_s_setprio(0); } while (0)
; #define PG8_WAIT_V(n) asm volatile("s_waitcnt vmcnt(" #n ")" ::: "memory")
; #define PG8_WAIT_L(n) asm volatile("s_waitcnt lgkmcnt(" #n ")" ::: "memory")
; #define PG8_BAR __builtin_amdgcn_s_barrier()
; #define PG8_SCHED __builtin_amdgcn_sched_barrier(0)
; template <class Sched, class Epi, bool ALIGN_EPI, bool SP2>
; __device__ __forceinline__ void gemm_phase(LAS unsigned char* lds, const int K, const int lda, const int ldb, const Sched& S, const Epi& E) {
;     ...
;             PG8_WAIT_V(8); PG8_WAIT_L(0); PG8_BAR; PG8_MMA(1, 0, At, B0); PG8_MMA(1, 1, At, B1); PG8_BAR; PG8_SCHED;
;             PG8_LDB(B0, 1, 0); PG8_LDB(B1, 1, 1); PG8_SCHED; PG8_LDA(At, 1, 0); PG8_STAGE(PG8_SA(0, 1), a2 + hstepA, voffA);
;             PG8_WAIT_V(8); PG8_WAIT_L(0); PG8_BAR; PG8_MMA(0, 0, At, B0); PG8_MMA(0, 1, At, B1); PG8_BAR; PG8_SCHED;
	v_mfma_f32_16x16x32_bf16 v[108:111], v[32:35], v[132:135], v[108:111]
	v_mfma_f32_16x16x32_bf16 v[104:107], v[48:51], v[132:135], v[104:107]
	v_mfma_f32_16x16x32_bf16 v[84:87], v[32:35], v[148:151], v[84:87]
	v_mfma_f32_16x16x32_bf16 v[72:75], v[48:51], v[148:151], v[72:75]
	v_mfma_f32_16x16x32_bf16 v[28:31], v[32:35], v[196:199], v[28:31]
	v_mfma_f32_16x16x32_bf16 v[24:27], v[48:51], v[196:199], v[24:27]
	v_mfma_f32_16x16x32_bf16 v[12:15], v[32:35], v[204:207], v[12:15]
	v_mfma_f32_16x16x32_bf16 v[8:11], v[48:51], v[204:207], v[8:11]
	v_mfma_f32_16x16x32_bf16 v[108:111], v[36:39], v[144:147], v[108:111]
	v_mfma_f32_16x16x32_bf16 v[104:107], v[52:55], v[144:147], v[104:107]
	v_mfma_f32_16x16x32_bf16 v[84:87], v[36:39], v[160:163], v[84:87]
	v_mfma_f32_16x16x32_bf16 v[72:75], v[52:55], v[160:163], v[72:75]
	v_mfma_f32_16x16x32_bf16 v[28:31], v[36:39], v[200:203], v[28:31]
	v_mfma_f32_16x16x32_bf16 v[24:27], v[52:55], v[200:203], v[24:27]
	v_mfma_f32_16x16x32_bf16 v[12:15], v[36:39], v[216:219], v[12:15]
	v_mfma_f32_16x16x32_bf16 v[8:11], v[52:55], v[216:219], v[8:11]
	v_mfma_f32_16x16x32_bf16 v[44:47], v[56:59], v[148:151], v[44:47]
	v_mfma_f32_16x16x32_bf16 v[40:43], v[64:67], v[148:151], v[40:43]
	v_mfma_f32_16x16x32_bf16 v[20:23], v[56:59], v[196:199], v[20:23]
	v_mfma_f32_16x16x32_bf16 v[16:19], v[64:67], v[196:199], v[16:19]
	v_mfma_f32_16x16x32_bf16 v[4:7], v[56:59], v[204:207], v[4:7]
	v_mfma_f32_16x16x32_bf16 v[0:3], v[64:67], v[204:207], v[0:3]
	v_mfma_f32_16x16x32_bf16 v[32:35], v[56:59], v[132:135], v[100:103]
	v_mfma_f32_16x16x32_bf16 v[36:39], v[64:67], v[132:135], v[96:99]
	v_mfma_f32_16x16x32_bf16 v[44:47], v[60:63], v[160:163], v[44:47]
	v_mfma_f32_16x16x32_bf16 v[40:43], v[68:71], v[160:163], v[40:43]
	v_mfma_f32_16x16x32_bf16 v[20:23], v[60:63], v[200:203], v[20:23]
	v_mfma_f32_16x16x32_bf16 v[16:19], v[68:71], v[200:203], v[16:19]
	v_mfma_f32_16x16x32_bf16 v[4:7], v[60:63], v[216:219], v[4:7]
	v_mfma_f32_16x16x32_bf16 v[0:3], v[68:71], v[216:219], v[0:3]
	v_mfma_f32_16x16x32_bf16 v[32:35], v[60:63], v[144:147], v[32:35]
	v_mfma_f32_16x16x32_bf16 v[36:39], v[68:71], v[144:147], v[36:39]
	s_barrier
	s_add_i32 s51, 0, 0x18000
	s_add_i32 s17, 0, 0x1c000
	v_add_u32_e32 v60, s51, v183
	v_add_u32_e32 v96, s17, v183
	ds_read_b128 v[48:51], v60
	ds_read_b128 v[52:55], v60 offset:1024
	ds_read_b128 v[56:59], v60 offset:2048
	ds_read_b128 v[60:63], v60 offset:3072
	ds_read_b128 v[64:67], v96
	ds_read_b128 v[68:71], v96 offset:1024
	ds_read_b128 v[196:199], v96 offset:2048
	ds_read_b128 v[200:203], v96 offset:3072
	s_add_u32 s8, s36, 0x80000
	s_addc_u32 s9, s37, 0
	s_mov_b32 m0, s91
	v_lshl_add_u64 v[148:149], s[8:9], 0, v[184:185]
	ds_read_b128 v[96:99], v213 offset:32768
	ds_read_b128 v[100:103], v213 offset:33792
	ds_read_b128 v[132:135], v213 offset:34816
	ds_read_b128 v[144:147], v213 offset:35840
	ds_read_b128 v[204:207], v213 offset:36864
	ds_read_b128 v[216:219], v213 offset:37888
	ds_read_b128 v[220:223], v213 offset:38912
	ds_read_b128 v[224:227], v213 offset:39936
	global_load_lds_dwordx4 v[148:149], off
	v_lshl_add_u64 v[148:149], s[8:9], 0, v[188:189]
	s_mov_b32 m0, s96
	s_nop 0
	global_load_lds_dwordx4 v[148:149], off
	s_waitcnt vmcnt(8) lgkmcnt(0)
	s_barrier
	v_mfma_f32_16x16x32_bf16 v[148:151], v[48:51], v[96:99], v[172:175]
	v_mfma_f32_16x16x32_bf16 v[172:175], v[52:55], v[100:103], v[148:151]
	v_mfma_f32_16x16x32_bf16 v[148:151], v[56:59], v[96:99], v[168:171]
	v_mfma_f32_16x16x32_bf16 v[168:171], v[60:63], v[100:103], v[148:151]
	v_mfma_f32_16x16x32_bf16 v[148:151], v[48:51], v[132:135], v[156:159]
	v_mfma_f32_16x16x32_bf16 v[156:159], v[52:55], v[144:147], v[148:151]
	v_mfma_f32_16x16x32_bf16 v[148:151], v[56:59], v[132:135], v[152:155]
	v_mfma_f32_16x16x32_bf16 v[140:143], v[48:51], v[204:207], v[140:143]
	v_mfma_f32_16x16x32_bf16 v[136:139], v[56:59], v[204:207], v[136:139]
	v_mfma_f32_16x16x32_bf16 v[124:127], v[48:51], v[220:223], v[124:127]
	v_mfma_f32_16x16x32_bf16 v[120:123], v[56:59], v[220:223], v[120:123]
	v_mfma_f32_16x16x32_bf16 v[152:155], v[60:63], v[144:147], v[148:151]
	v_mfma_f32_16x16x32_bf16 v[140:143], v[52:55], v[216:219], v[140:143]
	v_mfma_f32_16x16x32_bf16 v[136:139], v[60:63], v[216:219], v[136:139]
	v_mfma_f32_16x16x32_bf16 v[124:127], v[52:55], v[224:227], v[124:127]
	v_mfma_f32_16x16x32_bf16 v[120:123], v[60:63], v[224:227], v[120:123]
	v_mfma_f32_16x16x32_bf16 v[76:79], v[196:199], v[96:99], v[76:79]
	v_mfma_f32_16x16x32_bf16 v[148:151], v[64:67], v[96:99], v[164:167]
	v_mfma_f32_16x16x32_bf16 v[160:163], v[200:203], v[100:103], v[76:79]
	v_mfma_f32_16x16x32_bf16 v[76:79], v[64:67], v[132:135], v[80:83]
	v_mfma_f32_16x16x32_bf16 v[164:167], v[68:71], v[100:103], v[148:151]
	v_mfma_f32_16x16x32_bf16 v[148:151], v[68:71], v[144:147], v[76:79]
	v_mfma_f32_16x16x32_bf16 v[76:79], v[196:199], v[132:135], v[88:91]
	v_mfma_f32_16x16x32_bf16 v[144:147], v[200:203], v[144:147], v[76:79]
	v_mfma_f32_16x16x32_bf16 v[76:79], v[64:67], v[204:207], v[92:95]
	v_mfma_f32_16x16x32_bf16 v[132:135], v[68:71], v[216:219], v[76:79]
	v_mfma_f32_16x16x32_bf16 v[76:79], v[196:199], v[204:207], v[128:131]
	v_mfma_f32_16x16x32_bf16 v[128:131], v[200:203], v[216:219], v[76:79]
	v_mfma_f32_16x16x32_bf16 v[76:79], v[64:67], v[220:223], v[116:119]
	v_mfma_f32_16x16x32_bf16 v[116:119], v[68:71], v[224:227], v[76:79]
	v_mfma_f32_16x16x32_bf16 v[76:79], v[196:199], v[220:223], v[112:115]
	v_mfma_f32_16x16x32_bf16 v[112:115], v[200:203], v[224:227], v[76:79]
	s_barrier
; #define PG8_STAGE(bufoff, gbase, voff) do { _Pragma("unroll") for (int _i = 0; _i < 2; ++_i) \
;         __builtin_amdgcn_global_load_lds((const unsigned*)((const char*)(gbase) + (voff)[_i]), (LAS unsigned*)(lds + (bufoff) + ldsw + _i * 8192), 16, 0, 0); } while (0)
; #define PG8_LDA(dst, b, h) do { _Pragma("unroll") for (int m = 0; m < 4; ++m) _Pragma("unroll") for (int k = 0; k < 2; ++k) dst[m][k] = *(const LAS bf16x8*)(lds + PG8_SA(b, h) + aoff + m * 2048 + k * 1024); } while (0)
; #define PG8_MMA(ai, bj, At, Bt) do { __builtin_amdgcn_s_setprio(1); _Pragma("unroll") for (int m = 0; m < 4; ++m) _Pragma("unroll") for (int n = 0; n < 2; ++n) _Pragma("unroll") for (int k = 0; k < 2; ++k) \
;         acc[ai][bj][m][n] = __builtin_amdgcn_mfma_f32_16x16x32_bf16(Bt[n][k], At[m][k], acc[ai][bj][m][n], 0, 0, 0); __builtin_amdgcn_s_setprio(0); } while (0)
; #define PG8_WAIT_V(n) asm volatile("s_waitcnt vmcnt(" #n ")" ::: "memory")
; #define PG8_WAIT_L(n) asm volatile("s_waitcnt lgkmcnt(" #n ")" ::: "memory")
; #define PG8_BAR __builtin_amdgcn_s_barrier()
; #define PG8_SCHED __builtin_amdgcn_sched_barrier(0)
; template <class Sched, class Epi, bool ALIGN_EPI, bool SP2>
; __device__ __forceinline__ void gemm_phase(LAS unsigned char* lds, const int K, const int lda, const int ldb, const Sched& S, const Epi& E) {
;     ...
;             PG8_LDA(At, 1, 1); PG8_STAGE(PG8_SB(1, 0), b3, voffB); PG8_STAGE(PG8_SB(1, 1), b3 + hstepB, voffB); PG8_STAGE(PG8_SA(1, 0), a3, voffA);
;             PG8_WAIT_V(8); PG8_WAIT_L(0); PG8_BAR; PG8_MMA(1, 0, At, B0); PG8_MMA(1, 1, At, B1); PG8_BAR; PG8_SCHED;
	s_add_i32 s8, s51, s88
	v_lshl_add_u64 v[96:97], v[208:209], 0, s[10:11]
	s_mov_b32 m0, s8
	s_nop 1
	ds_read_b128 v[76:79], v213 offset:49152
	ds_read_b128 v[80:83], v213 offset:50176
	ds_read_b128 v[88:91], v213 offset:51200
	ds_read_b128 v[92:95], v213 offset:52224
	ds_read_b128 v[204:207], v213 offset:53248
	ds_read_b128 v[216:219], v213 offset:54272
	ds_read_b128 v[220:223], v213 offset:55296
	ds_read_b128 v[224:227], v213 offset:56320
	global_load_lds_dwordx4 v[96:97], off
	s_add_i32 m0, s8, 0x2000
	s_add_u32 s8, s28, 0x80080
	v_lshl_add_u64 v[96:97], v[228:229], 0, s[10:11]
	s_addc_u32 s9, s29, 0
	s_add_i32 s17, s17, s88
	global_load_lds_dwordx4 v[96:97], off
	v_lshl_add_u64 v[96:97], s[8:9], 0, v[186:187]
	s_mov_b32 m0, s17
	s_nop 0
	global_load_lds_dwordx4 v[96:97], off
	v_lshl_add_u64 v[96:97], s[8:9], 0, v[190:191]
	s_add_i32 m0, s17, 0x2000
	s_nop 0
	global_load_lds_dwordx4 v[96:97], off
	v_lshl_add_u64 v[96:97], v[230:231], 0, s[10:11]
	s_mov_b32 m0, s97
	s_nop 0
	global_load_lds_dwordx4 v[96:97], off
	v_lshl_add_u64 v[96:97], v[232:233], 0, s[10:11]
	s_mov_b32 m0, s84
	s_nop 0
	global_load_lds_dwordx4 v[96:97], off
	s_waitcnt vmcnt(8) lgkmcnt(0)
	s_barrier
	v_mfma_f32_16x16x32_bf16 v[96:99], v[48:51], v[76:79], v[108:111]
	v_mfma_f32_16x16x32_bf16 v[108:111], v[52:55], v[80:83], v[96:99]
	v_mfma_f32_16x16x32_bf16 v[96:99], v[56:59], v[76:79], v[104:107]
	v_mfma_f32_16x16x32_bf16 v[84:87], v[48:51], v[88:91], v[84:87]
	v_mfma_f32_16x16x32_bf16 v[72:75], v[56:59], v[88:91], v[72:75]
	v_mfma_f32_16x16x32_bf16 v[28:31], v[48:51], v[204:207], v[28:31]
	v_mfma_f32_16x16x32_bf16 v[24:27], v[56:59], v[204:207], v[24:27]
	v_mfma_f32_16x16x32_bf16 v[12:15], v[48:51], v[220:223], v[12:15]
	v_mfma_f32_16x16x32_bf16 v[8:11], v[56:59], v[220:223], v[8:11]
	v_mfma_f32_16x16x32_bf16 v[104:107], v[60:63], v[80:83], v[96:99]
	v_mfma_f32_16x16x32_bf16 v[84:87], v[52:55], v[92:95], v[84:87]
	v_mfma_f32_16x16x32_bf16 v[72:75], v[60:63], v[92:95], v[72:75]
	v_mfma_f32_16x16x32_bf16 v[28:31], v[52:55], v[216:219], v[28:31]
	v_mfma_f32_16x16x32_bf16 v[24:27], v[60:63], v[216:219], v[24:27]
	v_mfma_f32_16x16x32_bf16 v[12:15], v[52:55], v[224:227], v[12:15]
	v_mfma_f32_16x16x32_bf16 v[8:11], v[60:63], v[224:227], v[8:11]
	v_mfma_f32_16x16x32_bf16 v[32:35], v[64:67], v[76:79], v[32:35]
	v_mfma_f32_16x16x32_bf16 v[100:103], v[68:71], v[80:83], v[32:35]
	v_mfma_f32_16x16x32_bf16 v[32:35], v[196:199], v[76:79], v[36:39]
	v_mfma_f32_16x16x32_bf16 v[96:99], v[200:203], v[80:83], v[32:35]
	v_mfma_f32_16x16x32_bf16 v[32:35], v[64:67], v[88:91], v[44:47]
	v_mfma_f32_16x16x32_bf16 v[44:47], v[68:71], v[92:95], v[32:35]
	v_mfma_f32_16x16x32_bf16 v[32:35], v[196:199], v[88:91], v[40:43]
	v_mfma_f32_16x16x32_bf16 v[20:23], v[64:67], v[204:207], v[20:23]
	v_mfma_f32_16x16x32_bf16 v[16:19], v[196:199], v[204:207], v[16:19]
	v_mfma_f32_16x16x32_bf16 v[4:7], v[64:67], v[220:223], v[4:7]
	v_mfma_f32_16x16x32_bf16 v[0:3], v[196:199], v[220:223], v[0:3]
	v_mfma_f32_16x16x32_bf16 v[40:43], v[200:203], v[92:95], v[32:35]
	v_mfma_f32_16x16x32_bf16 v[20:23], v[68:71], v[216:219], v[20:23]
	v_mfma_f32_16x16x32_bf16 v[16:19], v[200:203], v[216:219], v[16:19]
	v_mfma_f32_16x16x32_bf16 v[4:7], v[68:71], v[224:227], v[4:7]
	v_mfma_f32_16x16x32_bf16 v[0:3], v[200:203], v[224:227], v[0:3]
	s_barrier
	s_add_i32 s7, s7, 2
	s_add_u32 s26, s26, 0x100
	s_addc_u32 s27, s27, 0
	s_add_u32 vcc_hi, vcc_hi, 0x100
	s_addc_u32 s6, s6, 0
	s_cmp_gt_u32 s7, 29
	s_cbranch_scc0 .LBB0_353
	s_setprio 0
	s_and_b64 vcc, exec, s[12:13]
	s_cbranch_vccz .LBB0_356
	s_barrier

; #define PG8_STAGE(bufoff, gbase, voff) do { _Pragma("unroll") for (int _i = 0; _i < 2; ++_i) \
;         __builtin_amdgcn_global_load_lds((const unsigned*)((const char*)(gbase) + (voff)[_i]), (LAS unsigned*)(lds + (bufoff) + ldsw + _i * 8192), 16, 0, 0); } while (0)
; #define PG8_LDA(dst, b, h) do { _Pragma("unroll") for (int m = 0; m < 4; ++m) _Pragma("unroll") for (int k = 0; k < 2; ++k) dst[m][k] = *(const LAS bf16x8*)(lds + PG8_SA(b, h) + aoff + m * 2048 + k * 1024); } while (0)
; #define PG8_LDB(dst, b, h) do { _Pragma("unroll") for (int n = 0; n < 2; ++n) _Pragma("unroll") for (int k = 0; k < 2; ++k) dst[n][k] = *(const LAS bf16x8*)(lds + PG8_SB(b, h) + boff + n * 2048 + k * 1024); } while (0)
; #define PG8_MMA(ai, bj, At, Bt) do { __builtin_amdgcn_s_setprio(1); _Pragma("unroll") for (int m = 0; m < 4; ++m) _Pragma("unroll") for (int n = 0; n < 2; ++n) _Pragma("unroll") for (int k = 0; k < 2; ++k) \
;         acc[ai][bj][m][n] = __builtin_amdgcn_mfma_f32_16x16x32_bf16(Bt[n][k], At[m][k], acc[ai][bj][m][n], 0, 0, 0); __builtin_amdgcn_s_setprio(0); } while (0)
; #define PG8_WAIT_V(n) asm volatile("s_waitcnt vmcnt(" #n ")" ::: "memory")
; #define PG8_WAIT_L(n) asm volatile("s_waitcnt lgkmcnt(" #n ")" ::: "memory")
; #define PG8_BAR __builtin_amdgcn_s_barrier()
; #define PG8_SCHED __builtin_amdgcn_sched_barrier(0)
; template <class Sched, class Epi, bool ALIGN_EPI, bool SP2>
; __device__ __forceinline__ void gemm_phase(LAS unsigned char* lds, const int K, const int lda, const int ldb, const Sched& S, const Epi& E) {
;     ...
;         for (int t = 0; t < nt; t += 2) {
;             const bool last = (t == nt - 2);
;             const char* a1 = cA + (size_t)(t + 1) * kstep;
;             const char* a2 = last ? nA : cA + (size_t)(t + 2) * kstep; const char* b2 = last ? nB : cB + (size_t)(t + 2) * kstep;
;             const char* a3 = a2 + kstep; const char* b3 = b2 + kstep;
;             if constexpr (SP2) {
;             PG8_LDB(B0, 0, 0); PG8_LDB(B1, 0, 1); PG8_SCHED; PG8_LDA(At, 0, 0); PG8_STAGE(PG8_SA(1, 1), a1 + hstepA, voffA);
;             PG8_WAIT_V(8); PG8_WAIT_L(0); PG8_BAR; PG8_MMA(0, 0, At, B0); PG8_MMA(0, 1, At, B1); PG8_BAR; PG8_SCHED;
;             PG8_LDA(At, 0, 1); PG8_STAGE(PG8_SB(0, 0), b2, voffB); PG8_STAGE(PG8_SB(0, 1), b2 + hstepB, voffB); PG8_STAGE(PG8_SA(0, 0), a2, voffA);
.Lprio_skip_821:
.LBB0_821:
	v_add_u32_e32 v140, s44, v181
	v_add_u32_e32 v170, s45, v181
	ds_read_b128 v[128:131], v140
	ds_read_b128 v[132:135], v140 offset:1024
	ds_read_b128 v[136:139], v140 offset:2048
	ds_read_b128 v[140:143], v140 offset:3072
	ds_read_b128 v[144:147], v170
	ds_read_b128 v[148:151], v170 offset:1024
	ds_read_b128 v[166:169], v170 offset:2048
	ds_read_b128 v[170:173], v170 offset:3072
	s_add_u32 s20, s4, 0x100
	s_addc_u32 s21, s5, 0
	s_cmp_eq_u32 s61, 12
	s_cselect_b32 s25, s15, s21
	s_cselect_b32 s24, s14, s20
	s_cselect_b32 s23, s17, s60
	s_cselect_b32 s22, s16, s53
	v_lshl_add_u64 v[174:175], s[4:5], 0, v[162:163]
	s_add_i32 m0, s29, 0xc000
	ds_read_b128 v[184:187], v183
	ds_read_b128 v[188:191], v183 offset:1024
	ds_read_b128 v[192:195], v183 offset:2048
	ds_read_b128 v[196:199], v183 offset:3072
	ds_read_b128 v[200:203], v183 offset:4096
	ds_read_b128 v[204:207], v183 offset:5120
	ds_read_b128 v[208:211], v183 offset:6144
	ds_read_b128 v[212:215], v183 offset:7168
	global_load_lds_dwordx4 v[174:175], off
	v_lshl_add_u64 v[174:175], s[4:5], 0, v[164:165]
	s_add_i32 m0, s29, 0xe000
	s_nop 0
	global_load_lds_dwordx4 v[174:175], off
	s_waitcnt vmcnt(8) lgkmcnt(0)
	s_barrier
	v_mfma_f32_16x16x32_bf16 v[124:127], v[128:131], v[184:187], v[124:127]
	v_mfma_f32_16x16x32_bf16 v[120:123], v[136:139], v[184:187], v[120:123]
	v_mfma_f32_16x16x32_bf16 v[116:119], v[128:131], v[192:195], v[116:119]
	v_mfma_f32_16x16x32_bf16 v[112:115], v[136:139], v[192:195], v[112:115]
	v_mfma_f32_16x16x32_bf16 v[108:111], v[128:131], v[200:203], v[108:111]
	v_mfma_f32_16x16x32_bf16 v[104:107], v[136:139], v[200:203], v[104:107]
	v_mfma_f32_16x16x32_bf16 v[100:103], v[128:131], v[208:211], v[100:103]
	v_mfma_f32_16x16x32_bf16 v[96:99], v[136:139], v[208:211], v[96:99]
	v_mfma_f32_16x16x32_bf16 v[124:127], v[132:135], v[188:191], v[124:127]
	v_mfma_f32_16x16x32_bf16 v[120:123], v[140:143], v[188:191], v[120:123]
	v_mfma_f32_16x16x32_bf16 v[116:119], v[132:135], v[196:199], v[116:119]
	v_mfma_f32_16x16x32_bf16 v[112:115], v[140:143], v[196:199], v[112:115]
	v_mfma_f32_16x16x32_bf16 v[108:111], v[132:135], v[204:207], v[108:111]
	v_mfma_f32_16x16x32_bf16 v[104:107], v[140:143], v[204:207], v[104:107]
	v_mfma_f32_16x16x32_bf16 v[100:103], v[132:135], v[212:215], v[100:103]
	v_mfma_f32_16x16x32_bf16 v[96:99], v[140:143], v[212:215], v[96:99]
	v_mfma_f32_16x16x32_bf16 v[92:95], v[144:147], v[184:187], v[92:95]
	v_mfma_f32_16x16x32_bf16 v[88:91], v[166:169], v[184:187], v[88:91]
	v_mfma_f32_16x16x32_bf16 v[84:87], v[144:147], v[192:195], v[84:87]
	v_mfma_f32_16x16x32_bf16 v[80:83], v[166:169], v[192:195], v[80:83]
	v_mfma_f32_16x16x32_bf16 v[76:79], v[144:147], v[200:203], v[76:79]
	v_mfma_f32_16x16x32_bf16 v[72:75], v[166:169], v[200:203], v[72:75]
	v_mfma_f32_16x16x32_bf16 v[68:71], v[144:147], v[208:211], v[68:71]
	v_mfma_f32_16x16x32_bf16 v[64:67], v[166:169], v[208:211], v[64:67]
	v_mfma_f32_16x16x32_bf16 v[92:95], v[148:151], v[188:191], v[92:95]
	v_mfma_f32_16x16x32_bf16 v[88:91], v[170:173], v[188:191], v[88:91]
	v_mfma_f32_16x16x32_bf16 v[84:87], v[148:151], v[196:199], v[84:87]
	v_mfma_f32_16x16x32_bf16 v[80:83], v[170:173], v[196:199], v[80:83]
	v_mfma_f32_16x16x32_bf16 v[76:79], v[148:151], v[204:207], v[76:79]
	v_mfma_f32_16x16x32_bf16 v[72:75], v[170:173], v[204:207], v[72:75]
	v_mfma_f32_16x16x32_bf16 v[68:71], v[148:151], v[212:215], v[68:71]
	v_mfma_f32_16x16x32_bf16 v[64:67], v[170:173], v[212:215], v[64:67]
	s_barrier
	s_add_i32 s4, s44, s28
	v_lshl_add_u64 v[174:175], s[22:23], 0, v[156:157]
	s_mov_b32 m0, s4
	ds_read_b128 v[184:187], v183 offset:16384
	ds_read_b128 v[188:191], v183 offset:17408
	ds_read_b128 v[192:195], v183 offset:18432
	ds_read_b128 v[196:199], v183 offset:19456
	ds_read_b128 v[200:203], v183 offset:20480
	ds_read_b128 v[204:207], v183 offset:21504
	ds_read_b128 v[208:211], v183 offset:22528
	ds_read_b128 v[212:215], v183 offset:23552
	global_load_lds_dwordx4 v[174:175], off
	s_add_i32 m0, s4, 0x2000
	s_add_u32 s4, s22, 0x40000
	v_lshl_add_u64 v[216:217], s[22:23], 0, v[160:161]
	s_addc_u32 s5, s23, 0
	s_add_i32 s62, s45, s28
	global_load_lds_dwordx4 v[216:217], off
	v_lshl_add_u64 v[218:219], s[4:5], 0, v[156:157]
	s_mov_b32 m0, s62
	v_lshl_add_u64 v[220:221], s[24:25], 0, v[158:159]
	global_load_lds_dwordx4 v[218:219], off
	v_lshl_add_u64 v[218:219], s[4:5], 0, v[160:161]
	s_add_i32 m0, s62, 0x2000
	s_nop 0
	global_load_lds_dwordx4 v[218:219], off
	v_lshl_add_u64 v[218:219], s[24:25], 0, v[154:155]
	s_mov_b32 m0, s29
	s_nop 0
	global_load_lds_dwordx4 v[218:219], off
	s_mov_b32 m0, s33
	s_nop 0
	global_load_lds_dwordx4 v[220:221], off
	s_waitcnt vmcnt(8) lgkmcnt(0)
	s_barrier
; #define PG8_STAGE(bufoff, gbase, voff) do { _Pragma("unroll") for (int _i = 0; _i < 2; ++_i) \
;         __builtin_amdgcn_global_load_lds((const unsigned*)((const char*)(gbase) + (voff)[_i]), (LAS unsigned*)(lds + (bufoff) + ldsw + _i * 8192), 16, 0, 0); } while (0)
; #define PG8_LDA(dst, b, h) do { _Pragma("unroll") for (int m = 0; m < 4; ++m) _Pragma("unroll") for (int k = 0; k < 2; ++k) dst[m][k] = *(const LAS bf16x8*)(lds + PG8_SA(b, h) + aoff + m * 2048 + k * 1024); } while (0)
; #define PG8_LDB(dst, b, h) do { _Pragma("unroll") for (int n = 0; n < 2; ++n) _Pragma("unroll") for (int k = 0; k < 2; ++k) dst[n][k] = *(const LAS bf16x8*)(lds + PG8_SB(b, h) + boff + n * 2048 + k * 1024); } while (0)
; #define PG8_MMA(ai, bj, At, Bt) do { __builtin_amdgcn_s_setprio(1); _Pragma("unroll") for (int m = 0; m < 4; ++m) _Pragma("unroll") for (int n = 0; n < 2; ++n) _Pragma("unroll") for (int k = 0; k < 2; ++k) \
;         acc[ai][bj][m][n] = __builtin_amdgcn_mfma_f32_16x16x32_bf16(Bt[n][k], At[m][k], acc[ai][bj][m][n], 0, 0, 0); __builtin_amdgcn_s_setprio(0); } while (0)
; #define PG8_WAIT_V(n) asm volatile("s_waitcnt vmcnt(" #n ")" ::: "memory")
; #define PG8_WAIT_L(n) asm volatile("s_waitcnt lgkmcnt(" #n ")" ::: "memory")
; #define PG8_BAR __builtin_amdgcn_s_barrier()
; #define PG8_SCHED __builtin_amdgcn_sched_barrier(0)
; template <class Sched, class Epi, bool ALIGN_EPI, bool SP2>
; __device__ __forceinline__ void gemm_phase(LAS unsigned char* lds, const int K, const int lda, const int ldb, const Sched& S, const Epi& E) {
;     ...
;             PG8_WAIT_V(8); PG8_WAIT_L(0); PG8_BAR; PG8_MMA(1, 0, At, B0); PG8_MMA(1, 1, At, B1); PG8_BAR; PG8_SCHED;
;             PG8_LDB(B0, 1, 0); PG8_LDB(B1, 1, 1); PG8_SCHED; PG8_LDA(At, 1, 0); PG8_STAGE(PG8_SA(0, 1), a2 + hstepA, voffA);
;             PG8_WAIT_V(8); PG8_WAIT_L(0); PG8_BAR; PG8_MMA(0, 0, At, B0); PG8_MMA(0, 1, At, B1); PG8_BAR; PG8_SCHED;
	v_mfma_f32_16x16x32_bf16 v[60:63], v[128:131], v[184:187], v[60:63]
	v_mfma_f32_16x16x32_bf16 v[56:59], v[136:139], v[184:187], v[56:59]
	v_mfma_f32_16x16x32_bf16 v[52:55], v[128:131], v[192:195], v[52:55]
	v_mfma_f32_16x16x32_bf16 v[48:51], v[136:139], v[192:195], v[48:51]
	v_mfma_f32_16x16x32_bf16 v[44:47], v[128:131], v[200:203], v[44:47]
	v_mfma_f32_16x16x32_bf16 v[40:43], v[136:139], v[200:203], v[40:43]
	v_mfma_f32_16x16x32_bf16 v[36:39], v[128:131], v[208:211], v[36:39]
	v_mfma_f32_16x16x32_bf16 v[32:35], v[136:139], v[208:211], v[32:35]
	v_mfma_f32_16x16x32_bf16 v[60:63], v[132:135], v[188:191], v[60:63]
	v_mfma_f32_16x16x32_bf16 v[56:59], v[140:143], v[188:191], v[56:59]
	v_mfma_f32_16x16x32_bf16 v[52:55], v[132:135], v[196:199], v[52:55]
	v_mfma_f32_16x16x32_bf16 v[48:51], v[140:143], v[196:199], v[48:51]
	v_mfma_f32_16x16x32_bf16 v[44:47], v[132:135], v[204:207], v[44:47]
	v_mfma_f32_16x16x32_bf16 v[40:43], v[140:143], v[204:207], v[40:43]
	v_mfma_f32_16x16x32_bf16 v[36:39], v[132:135], v[212:215], v[36:39]
	v_mfma_f32_16x16x32_bf16 v[32:35], v[140:143], v[212:215], v[32:35]
	v_mfma_f32_16x16x32_bf16 v[28:31], v[144:147], v[184:187], v[28:31]
	v_mfma_f32_16x16x32_bf16 v[24:27], v[166:169], v[184:187], v[24:27]
	v_mfma_f32_16x16x32_bf16 v[20:23], v[144:147], v[192:195], v[20:23]
	v_mfma_f32_16x16x32_bf16 v[16:19], v[166:169], v[192:195], v[16:19]
	v_mfma_f32_16x16x32_bf16 v[12:15], v[144:147], v[200:203], v[12:15]
	v_mfma_f32_16x16x32_bf16 v[8:11], v[166:169], v[200:203], v[8:11]
	v_mfma_f32_16x16x32_bf16 v[4:7], v[144:147], v[208:211], v[4:7]
	v_mfma_f32_16x16x32_bf16 v[0:3], v[166:169], v[208:211], v[0:3]
	v_mfma_f32_16x16x32_bf16 v[28:31], v[148:151], v[188:191], v[28:31]
	v_mfma_f32_16x16x32_bf16 v[24:27], v[170:173], v[188:191], v[24:27]
	v_mfma_f32_16x16x32_bf16 v[20:23], v[148:151], v[196:199], v[20:23]
	v_mfma_f32_16x16x32_bf16 v[16:19], v[170:173], v[196:199], v[16:19]
	v_mfma_f32_16x16x32_bf16 v[12:15], v[148:151], v[204:207], v[12:15]
	v_mfma_f32_16x16x32_bf16 v[8:11], v[170:173], v[204:207], v[8:11]
	v_mfma_f32_16x16x32_bf16 v[4:7], v[148:151], v[212:215], v[4:7]
	v_mfma_f32_16x16x32_bf16 v[0:3], v[170:173], v[212:215], v[0:3]
	s_barrier
	s_add_i32 s62, 0, 0x18000
	s_add_i32 s63, 0, 0x1c000
	v_add_u32_e32 v140, s62, v181
	v_add_u32_e32 v170, s63, v181
	ds_read_b128 v[128:131], v140
	ds_read_b128 v[132:135], v140 offset:1024
	ds_read_b128 v[136:139], v140 offset:2048
	ds_read_b128 v[140:143], v140 offset:3072
	ds_read_b128 v[144:147], v170
	ds_read_b128 v[148:151], v170 offset:1024
	ds_read_b128 v[166:169], v170 offset:2048
	ds_read_b128 v[170:173], v170 offset:3072
	s_add_u32 s4, s24, 0xc0000
	s_addc_u32 s5, s25, 0
	s_mov_b32 m0, s35
	v_lshl_add_u64 v[222:223], s[4:5], 0, v[154:155]
	ds_read_b128 v[184:187], v183 offset:32768
	ds_read_b128 v[188:191], v183 offset:33792
	ds_read_b128 v[192:195], v183 offset:34816
	ds_read_b128 v[196:199], v183 offset:35840
	ds_read_b128 v[200:203], v183 offset:36864
	ds_read_b128 v[204:207], v183 offset:37888
	ds_read_b128 v[208:211], v183 offset:38912
	ds_read_b128 v[212:215], v183 offset:39936
	global_load_lds_dwordx4 v[222:223], off
	v_lshl_add_u64 v[222:223], s[4:5], 0, v[158:159]
	s_mov_b32 m0, s36
	s_nop 0
	global_load_lds_dwordx4 v[222:223], off
	s_waitcnt vmcnt(8) lgkmcnt(0)
	s_barrier
	v_mfma_f32_16x16x32_bf16 v[124:127], v[128:131], v[184:187], v[124:127]
	v_mfma_f32_16x16x32_bf16 v[120:123], v[136:139], v[184:187], v[120:123]
	v_mfma_f32_16x16x32_bf16 v[116:119], v[128:131], v[192:195], v[116:119]
	v_mfma_f32_16x16x32_bf16 v[112:115], v[136:139], v[192:195], v[112:115]
	v_mfma_f32_16x16x32_bf16 v[108:111], v[128:131], v[200:203], v[108:111]
	v_mfma_f32_16x16x32_bf16 v[104:107], v[136:139], v[200:203], v[104:107]
	v_mfma_f32_16x16x32_bf16 v[100:103], v[128:131], v[208:211], v[100:103]
	v_mfma_f32_16x16x32_bf16 v[96:99], v[136:139], v[208:211], v[96:99]
	v_mfma_f32_16x16x32_bf16 v[124:127], v[132:135], v[188:191], v[124:127]
	v_mfma_f32_16x16x32_bf16 v[120:123], v[140:143], v[188:191], v[120:123]
	v_mfma_f32_16x16x32_bf16 v[116:119], v[132:135], v[196:199], v[116:119]
	v_mfma_f32_16x16x32_bf16 v[112:115], v[140:143], v[196:199], v[112:115]
	v_mfma_f32_16x16x32_bf16 v[108:111], v[132:135], v[204:207], v[108:111]
	v_mfma_f32_16x16x32_bf16 v[104:107], v[140:143], v[204:207], v[104:107]
	v_mfma_f32_16x16x32_bf16 v[100:103], v[132:135], v[212:215], v[100:103]
	v_mfma_f32_16x16x32_bf16 v[96:99], v[140:143], v[212:215], v[96:99]
	v_mfma_f32_16x16x32_bf16 v[92:95], v[144:147], v[184:187], v[92:95]
	v_mfma_f32_16x16x32_bf16 v[88:91], v[166:169], v[184:187], v[88:91]
	v_mfma_f32_16x16x32_bf16 v[84:87], v[144:147], v[192:195], v[84:87]
	v_mfma_f32_16x16x32_bf16 v[80:83], v[166:169], v[192:195], v[80:83]
	v_mfma_f32_16x16x32_bf16 v[76:79], v[144:147], v[200:203], v[76:79]
	v_mfma_f32_16x16x32_bf16 v[72:75], v[166:169], v[200:203], v[72:75]
	v_mfma_f32_16x16x32_bf16 v[68:71], v[144:147], v[208:211], v[68:71]
	v_mfma_f32_16x16x32_bf16 v[64:67], v[166:169], v[208:211], v[64:67]
	v_mfma_f32_16x16x32_bf16 v[92:95], v[148:151], v[188:191], v[92:95]
	v_mfma_f32_16x16x32_bf16 v[88:91], v[170:173], v[188:191], v[88:91]
	v_mfma_f32_16x16x32_bf16 v[84:87], v[148:151], v[196:199], v[84:87]
	v_mfma_f32_16x16x32_bf16 v[80:83], v[170:173], v[196:199], v[80:83]
	v_mfma_f32_16x16x32_bf16 v[76:79], v[148:151], v[204:207], v[76:79]
	v_mfma_f32_16x16x32_bf16 v[72:75], v[170:173], v[204:207], v[72:75]
	v_mfma_f32_16x16x32_bf16 v[68:71], v[148:151], v[212:215], v[68:71]
	v_mfma_f32_16x16x32_bf16 v[64:67], v[170:173], v[212:215], v[64:67]
	s_barrier
; #define PG8_STAGE(bufoff, gbase, voff) do { _Pragma("unroll") for (int _i = 0; _i < 2; ++_i) \
;         __builtin_amdgcn_global_load_lds((const unsigned*)((const char*)(gbase) + (voff)[_i]), (LAS unsigned*)(lds + (bufoff) + ldsw + _i * 8192), 16, 0, 0); } while (0)
; #define PG8_LDA(dst, b, h) do { _Pragma("unroll") for (int m = 0; m < 4; ++m) _Pragma("unroll") for (int k = 0; k < 2; ++k) dst[m][k] = *(const LAS bf16x8*)(lds + PG8_SA(b, h) + aoff + m * 2048 + k * 1024); } while (0)
; #define PG8_MMA(ai, bj, At, Bt) do { __builtin_amdgcn_s_setprio(1); _Pragma("unroll") for (int m = 0; m < 4; ++m) _Pragma("unroll") for (int n = 0; n < 2; ++n) _Pragma("unroll") for (int k = 0; k < 2; ++k) \
;         acc[ai][bj][m][n] = __builtin_amdgcn_mfma_f32_16x16x32_bf16(Bt[n][k], At[m][k], acc[ai][bj][m][n], 0, 0, 0); __builtin_amdgcn_s_setprio(0); } while (0)
; #define PG8_WAIT_V(n) asm volatile("s_waitcnt vmcnt(" #n ")" ::: "memory")
; #define PG8_WAIT_L(n) asm volatile("s_waitcnt lgkmcnt(" #n ")" ::: "memory")
; #define PG8_BAR __builtin_amdgcn_s_barrier()
; #define PG8_SCHED __builtin_amdgcn_sched_barrier(0)
; template <class Sched, class Epi, bool ALIGN_EPI, bool SP2>
; __device__ __forceinline__ void gemm_phase(LAS unsigned char* lds, const int K, const int lda, const int ldb, const Sched& S, const Epi& E) {
;     ...
;             PG8_LDA(At, 1, 1); PG8_STAGE(PG8_SB(1, 0), b3, voffB); PG8_STAGE(PG8_SB(1, 1), b3 + hstepB, voffB); PG8_STAGE(PG8_SA(1, 0), a3, voffA);
;             PG8_WAIT_V(8); PG8_WAIT_L(0); PG8_BAR; PG8_MMA(1, 0, At, B0); PG8_MMA(1, 1, At, B1); PG8_BAR; PG8_SCHED;
	s_add_i32 s4, s62, s28
	v_lshl_add_u64 v[174:175], v[174:175], 0, s[8:9]
	s_mov_b32 m0, s4
	ds_read_b128 v[184:187], v183 offset:49152
	ds_read_b128 v[188:191], v183 offset:50176
	ds_read_b128 v[192:195], v183 offset:51200
	ds_read_b128 v[196:199], v183 offset:52224
	ds_read_b128 v[200:203], v183 offset:53248
	ds_read_b128 v[204:207], v183 offset:54272
	ds_read_b128 v[208:211], v183 offset:55296
	ds_read_b128 v[212:215], v183 offset:56320
	global_load_lds_dwordx4 v[174:175], off
	s_add_i32 m0, s4, 0x2000
	s_add_u32 s4, s22, 0x40080
	v_lshl_add_u64 v[174:175], v[216:217], 0, s[8:9]
	s_addc_u32 s5, s23, 0
	s_add_i32 s22, s63, s28
	global_load_lds_dwordx4 v[174:175], off
	v_lshl_add_u64 v[174:175], s[4:5], 0, v[156:157]
	s_mov_b32 m0, s22
	s_nop 0
	global_load_lds_dwordx4 v[174:175], off
	v_lshl_add_u64 v[174:175], s[4:5], 0, v[160:161]
	s_add_i32 m0, s22, 0x2000
	s_nop 0
	global_load_lds_dwordx4 v[174:175], off
	v_lshl_add_u64 v[174:175], v[218:219], 0, s[8:9]
	s_mov_b32 m0, s42
	s_nop 0
	global_load_lds_dwordx4 v[174:175], off
	v_lshl_add_u64 v[174:175], v[220:221], 0, s[8:9]
	s_mov_b32 m0, s43
	s_nop 0
	global_load_lds_dwordx4 v[174:175], off
	s_waitcnt vmcnt(8) lgkmcnt(0)
	s_barrier
	v_mfma_f32_16x16x32_bf16 v[60:63], v[128:131], v[184:187], v[60:63]
	v_mfma_f32_16x16x32_bf16 v[56:59], v[136:139], v[184:187], v[56:59]
	v_mfma_f32_16x16x32_bf16 v[52:55], v[128:131], v[192:195], v[52:55]
	v_mfma_f32_16x16x32_bf16 v[48:51], v[136:139], v[192:195], v[48:51]
	v_mfma_f32_16x16x32_bf16 v[44:47], v[128:131], v[200:203], v[44:47]
	v_mfma_f32_16x16x32_bf16 v[40:43], v[136:139], v[200:203], v[40:43]
	v_mfma_f32_16x16x32_bf16 v[36:39], v[128:131], v[208:211], v[36:39]
	v_mfma_f32_16x16x32_bf16 v[32:35], v[136:139], v[208:211], v[32:35]
	v_mfma_f32_16x16x32_bf16 v[60:63], v[132:135], v[188:191], v[60:63]
	v_mfma_f32_16x16x32_bf16 v[56:59], v[140:143], v[188:191], v[56:59]
	v_mfma_f32_16x16x32_bf16 v[52:55], v[132:135], v[196:199], v[52:55]
	v_mfma_f32_16x16x32_bf16 v[48:51], v[140:143], v[196:199], v[48:51]
	v_mfma_f32_16x16x32_bf16 v[44:47], v[132:135], v[204:207], v[44:47]
	v_mfma_f32_16x16x32_bf16 v[40:43], v[140:143], v[204:207], v[40:43]
	v_mfma_f32_16x16x32_bf16 v[36:39], v[132:135], v[212:215], v[36:39]
	v_mfma_f32_16x16x32_bf16 v[32:35], v[140:143], v[212:215], v[32:35]
	v_mfma_f32_16x16x32_bf16 v[28:31], v[144:147], v[184:187], v[28:31]
	v_mfma_f32_16x16x32_bf16 v[24:27], v[166:169], v[184:187], v[24:27]
	v_mfma_f32_16x16x32_bf16 v[20:23], v[144:147], v[192:195], v[20:23]
	v_mfma_f32_16x16x32_bf16 v[16:19], v[166:169], v[192:195], v[16:19]
	v_mfma_f32_16x16x32_bf16 v[12:15], v[144:147], v[200:203], v[12:15]
	v_mfma_f32_16x16x32_bf16 v[8:11], v[166:169], v[200:203], v[8:11]
	v_mfma_f32_16x16x32_bf16 v[4:7], v[144:147], v[208:211], v[4:7]
	v_mfma_f32_16x16x32_bf16 v[0:3], v[166:169], v[208:211], v[0:3]
	v_mfma_f32_16x16x32_bf16 v[28:31], v[148:151], v[188:191], v[28:31]
	v_mfma_f32_16x16x32_bf16 v[24:27], v[170:173], v[188:191], v[24:27]
	v_mfma_f32_16x16x32_bf16 v[20:23], v[148:151], v[196:199], v[20:23]
	v_mfma_f32_16x16x32_bf16 v[16:19], v[170:173], v[196:199], v[16:19]
	v_mfma_f32_16x16x32_bf16 v[12:15], v[148:151], v[204:207], v[12:15]
	v_mfma_f32_16x16x32_bf16 v[8:11], v[170:173], v[204:207], v[8:11]
	v_mfma_f32_16x16x32_bf16 v[4:7], v[148:151], v[212:215], v[4:7]
	v_mfma_f32_16x16x32_bf16 v[0:3], v[170:173], v[212:215], v[0:3]
	s_barrier
	s_add_i32 s61, s61, 2
	s_add_u32 s53, s53, 0x100
	s_addc_u32 s60, s60, 0
	s_cmp_gt_u32 s61, 13
	s_mov_b64 s[4:5], s[20:21]
	s_cbranch_scc0 .LBB0_821
	s_setprio 0
	s_and_b64 vcc, exec, s[10:11]
	s_cbranch_vccz .LBB0_824
	s_barrier

; #define PG8_STAGE(bufoff, gbase, voff) do { _Pragma("unroll") for (int _i = 0; _i < 2; ++_i) \
;         __builtin_amdgcn_global_load_lds((const unsigned*)((const char*)(gbase) + (voff)[_i]), (LAS unsigned*)(lds + (bufoff) + ldsw + _i * 8192), 16, 0, 0); } while (0)
; #define PG8_LDA(dst, b, h) do { _Pragma("unroll") for (int m = 0; m < 4; ++m) _Pragma("unroll") for (int k = 0; k < 2; ++k) dst[m][k] = *(const LAS bf16x8*)(lds + PG8_SA(b, h) + aoff + m * 2048 + k * 1024); } while (0)
; #define PG8_LDB(dst, b, h) do { _Pragma("unroll") for (int n = 0; n < 2; ++n) _Pragma("unroll") for (int k = 0; k < 2; ++k) dst[n][k] = *(const LAS bf16x8*)(lds + PG8_SB(b, h) + boff + n * 2048 + k * 1024); } while (0)
; #define PG8_MMA(ai, bj, At, Bt) do { __builtin_amdgcn_s_setprio(1); _Pragma("unroll") for (int m = 0; m < 4; ++m) _Pragma("unroll") for (int n = 0; n < 2; ++n) _Pragma("unroll") for (int k = 0; k < 2; ++k) \
;         acc[ai][bj][m][n] = __builtin_amdgcn_mfma_f32_16x16x32_bf16(Bt[n][k], At[m][k], acc[ai][bj][m][n], 0, 0, 0); __builtin_amdgcn_s_setprio(0); } while (0)
; #define PG8_WAIT_V(n) asm volatile("s_waitcnt vmcnt(" #n ")" ::: "memory")
; #define PG8_WAIT_L(n) asm volatile("s_waitcnt lgkmcnt(" #n ")" ::: "memory")
; #define PG8_BAR __builtin_amdgcn_s_barrier()
; #define PG8_SCHED __builtin_amdgcn_sched_barrier(0)
; template <class Sched, class Epi, bool ALIGN_EPI, bool SP2>
; __device__ __forceinline__ void gemm_phase(LAS unsigned char* lds, const int K, const int lda, const int ldb, const Sched& S, const Epi& E) {
;     ...
;         for (int t = 0; t < nt; t += 2) {
;             const bool last = (t == nt - 2);
;             const char* a1 = cA + (size_t)(t + 1) * kstep;
;             const char* a2 = last ? nA : cA + (size_t)(t + 2) * kstep; const char* b2 = last ? nB : cB + (size_t)(t + 2) * kstep;
;             const char* a3 = a2 + kstep; const char* b3 = b2 + kstep;
;             if constexpr (SP2) {
;             PG8_LDB(B0, 0, 0); PG8_LDB(B1, 0, 1); PG8_SCHED; PG8_LDA(At, 0, 0); PG8_STAGE(PG8_SA(1, 1), a1 + hstepA, voffA);
;             PG8_WAIT_V(8); PG8_WAIT_L(0); PG8_BAR; PG8_MMA(0, 0, At, B0); PG8_MMA(0, 1, At, B1); PG8_BAR; PG8_SCHED;
;             PG8_LDA(At, 0, 1); PG8_STAGE(PG8_SB(0, 0), b2, voffB); PG8_STAGE(PG8_SB(0, 1), b2 + hstepB, voffB); PG8_STAGE(PG8_SA(0, 0), a2, voffA);
.Lprio_skip_945:
.LBB0_945:
	ds_read_b128 v[52:55], v209
	ds_read_b128 v[56:59], v209 offset:1024
	ds_read_b128 v[64:67], v209 offset:2048
	ds_read_b128 v[68:71], v209 offset:3072
	ds_read_b128 v[72:75], v210
	ds_read_b128 v[76:79], v210 offset:1024
	ds_read_b128 v[88:91], v210 offset:2048
	ds_read_b128 v[92:95], v210 offset:3072
	s_add_u32 s42, s36, 0xfff80080
	s_addc_u32 s43, s37, -1
	s_cmp_eq_u32 s61, 28
	s_cselect_b32 s45, s27, s43
	s_cselect_b32 s44, s26, s42
	s_cselect_b32 s43, s29, s25
	s_cselect_b32 s42, s28, s1
	v_lshl_add_u64 v[206:207], s[36:37], 0, v[186:187]
	s_add_i32 m0, s21, 0xc000
	ds_read_b128 v[160:163], v211
	ds_read_b128 v[164:167], v211 offset:1024
	ds_read_b128 v[168:171], v211 offset:2048
	ds_read_b128 v[172:175], v211 offset:3072
	ds_read_b128 v[190:193], v211 offset:4096
	ds_read_b128 v[194:197], v211 offset:5120
	ds_read_b128 v[198:201], v211 offset:6144
	ds_read_b128 v[202:205], v211 offset:7168
	global_load_lds_dwordx4 v[206:207], off
	v_lshl_add_u64 v[206:207], s[36:37], 0, v[188:189]
	s_add_i32 m0, s21, 0xe000
	s_nop 0
	global_load_lds_dwordx4 v[206:207], off
	s_waitcnt vmcnt(8) lgkmcnt(0)
	s_barrier
	v_mfma_f32_16x16x32_bf16 v[156:159], v[52:55], v[160:163], v[156:159]
	v_mfma_f32_16x16x32_bf16 v[152:155], v[64:67], v[160:163], v[152:155]
	v_mfma_f32_16x16x32_bf16 v[140:143], v[52:55], v[168:171], v[140:143]
	v_mfma_f32_16x16x32_bf16 v[136:139], v[64:67], v[168:171], v[136:139]
	v_mfma_f32_16x16x32_bf16 v[124:127], v[52:55], v[190:193], v[124:127]
	v_mfma_f32_16x16x32_bf16 v[120:123], v[64:67], v[190:193], v[120:123]
	v_mfma_f32_16x16x32_bf16 v[108:111], v[52:55], v[198:201], v[108:111]
	v_mfma_f32_16x16x32_bf16 v[104:107], v[64:67], v[198:201], v[104:107]
	v_mfma_f32_16x16x32_bf16 v[156:159], v[56:59], v[164:167], v[156:159]
	v_mfma_f32_16x16x32_bf16 v[152:155], v[68:71], v[164:167], v[152:155]
	v_mfma_f32_16x16x32_bf16 v[140:143], v[56:59], v[172:175], v[140:143]
	v_mfma_f32_16x16x32_bf16 v[136:139], v[68:71], v[172:175], v[136:139]
	v_mfma_f32_16x16x32_bf16 v[124:127], v[56:59], v[194:197], v[124:127]
	v_mfma_f32_16x16x32_bf16 v[120:123], v[68:71], v[194:197], v[120:123]
	v_mfma_f32_16x16x32_bf16 v[108:111], v[56:59], v[202:205], v[108:111]
	v_mfma_f32_16x16x32_bf16 v[104:107], v[68:71], v[202:205], v[104:107]
	v_mfma_f32_16x16x32_bf16 v[148:151], v[72:75], v[160:163], v[148:151]
	v_mfma_f32_16x16x32_bf16 v[144:147], v[88:91], v[160:163], v[144:147]
	v_mfma_f32_16x16x32_bf16 v[132:135], v[72:75], v[168:171], v[132:135]
	v_mfma_f32_16x16x32_bf16 v[128:131], v[88:91], v[168:171], v[128:131]
	v_mfma_f32_16x16x32_bf16 v[116:119], v[72:75], v[190:193], v[116:119]
	v_mfma_f32_16x16x32_bf16 v[112:115], v[88:91], v[190:193], v[112:115]
	v_mfma_f32_16x16x32_bf16 v[100:103], v[72:75], v[198:201], v[100:103]
	v_mfma_f32_16x16x32_bf16 v[96:99], v[88:91], v[198:201], v[96:99]
	v_mfma_f32_16x16x32_bf16 v[148:151], v[76:79], v[164:167], v[148:151]
	v_mfma_f32_16x16x32_bf16 v[144:147], v[92:95], v[164:167], v[144:147]
	v_mfma_f32_16x16x32_bf16 v[132:135], v[76:79], v[172:175], v[132:135]
	v_mfma_f32_16x16x32_bf16 v[128:131], v[92:95], v[172:175], v[128:131]
	v_mfma_f32_16x16x32_bf16 v[116:119], v[76:79], v[194:197], v[116:119]
	v_mfma_f32_16x16x32_bf16 v[112:115], v[92:95], v[194:197], v[112:115]
	v_mfma_f32_16x16x32_bf16 v[100:103], v[76:79], v[202:205], v[100:103]
	v_mfma_f32_16x16x32_bf16 v[96:99], v[92:95], v[202:205], v[96:99]
	s_barrier
	s_add_i32 s62, s50, s19
	v_lshl_add_u64 v[206:207], s[42:43], 0, v[182:183]
	s_mov_b32 m0, s62
	ds_read_b128 v[160:163], v211 offset:16384
	ds_read_b128 v[164:167], v211 offset:17408
	ds_read_b128 v[168:171], v211 offset:18432
	ds_read_b128 v[172:175], v211 offset:19456
	ds_read_b128 v[190:193], v211 offset:20480
	ds_read_b128 v[194:197], v211 offset:21504
	ds_read_b128 v[198:201], v211 offset:22528
	ds_read_b128 v[202:205], v211 offset:23552
	global_load_lds_dwordx4 v[206:207], off
	s_add_i32 m0, s62, 0x2000
	s_add_u32 s62, s42, 0x80000
	v_lshl_add_u64 v[214:215], s[42:43], 0, v[184:185]
	s_addc_u32 s63, s43, 0
	s_add_i32 s64, s51, s19
	global_load_lds_dwordx4 v[214:215], off
	v_lshl_add_u64 v[216:217], s[62:63], 0, v[182:183]
	s_mov_b32 m0, s64
	v_lshl_add_u64 v[218:219], s[44:45], 0, v[184:185]
	global_load_lds_dwordx4 v[216:217], off
	v_lshl_add_u64 v[216:217], s[62:63], 0, v[184:185]
	s_add_i32 m0, s64, 0x2000
	s_nop 0
	global_load_lds_dwordx4 v[216:217], off
	v_lshl_add_u64 v[216:217], s[44:45], 0, v[182:183]
	s_mov_b32 m0, s21
	s_nop 0
	global_load_lds_dwordx4 v[216:217], off
	s_mov_b32 m0, s33
	s_nop 0
	global_load_lds_dwordx4 v[218:219], off
	s_waitcnt vmcnt(8) lgkmcnt(0)
	s_barrier
; #define PG8_STAGE(bufoff, gbase, voff) do { _Pragma("unroll") for (int _i = 0; _i < 2; ++_i) \
;         __builtin_amdgcn_global_load_lds((const unsigned*)((const char*)(gbase) + (voff)[_i]), (LAS unsigned*)(lds + (bufoff) + ldsw + _i * 8192), 16, 0, 0); } while (0)
; #define PG8_LDA(dst, b, h) do { _Pragma("unroll") for (int m = 0; m < 4; ++m) _Pragma("unroll") for (int k = 0; k < 2; ++k) dst[m][k] = *(const LAS bf16x8*)(lds + PG8_SA(b, h) + aoff + m * 2048 + k * 1024); } while (0)
; #define PG8_LDB(dst, b, h) do { _Pragma("unroll") for (int n = 0; n < 2; ++n) _Pragma("unroll") for (int k = 0; k < 2; ++k) dst[n][k] = *(const LAS bf16x8*)(lds + PG8_SB(b, h) + boff + n * 2048 + k * 1024); } while (0)
; #define PG8_MMA(ai, bj, At, Bt) do { __builtin_amdgcn_s_setprio(1); _Pragma("unroll") for (int m = 0; m < 4; ++m) _Pragma("unroll") for (int n = 0; n < 2; ++n) _Pragma("unroll") for (int k = 0; k < 2; ++k) \
;         acc[ai][bj][m][n] = __builtin_amdgcn_mfma_f32_16x16x32_bf16(Bt[n][k], At[m][k], acc[ai][bj][m][n], 0, 0, 0); __builtin_amdgcn_s_setprio(0); } while (0)
; #define PG8_WAIT_V(n) asm volatile("s_waitcnt vmcnt(" #n ")" ::: "memory")
; #define PG8_WAIT_L(n) asm volatile("s_waitcnt lgkmcnt(" #n ")" ::: "memory")
; #define PG8_BAR __builtin_amdgcn_s_barrier()
; #define PG8_SCHED __builtin_amdgcn_sched_barrier(0)
; template <class Sched, class Epi, bool ALIGN_EPI, bool SP2>
; __device__ __forceinline__ void gemm_phase(LAS unsigned char* lds, const int K, const int lda, const int ldb, const Sched& S, const Epi& E) {
;     ...
;             PG8_WAIT_V(8); PG8_WAIT_L(0); PG8_BAR; PG8_MMA(1, 0, At, B0); PG8_MMA(1, 1, At, B1); PG8_BAR; PG8_SCHED;
;             PG8_LDB(B0, 1, 0); PG8_LDB(B1, 1, 1); PG8_SCHED; PG8_LDA(At, 1, 0); PG8_STAGE(PG8_SA(0, 1), a2 + hstepA, voffA);
;             PG8_WAIT_V(8); PG8_WAIT_L(0); PG8_BAR; PG8_MMA(0, 0, At, B0); PG8_MMA(0, 1, At, B1); PG8_BAR; PG8_SCHED;
	v_mfma_f32_16x16x32_bf16 v[84:87], v[52:55], v[160:163], v[84:87]
	v_mfma_f32_16x16x32_bf16 v[80:83], v[64:67], v[160:163], v[80:83]
	v_mfma_f32_16x16x32_bf16 v[44:47], v[52:55], v[168:171], v[44:47]
	v_mfma_f32_16x16x32_bf16 v[40:43], v[64:67], v[168:171], v[40:43]
	v_mfma_f32_16x16x32_bf16 v[28:31], v[52:55], v[190:193], v[28:31]
	v_mfma_f32_16x16x32_bf16 v[24:27], v[64:67], v[190:193], v[24:27]
	v_mfma_f32_16x16x32_bf16 v[12:15], v[52:55], v[198:201], v[12:15]
	v_mfma_f32_16x16x32_bf16 v[8:11], v[64:67], v[198:201], v[8:11]
	v_mfma_f32_16x16x32_bf16 v[84:87], v[56:59], v[164:167], v[84:87]
	v_mfma_f32_16x16x32_bf16 v[80:83], v[68:71], v[164:167], v[80:83]
	v_mfma_f32_16x16x32_bf16 v[44:47], v[56:59], v[172:175], v[44:47]
	v_mfma_f32_16x16x32_bf16 v[40:43], v[68:71], v[172:175], v[40:43]
	v_mfma_f32_16x16x32_bf16 v[28:31], v[56:59], v[194:197], v[28:31]
	v_mfma_f32_16x16x32_bf16 v[24:27], v[68:71], v[194:197], v[24:27]
	v_mfma_f32_16x16x32_bf16 v[12:15], v[56:59], v[202:205], v[12:15]
	v_mfma_f32_16x16x32_bf16 v[8:11], v[68:71], v[202:205], v[8:11]
	v_mfma_f32_16x16x32_bf16 v[48:51], v[88:91], v[160:163], v[48:51]
	v_mfma_f32_16x16x32_bf16 v[36:39], v[72:75], v[168:171], v[36:39]
	v_mfma_f32_16x16x32_bf16 v[32:35], v[88:91], v[168:171], v[32:35]
	v_mfma_f32_16x16x32_bf16 v[20:23], v[72:75], v[190:193], v[20:23]
	v_mfma_f32_16x16x32_bf16 v[16:19], v[88:91], v[190:193], v[16:19]
	v_mfma_f32_16x16x32_bf16 v[4:7], v[72:75], v[198:201], v[4:7]
	v_mfma_f32_16x16x32_bf16 v[0:3], v[88:91], v[198:201], v[0:3]
	v_mfma_f32_16x16x32_bf16 v[52:55], v[72:75], v[160:163], v[60:63]
	v_mfma_f32_16x16x32_bf16 v[48:51], v[92:95], v[164:167], v[48:51]
	v_mfma_f32_16x16x32_bf16 v[36:39], v[76:79], v[172:175], v[36:39]
	v_mfma_f32_16x16x32_bf16 v[32:35], v[92:95], v[172:175], v[32:35]
	v_mfma_f32_16x16x32_bf16 v[20:23], v[76:79], v[194:197], v[20:23]
	v_mfma_f32_16x16x32_bf16 v[16:19], v[92:95], v[194:197], v[16:19]
	v_mfma_f32_16x16x32_bf16 v[4:7], v[76:79], v[202:205], v[4:7]
	v_mfma_f32_16x16x32_bf16 v[0:3], v[92:95], v[202:205], v[0:3]
	v_mfma_f32_16x16x32_bf16 v[52:55], v[76:79], v[164:167], v[52:55]
	s_barrier
	s_add_i32 s62, 0, 0x18000
	s_add_i32 s63, 0, 0x1c000
	v_add_u32_e32 v68, s62, v181
	v_add_u32_e32 v92, s63, v181
	ds_read_b128 v[56:59], v68
	ds_read_b128 v[60:63], v68 offset:1024
	ds_read_b128 v[64:67], v68 offset:2048
	ds_read_b128 v[68:71], v68 offset:3072
	ds_read_b128 v[72:75], v92
	ds_read_b128 v[76:79], v92 offset:1024
	ds_read_b128 v[88:91], v92 offset:2048
	ds_read_b128 v[92:95], v92 offset:3072
	s_add_u32 s44, s44, 0x80000
	s_addc_u32 s45, s45, 0
	s_mov_b32 m0, s35
	v_lshl_add_u64 v[220:221], s[44:45], 0, v[182:183]
	ds_read_b128 v[160:163], v211 offset:32768
	ds_read_b128 v[164:167], v211 offset:33792
	ds_read_b128 v[168:171], v211 offset:34816
	ds_read_b128 v[172:175], v211 offset:35840
	ds_read_b128 v[190:193], v211 offset:36864
	ds_read_b128 v[194:197], v211 offset:37888
	ds_read_b128 v[198:201], v211 offset:38912
	ds_read_b128 v[202:205], v211 offset:39936
	global_load_lds_dwordx4 v[220:221], off
	v_lshl_add_u64 v[220:221], s[44:45], 0, v[184:185]
	s_mov_b32 m0, s46
	s_nop 0
	global_load_lds_dwordx4 v[220:221], off
	s_waitcnt vmcnt(8) lgkmcnt(0)
	s_barrier
	v_mfma_f32_16x16x32_bf16 v[156:159], v[56:59], v[160:163], v[156:159]
	v_mfma_f32_16x16x32_bf16 v[152:155], v[64:67], v[160:163], v[152:155]
	v_mfma_f32_16x16x32_bf16 v[140:143], v[56:59], v[168:171], v[140:143]
	v_mfma_f32_16x16x32_bf16 v[136:139], v[64:67], v[168:171], v[136:139]
	v_mfma_f32_16x16x32_bf16 v[124:127], v[56:59], v[190:193], v[124:127]
	v_mfma_f32_16x16x32_bf16 v[120:123], v[64:67], v[190:193], v[120:123]
	v_mfma_f32_16x16x32_bf16 v[108:111], v[56:59], v[198:201], v[108:111]
	v_mfma_f32_16x16x32_bf16 v[104:107], v[64:67], v[198:201], v[104:107]
	v_mfma_f32_16x16x32_bf16 v[156:159], v[60:63], v[164:167], v[156:159]
	v_mfma_f32_16x16x32_bf16 v[152:155], v[68:71], v[164:167], v[152:155]
	v_mfma_f32_16x16x32_bf16 v[140:143], v[60:63], v[172:175], v[140:143]
	v_mfma_f32_16x16x32_bf16 v[136:139], v[68:71], v[172:175], v[136:139]
	v_mfma_f32_16x16x32_bf16 v[124:127], v[60:63], v[194:197], v[124:127]
	v_mfma_f32_16x16x32_bf16 v[120:123], v[68:71], v[194:197], v[120:123]
	v_mfma_f32_16x16x32_bf16 v[108:111], v[60:63], v[202:205], v[108:111]
	v_mfma_f32_16x16x32_bf16 v[104:107], v[68:71], v[202:205], v[104:107]
	v_mfma_f32_16x16x32_bf16 v[148:151], v[72:75], v[160:163], v[148:151]
	v_mfma_f32_16x16x32_bf16 v[144:147], v[88:91], v[160:163], v[144:147]
	v_mfma_f32_16x16x32_bf16 v[132:135], v[72:75], v[168:171], v[132:135]
	v_mfma_f32_16x16x32_bf16 v[128:131], v[88:91], v[168:171], v[128:131]
	v_mfma_f32_16x16x32_bf16 v[116:119], v[72:75], v[190:193], v[116:119]
	v_mfma_f32_16x16x32_bf16 v[112:115], v[88:91], v[190:193], v[112:115]
	v_mfma_f32_16x16x32_bf16 v[100:103], v[72:75], v[198:201], v[100:103]
	v_mfma_f32_16x16x32_bf16 v[96:99], v[88:91], v[198:201], v[96:99]
	v_mfma_f32_16x16x32_bf16 v[148:151], v[76:79], v[164:167], v[148:151]
	v_mfma_f32_16x16x32_bf16 v[144:147], v[92:95], v[164:167], v[144:147]
	v_mfma_f32_16x16x32_bf16 v[132:135], v[76:79], v[172:175], v[132:135]
	v_mfma_f32_16x16x32_bf16 v[128:131], v[92:95], v[172:175], v[128:131]
	v_mfma_f32_16x16x32_bf16 v[116:119], v[76:79], v[194:197], v[116:119]
	v_mfma_f32_16x16x32_bf16 v[112:115], v[92:95], v[194:197], v[112:115]
	v_mfma_f32_16x16x32_bf16 v[100:103], v[76:79], v[202:205], v[100:103]
	v_mfma_f32_16x16x32_bf16 v[96:99], v[92:95], v[202:205], v[96:99]
	s_barrier
; #define PG8_STAGE(bufoff, gbase, voff) do { _Pragma("unroll") for (int _i = 0; _i < 2; ++_i) \
;         __builtin_amdgcn_global_load_lds((const unsigned*)((const char*)(gbase) + (voff)[_i]), (LAS unsigned*)(lds + (bufoff) + ldsw + _i * 8192), 16, 0, 0); } while (0)
; #define PG8_LDA(dst, b, h) do { _Pragma("unroll") for (int m = 0; m < 4; ++m) _Pragma("unroll") for (int k = 0; k < 2; ++k) dst[m][k] = *(const LAS bf16x8*)(lds + PG8_SA(b, h) + aoff + m * 2048 + k * 1024); } while (0)
; #define PG8_MMA(ai, bj, At, Bt) do { __builtin_amdgcn_s_setprio(1); _Pragma("unroll") for (int m = 0; m < 4; ++m) _Pragma("unroll") for (int n = 0; n < 2; ++n) _Pragma("unroll") for (int k = 0; k < 2; ++k) \
;         acc[ai][bj][m][n] = __builtin_amdgcn_mfma_f32_16x16x32_bf16(Bt[n][k], At[m][k], acc[ai][bj][m][n], 0, 0, 0); __builtin_amdgcn_s_setprio(0); } while (0)
; #define PG8_WAIT_V(n) asm volatile("s_waitcnt vmcnt(" #n ")" ::: "memory")
; #define PG8_WAIT_L(n) asm volatile("s_waitcnt lgkmcnt(" #n ")" ::: "memory")
; #define PG8_BAR __builtin_amdgcn_s_barrier()
; #define PG8_SCHED __builtin_amdgcn_sched_barrier(0)
; template <class Sched, class Epi, bool ALIGN_EPI, bool SP2>
; __device__ __forceinline__ void gemm_phase(LAS unsigned char* lds, const int K, const int lda, const int ldb, const Sched& S, const Epi& E) {
;     ...
;             PG8_LDA(At, 1, 1); PG8_STAGE(PG8_SB(1, 0), b3, voffB); PG8_STAGE(PG8_SB(1, 1), b3 + hstepB, voffB); PG8_STAGE(PG8_SA(1, 0), a3, voffA);
;             PG8_WAIT_V(8); PG8_WAIT_L(0); PG8_BAR; PG8_MMA(1, 0, At, B0); PG8_MMA(1, 1, At, B1); PG8_BAR; PG8_SCHED;
	s_add_i32 s44, s62, s19
	v_lshl_add_u64 v[206:207], v[206:207], 0, s[14:15]
	s_mov_b32 m0, s44
	ds_read_b128 v[160:163], v211 offset:49152
	ds_read_b128 v[164:167], v211 offset:50176
	ds_read_b128 v[168:171], v211 offset:51200
	ds_read_b128 v[172:175], v211 offset:52224
	ds_read_b128 v[190:193], v211 offset:53248
	ds_read_b128 v[194:197], v211 offset:54272
	ds_read_b128 v[198:201], v211 offset:55296
	ds_read_b128 v[202:205], v211 offset:56320
	global_load_lds_dwordx4 v[206:207], off
	s_add_i32 m0, s44, 0x2000
	s_add_u32 s42, s42, 0x80080
	v_lshl_add_u64 v[206:207], v[214:215], 0, s[14:15]
	s_addc_u32 s43, s43, 0
	s_add_i32 s44, s63, s19
	global_load_lds_dwordx4 v[206:207], off
	v_lshl_add_u64 v[206:207], s[42:43], 0, v[182:183]
	s_mov_b32 m0, s44
	s_nop 0
	global_load_lds_dwordx4 v[206:207], off
	v_lshl_add_u64 v[206:207], s[42:43], 0, v[184:185]
	s_add_i32 m0, s44, 0x2000
	s_nop 0
	global_load_lds_dwordx4 v[206:207], off
	v_lshl_add_u64 v[206:207], v[216:217], 0, s[14:15]
	s_mov_b32 m0, s48
	s_nop 0
	global_load_lds_dwordx4 v[206:207], off
	v_lshl_add_u64 v[206:207], v[218:219], 0, s[14:15]
	s_mov_b32 m0, s49
	s_nop 0
	global_load_lds_dwordx4 v[206:207], off
	s_waitcnt vmcnt(8) lgkmcnt(0)
	s_barrier
	v_mfma_f32_16x16x32_bf16 v[84:87], v[56:59], v[160:163], v[84:87]
	v_mfma_f32_16x16x32_bf16 v[80:83], v[64:67], v[160:163], v[80:83]
	v_mfma_f32_16x16x32_bf16 v[44:47], v[56:59], v[168:171], v[44:47]
	v_mfma_f32_16x16x32_bf16 v[40:43], v[64:67], v[168:171], v[40:43]
	v_mfma_f32_16x16x32_bf16 v[28:31], v[56:59], v[190:193], v[28:31]
	v_mfma_f32_16x16x32_bf16 v[24:27], v[64:67], v[190:193], v[24:27]
	v_mfma_f32_16x16x32_bf16 v[12:15], v[56:59], v[198:201], v[12:15]
	v_mfma_f32_16x16x32_bf16 v[8:11], v[64:67], v[198:201], v[8:11]
	v_mfma_f32_16x16x32_bf16 v[84:87], v[60:63], v[164:167], v[84:87]
	v_mfma_f32_16x16x32_bf16 v[80:83], v[68:71], v[164:167], v[80:83]
	v_mfma_f32_16x16x32_bf16 v[44:47], v[60:63], v[172:175], v[44:47]
	v_mfma_f32_16x16x32_bf16 v[40:43], v[68:71], v[172:175], v[40:43]
	v_mfma_f32_16x16x32_bf16 v[28:31], v[60:63], v[194:197], v[28:31]
	v_mfma_f32_16x16x32_bf16 v[24:27], v[68:71], v[194:197], v[24:27]
	v_mfma_f32_16x16x32_bf16 v[12:15], v[60:63], v[202:205], v[12:15]
	v_mfma_f32_16x16x32_bf16 v[8:11], v[68:71], v[202:205], v[8:11]
	v_mfma_f32_16x16x32_bf16 v[52:55], v[72:75], v[160:163], v[52:55]
	v_mfma_f32_16x16x32_bf16 v[48:51], v[88:91], v[160:163], v[48:51]
	v_mfma_f32_16x16x32_bf16 v[36:39], v[72:75], v[168:171], v[36:39]
	v_mfma_f32_16x16x32_bf16 v[32:35], v[88:91], v[168:171], v[32:35]
	v_mfma_f32_16x16x32_bf16 v[20:23], v[72:75], v[190:193], v[20:23]
	v_mfma_f32_16x16x32_bf16 v[16:19], v[88:91], v[190:193], v[16:19]
	v_mfma_f32_16x16x32_bf16 v[4:7], v[72:75], v[198:201], v[4:7]
	v_mfma_f32_16x16x32_bf16 v[0:3], v[88:91], v[198:201], v[0:3]
	v_mfma_f32_16x16x32_bf16 v[60:63], v[76:79], v[164:167], v[52:55]
	v_mfma_f32_16x16x32_bf16 v[48:51], v[92:95], v[164:167], v[48:51]
	v_mfma_f32_16x16x32_bf16 v[36:39], v[76:79], v[172:175], v[36:39]
	v_mfma_f32_16x16x32_bf16 v[32:35], v[92:95], v[172:175], v[32:35]
	v_mfma_f32_16x16x32_bf16 v[20:23], v[76:79], v[194:197], v[20:23]
	v_mfma_f32_16x16x32_bf16 v[16:19], v[92:95], v[194:197], v[16:19]
	v_mfma_f32_16x16x32_bf16 v[4:7], v[76:79], v[202:205], v[4:7]
	v_mfma_f32_16x16x32_bf16 v[0:3], v[92:95], v[202:205], v[0:3]
	s_barrier
	s_add_i32 s61, s61, 2
	s_add_u32 s36, s36, 0x100
	s_addc_u32 s37, s37, 0
	s_add_u32 s1, s1, 0x100
	s_addc_u32 s25, s25, 0
	s_cmp_gt_u32 s61, 29
	s_cbranch_scc0 .LBB0_945
	s_setprio 0
	s_and_b64 vcc, exec, s[16:17]
	s_cbranch_vccz .LBB0_948
	s_barrier

; #define PG8_STAGE(bufoff, gbase, voff) do { _Pragma("unroll") for (int _i = 0; _i < 2; ++_i) \
;         __builtin_amdgcn_global_load_lds((const unsigned*)((const char*)(gbase) + (voff)[_i]), (LAS unsigned*)(lds + (bufoff) + ldsw + _i * 8192), 16, 0, 0); } while (0)
; #define PG8_LDA(dst, b, h) do { _Pragma("unroll") for (int m = 0; m < 4; ++m) _Pragma("unroll") for (int k = 0; k < 2; ++k) dst[m][k] = *(const LAS bf16x8*)(lds + PG8_SA(b, h) + aoff + m * 2048 + k * 1024); } while (0)
; #define PG8_LDB(dst, b, h) do { _Pragma("unroll") for (int n = 0; n < 2; ++n) _Pragma("unroll") for (int k = 0; k < 2; ++k) dst[n][k] = *(const LAS bf16x8*)(lds + PG8_SB(b, h) + boff + n * 2048 + k * 1024); } while (0)
; #define PG8_MMA(ai, bj, At, Bt) do { __builtin_amdgcn_s_setprio(1); _Pragma("unroll") for (int m = 0; m < 4; ++m) _Pragma("unroll") for (int n = 0; n < 2; ++n) _Pragma("unroll") for (int k = 0; k < 2; ++k) \
;         acc[ai][bj][m][n] = __builtin_amdgcn_mfma_f32_16x16x32_bf16(Bt[n][k], At[m][k], acc[ai][bj][m][n], 0, 0, 0); __builtin_amdgcn_s_setprio(0); } while (0)
; #define PG8_WAIT_V(n) asm volatile("s_waitcnt vmcnt(" #n ")" ::: "memory")
; #define PG8_WAIT_L(n) asm volatile("s_waitcnt lgkmcnt(" #n ")" ::: "memory")
; #define PG8_BAR __builtin_amdgcn_s_barrier()
; #define PG8_SCHED __builtin_amdgcn_sched_barrier(0)
; template <class Sched, class Epi, bool ALIGN_EPI, bool SP2>
; __device__ __forceinline__ void gemm_phase(LAS unsigned char* lds, const int K, const int lda, const int ldb, const Sched& S, const Epi& E) {
;     ...
;         for (int t = 0; t < nt; t += 2) {
;             const bool last = (t == nt - 2);
;             const char* a1 = cA + (size_t)(t + 1) * kstep;
;             const char* a2 = last ? nA : cA + (size_t)(t + 2) * kstep; const char* b2 = last ? nB : cB + (size_t)(t + 2) * kstep;
;             const char* a3 = a2 + kstep; const char* b3 = b2 + kstep;
;             if constexpr (SP2) {
;             PG8_LDB(B0, 0, 0); PG8_LDB(B1, 0, 1); PG8_SCHED; PG8_LDA(At, 0, 0); PG8_STAGE(PG8_SA(1, 1), a1 + hstepA, voffA);
;             PG8_WAIT_V(8); PG8_WAIT_L(0); PG8_BAR; PG8_MMA(0, 0, At, B0); PG8_MMA(0, 1, At, B1); PG8_BAR; PG8_SCHED;
;             PG8_LDA(At, 0, 1); PG8_STAGE(PG8_SB(0, 0), b2, voffB); PG8_STAGE(PG8_SB(0, 1), b2 + hstepB, voffB); PG8_STAGE(PG8_SA(0, 0), a2, voffA);
.Lprio_skip_1037:
.LBB0_1037:
	ds_read_b128 v[64:67], v183
	ds_read_b128 v[68:71], v183 offset:1024
	ds_read_b128 v[72:75], v183 offset:2048
	ds_read_b128 v[76:79], v183 offset:3072
	ds_read_b128 v[144:147], v184
	ds_read_b128 v[160:163], v184 offset:1024
	ds_read_b128 v[164:167], v184 offset:2048
	ds_read_b128 v[168:171], v184 offset:3072
	s_add_u32 s42, s36, 0xfff80080
	s_addc_u32 s43, s37, -1
	s_cmp_eq_u32 s57, 28
	s_cselect_b32 s45, s27, s43
	s_cselect_b32 s44, s26, s42
	s_cselect_b32 s43, s29, s56
	s_cselect_b32 s42, s28, s25
	v_lshl_add_u64 v[216:217], s[36:37], 0, v[156:157]
	s_add_i32 m0, s33, 0xc000
	ds_read_b128 v[172:175], v185
	ds_read_b128 v[188:191], v185 offset:1024
	ds_read_b128 v[192:195], v185 offset:2048
	ds_read_b128 v[196:199], v185 offset:3072
	ds_read_b128 v[200:203], v185 offset:4096
	ds_read_b128 v[204:207], v185 offset:5120
	ds_read_b128 v[208:211], v185 offset:6144
	ds_read_b128 v[212:215], v185 offset:7168
	global_load_lds_dwordx4 v[216:217], off
	v_lshl_add_u64 v[216:217], s[36:37], 0, v[158:159]
	s_add_i32 m0, s33, 0xe000
	s_nop 0
	global_load_lds_dwordx4 v[216:217], off
	s_waitcnt vmcnt(8) lgkmcnt(0)
	s_barrier
	v_mfma_f32_16x16x32_bf16 v[140:143], v[64:67], v[172:175], v[140:143]
	v_mfma_f32_16x16x32_bf16 v[136:139], v[72:75], v[172:175], v[136:139]
	v_mfma_f32_16x16x32_bf16 v[124:127], v[64:67], v[192:195], v[124:127]
	v_mfma_f32_16x16x32_bf16 v[120:123], v[72:75], v[192:195], v[120:123]
	v_mfma_f32_16x16x32_bf16 v[108:111], v[64:67], v[200:203], v[108:111]
	v_mfma_f32_16x16x32_bf16 v[104:107], v[72:75], v[200:203], v[104:107]
	v_mfma_f32_16x16x32_bf16 v[92:95], v[64:67], v[208:211], v[92:95]
	v_mfma_f32_16x16x32_bf16 v[88:91], v[72:75], v[208:211], v[88:91]
	v_mfma_f32_16x16x32_bf16 v[140:143], v[68:71], v[188:191], v[140:143]
	v_mfma_f32_16x16x32_bf16 v[136:139], v[76:79], v[188:191], v[136:139]
	v_mfma_f32_16x16x32_bf16 v[124:127], v[68:71], v[196:199], v[124:127]
	v_mfma_f32_16x16x32_bf16 v[120:123], v[76:79], v[196:199], v[120:123]
	v_mfma_f32_16x16x32_bf16 v[108:111], v[68:71], v[204:207], v[108:111]
	v_mfma_f32_16x16x32_bf16 v[104:107], v[76:79], v[204:207], v[104:107]
	v_mfma_f32_16x16x32_bf16 v[92:95], v[68:71], v[212:215], v[92:95]
	v_mfma_f32_16x16x32_bf16 v[88:91], v[76:79], v[212:215], v[88:91]
	v_mfma_f32_16x16x32_bf16 v[132:135], v[144:147], v[172:175], v[132:135]
	v_mfma_f32_16x16x32_bf16 v[128:131], v[164:167], v[172:175], v[128:131]
	v_mfma_f32_16x16x32_bf16 v[116:119], v[144:147], v[192:195], v[116:119]
	v_mfma_f32_16x16x32_bf16 v[112:115], v[164:167], v[192:195], v[112:115]
	v_mfma_f32_16x16x32_bf16 v[100:103], v[144:147], v[200:203], v[100:103]
	v_mfma_f32_16x16x32_bf16 v[96:99], v[164:167], v[200:203], v[96:99]
	v_mfma_f32_16x16x32_bf16 v[84:87], v[144:147], v[208:211], v[84:87]
	v_mfma_f32_16x16x32_bf16 v[80:83], v[164:167], v[208:211], v[80:83]
	v_mfma_f32_16x16x32_bf16 v[132:135], v[160:163], v[188:191], v[132:135]
	v_mfma_f32_16x16x32_bf16 v[128:131], v[168:171], v[188:191], v[128:131]
	v_mfma_f32_16x16x32_bf16 v[116:119], v[160:163], v[196:199], v[116:119]
	v_mfma_f32_16x16x32_bf16 v[112:115], v[168:171], v[196:199], v[112:115]
	v_mfma_f32_16x16x32_bf16 v[100:103], v[160:163], v[204:207], v[100:103]
	v_mfma_f32_16x16x32_bf16 v[96:99], v[168:171], v[204:207], v[96:99]
	v_mfma_f32_16x16x32_bf16 v[84:87], v[160:163], v[212:215], v[84:87]
	v_mfma_f32_16x16x32_bf16 v[80:83], v[168:171], v[212:215], v[80:83]
	s_barrier
	s_add_i32 s58, s51, s21
	v_lshl_add_u64 v[216:217], s[42:43], 0, v[150:151]
	s_mov_b32 m0, s58
	ds_read_b128 v[172:175], v185 offset:16384
	ds_read_b128 v[188:191], v185 offset:17408
	ds_read_b128 v[192:195], v185 offset:18432
	ds_read_b128 v[196:199], v185 offset:19456
	ds_read_b128 v[200:203], v185 offset:20480
	ds_read_b128 v[204:207], v185 offset:21504
	ds_read_b128 v[208:211], v185 offset:22528
	ds_read_b128 v[212:215], v185 offset:23552
	global_load_lds_dwordx4 v[216:217], off
	s_add_i32 m0, s58, 0x2000
	s_add_u32 s58, s42, 0x80000
	v_lshl_add_u64 v[218:219], s[42:43], 0, v[154:155]
	s_addc_u32 s59, s43, 0
	s_add_i32 s60, s52, s21
	global_load_lds_dwordx4 v[218:219], off
	v_lshl_add_u64 v[220:221], s[58:59], 0, v[150:151]
	s_mov_b32 m0, s60
	v_lshl_add_u64 v[222:223], s[44:45], 0, v[152:153]
	global_load_lds_dwordx4 v[220:221], off
	v_lshl_add_u64 v[220:221], s[58:59], 0, v[154:155]
	s_add_i32 m0, s60, 0x2000
	s_nop 0
	global_load_lds_dwordx4 v[220:221], off
	v_lshl_add_u64 v[220:221], s[44:45], 0, v[148:149]
	s_mov_b32 m0, s33
	s_nop 0
	global_load_lds_dwordx4 v[220:221], off
	s_mov_b32 m0, s35
	s_nop 0
	global_load_lds_dwordx4 v[222:223], off
	s_waitcnt vmcnt(8) lgkmcnt(0)
	s_barrier
; #define PG8_STAGE(bufoff, gbase, voff) do { _Pragma("unroll") for (int _i = 0; _i < 2; ++_i) \
;         __builtin_amdgcn_global_load_lds((const unsigned*)((const char*)(gbase) + (voff)[_i]), (LAS unsigned*)(lds + (bufoff) + ldsw + _i * 8192), 16, 0, 0); } while (0)
; #define PG8_LDA(dst, b, h) do { _Pragma("unroll") for (int m = 0; m < 4; ++m) _Pragma("unroll") for (int k = 0; k < 2; ++k) dst[m][k] = *(const LAS bf16x8*)(lds + PG8_SA(b, h) + aoff + m * 2048 + k * 1024); } while (0)
; #define PG8_LDB(dst, b, h) do { _Pragma("unroll") for (int n = 0; n < 2; ++n) _Pragma("unroll") for (int k = 0; k < 2; ++k) dst[n][k] = *(const LAS bf16x8*)(lds + PG8_SB(b, h) + boff + n * 2048 + k * 1024); } while (0)
; #define PG8_MMA(ai, bj, At, Bt) do { __builtin_amdgcn_s_setprio(1); _Pragma("unroll") for (int m = 0; m < 4; ++m) _Pragma("unroll") for (int n = 0; n < 2; ++n) _Pragma("unroll") for (int k = 0; k < 2; ++k) \
;         acc[ai][bj][m][n] = __builtin_amdgcn_mfma_f32_16x16x32_bf16(Bt[n][k], At[m][k], acc[ai][bj][m][n], 0, 0, 0); __builtin_amdgcn_s_setprio(0); } while (0)
; #define PG8_WAIT_V(n) asm volatile("s_waitcnt vmcnt(" #n ")" ::: "memory")
; #define PG8_WAIT_L(n) asm volatile("s_waitcnt lgkmcnt(" #n ")" ::: "memory")
; #define PG8_BAR __builtin_amdgcn_s_barrier()
; #define PG8_SCHED __builtin_amdgcn_sched_barrier(0)
; template <class Sched, class Epi, bool ALIGN_EPI, bool SP2>
; __device__ __forceinline__ void gemm_phase(LAS unsigned char* lds, const int K, const int lda, const int ldb, const Sched& S, const Epi& E) {
;     ...
;             PG8_WAIT_V(8); PG8_WAIT_L(0); PG8_BAR; PG8_MMA(1, 0, At, B0); PG8_MMA(1, 1, At, B1); PG8_BAR; PG8_SCHED;
;             PG8_LDB(B0, 1, 0); PG8_LDB(B1, 1, 1); PG8_SCHED; PG8_LDA(At, 1, 0); PG8_STAGE(PG8_SA(0, 1), a2 + hstepA, voffA);
;             PG8_WAIT_V(8); PG8_WAIT_L(0); PG8_BAR; PG8_MMA(0, 0, At, B0); PG8_MMA(0, 1, At, B1); PG8_BAR; PG8_SCHED;
	v_mfma_f32_16x16x32_bf16 v[60:63], v[64:67], v[172:175], v[60:63]
	v_mfma_f32_16x16x32_bf16 v[56:59], v[72:75], v[172:175], v[56:59]
	v_mfma_f32_16x16x32_bf16 v[44:47], v[64:67], v[192:195], v[44:47]
	v_mfma_f32_16x16x32_bf16 v[40:43], v[72:75], v[192:195], v[40:43]
	v_mfma_f32_16x16x32_bf16 v[24:27], v[64:67], v[200:203], v[24:27]
	v_mfma_f32_16x16x32_bf16 v[20:23], v[72:75], v[200:203], v[20:23]
	v_mfma_f32_16x16x32_bf16 v[8:11], v[64:67], v[208:211], v[8:11]
	v_mfma_f32_16x16x32_bf16 v[0:3], v[72:75], v[208:211], v[0:3]
	v_mfma_f32_16x16x32_bf16 v[60:63], v[68:71], v[188:191], v[60:63]
	v_mfma_f32_16x16x32_bf16 v[56:59], v[76:79], v[188:191], v[56:59]
	v_mfma_f32_16x16x32_bf16 v[44:47], v[68:71], v[196:199], v[44:47]
	v_mfma_f32_16x16x32_bf16 v[40:43], v[76:79], v[196:199], v[40:43]
	v_mfma_f32_16x16x32_bf16 v[24:27], v[68:71], v[204:207], v[24:27]
	v_mfma_f32_16x16x32_bf16 v[20:23], v[76:79], v[204:207], v[20:23]
	v_mfma_f32_16x16x32_bf16 v[8:11], v[68:71], v[212:215], v[8:11]
	v_mfma_f32_16x16x32_bf16 v[0:3], v[76:79], v[212:215], v[0:3]
	v_mfma_f32_16x16x32_bf16 v[52:55], v[144:147], v[172:175], v[52:55]
	v_mfma_f32_16x16x32_bf16 v[48:51], v[164:167], v[172:175], v[48:51]
	v_mfma_f32_16x16x32_bf16 v[36:39], v[144:147], v[192:195], v[36:39]
	v_mfma_f32_16x16x32_bf16 v[32:35], v[164:167], v[192:195], v[32:35]
	v_mfma_f32_16x16x32_bf16 v[28:31], v[144:147], v[200:203], v[28:31]
	v_mfma_f32_16x16x32_bf16 v[16:19], v[164:167], v[200:203], v[16:19]
	v_mfma_f32_16x16x32_bf16 v[12:15], v[144:147], v[208:211], v[12:15]
	v_mfma_f32_16x16x32_bf16 v[4:7], v[164:167], v[208:211], v[4:7]
	v_mfma_f32_16x16x32_bf16 v[52:55], v[160:163], v[188:191], v[52:55]
	v_mfma_f32_16x16x32_bf16 v[48:51], v[168:171], v[188:191], v[48:51]
	v_mfma_f32_16x16x32_bf16 v[36:39], v[160:163], v[196:199], v[36:39]
	v_mfma_f32_16x16x32_bf16 v[32:35], v[168:171], v[196:199], v[32:35]
	v_mfma_f32_16x16x32_bf16 v[28:31], v[160:163], v[204:207], v[28:31]
	v_mfma_f32_16x16x32_bf16 v[16:19], v[168:171], v[204:207], v[16:19]
	v_mfma_f32_16x16x32_bf16 v[12:15], v[160:163], v[212:215], v[12:15]
	v_mfma_f32_16x16x32_bf16 v[4:7], v[168:171], v[212:215], v[4:7]
	s_barrier
	s_add_i32 s58, 0, 0x18000
	s_add_i32 s59, 0, 0x1c000
	v_add_u32_e32 v76, s58, v181
	v_add_u32_e32 v168, s59, v181
	ds_read_b128 v[64:67], v76
	ds_read_b128 v[68:71], v76 offset:1024
	ds_read_b128 v[72:75], v76 offset:2048
	ds_read_b128 v[76:79], v76 offset:3072
	ds_read_b128 v[144:147], v168
	ds_read_b128 v[160:163], v168 offset:1024
	ds_read_b128 v[164:167], v168 offset:2048
	ds_read_b128 v[168:171], v168 offset:3072
	s_add_u32 s44, s44, 0x80000
	s_addc_u32 s45, s45, 0
	s_mov_b32 m0, s46
	v_lshl_add_u64 v[224:225], s[44:45], 0, v[148:149]
	ds_read_b128 v[172:175], v185 offset:32768
	ds_read_b128 v[188:191], v185 offset:33792
	ds_read_b128 v[192:195], v185 offset:34816
	ds_read_b128 v[196:199], v185 offset:35840
	ds_read_b128 v[200:203], v185 offset:36864
	ds_read_b128 v[204:207], v185 offset:37888
	ds_read_b128 v[208:211], v185 offset:38912
	ds_read_b128 v[212:215], v185 offset:39936
	global_load_lds_dwordx4 v[224:225], off
	v_lshl_add_u64 v[224:225], s[44:45], 0, v[152:153]
	s_mov_b32 m0, s47
	s_nop 0
	global_load_lds_dwordx4 v[224:225], off
	s_waitcnt vmcnt(8) lgkmcnt(0)
	s_barrier
	v_mfma_f32_16x16x32_bf16 v[140:143], v[64:67], v[172:175], v[140:143]
	v_mfma_f32_16x16x32_bf16 v[136:139], v[72:75], v[172:175], v[136:139]
	v_mfma_f32_16x16x32_bf16 v[124:127], v[64:67], v[192:195], v[124:127]
	v_mfma_f32_16x16x32_bf16 v[120:123], v[72:75], v[192:195], v[120:123]
	v_mfma_f32_16x16x32_bf16 v[108:111], v[64:67], v[200:203], v[108:111]
	v_mfma_f32_16x16x32_bf16 v[104:107], v[72:75], v[200:203], v[104:107]
	v_mfma_f32_16x16x32_bf16 v[92:95], v[64:67], v[208:211], v[92:95]
	v_mfma_f32_16x16x32_bf16 v[88:91], v[72:75], v[208:211], v[88:91]
	v_mfma_f32_16x16x32_bf16 v[140:143], v[68:71], v[188:191], v[140:143]
	v_mfma_f32_16x16x32_bf16 v[136:139], v[76:79], v[188:191], v[136:139]
	v_mfma_f32_16x16x32_bf16 v[124:127], v[68:71], v[196:199], v[124:127]
	v_mfma_f32_16x16x32_bf16 v[120:123], v[76:79], v[196:199], v[120:123]
	v_mfma_f32_16x16x32_bf16 v[108:111], v[68:71], v[204:207], v[108:111]
	v_mfma_f32_16x16x32_bf16 v[104:107], v[76:79], v[204:207], v[104:107]
	v_mfma_f32_16x16x32_bf16 v[92:95], v[68:71], v[212:215], v[92:95]
	v_mfma_f32_16x16x32_bf16 v[88:91], v[76:79], v[212:215], v[88:91]
	v_mfma_f32_16x16x32_bf16 v[132:135], v[144:147], v[172:175], v[132:135]
	v_mfma_f32_16x16x32_bf16 v[128:131], v[164:167], v[172:175], v[128:131]
	v_mfma_f32_16x16x32_bf16 v[116:119], v[144:147], v[192:195], v[116:119]
	v_mfma_f32_16x16x32_bf16 v[112:115], v[164:167], v[192:195], v[112:115]
	v_mfma_f32_16x16x32_bf16 v[100:103], v[144:147], v[200:203], v[100:103]
	v_mfma_f32_16x16x32_bf16 v[96:99], v[164:167], v[200:203], v[96:99]
	v_mfma_f32_16x16x32_bf16 v[84:87], v[144:147], v[208:211], v[84:87]
	v_mfma_f32_16x16x32_bf16 v[80:83], v[164:167], v[208:211], v[80:83]
	v_mfma_f32_16x16x32_bf16 v[132:135], v[160:163], v[188:191], v[132:135]
	v_mfma_f32_16x16x32_bf16 v[128:131], v[168:171], v[188:191], v[128:131]
	v_mfma_f32_16x16x32_bf16 v[116:119], v[160:163], v[196:199], v[116:119]
	v_mfma_f32_16x16x32_bf16 v[112:115], v[168:171], v[196:199], v[112:115]
	v_mfma_f32_16x16x32_bf16 v[100:103], v[160:163], v[204:207], v[100:103]
	v_mfma_f32_16x16x32_bf16 v[96:99], v[168:171], v[204:207], v[96:99]
	v_mfma_f32_16x16x32_bf16 v[84:87], v[160:163], v[212:215], v[84:87]
	v_mfma_f32_16x16x32_bf16 v[80:83], v[168:171], v[212:215], v[80:83]
	s_barrier
; #define PG8_STAGE(bufoff, gbase, voff) do { _Pragma("unroll") for (int _i = 0; _i < 2; ++_i) \
;         __builtin_amdgcn_global_load_lds((const unsigned*)((const char*)(gbase) + (voff)[_i]), (LAS unsigned*)(lds + (bufoff) + ldsw + _i * 8192), 16, 0, 0); } while (0)
; #define PG8_LDA(dst, b, h) do { _Pragma("unroll") for (int m = 0; m < 4; ++m) _Pragma("unroll") for (int k = 0; k < 2; ++k) dst[m][k] = *(const LAS bf16x8*)(lds + PG8_SA(b, h) + aoff + m * 2048 + k * 1024); } while (0)
; #define PG8_MMA(ai, bj, At, Bt) do { __builtin_amdgcn_s_setprio(1); _Pragma("unroll") for (int m = 0; m < 4; ++m) _Pragma("unroll") for (int n = 0; n < 2; ++n) _Pragma("unroll") for (int k = 0; k < 2; ++k) \
;         acc[ai][bj][m][n] = __builtin_amdgcn_mfma_f32_16x16x32_bf16(Bt[n][k], At[m][k], acc[ai][bj][m][n], 0, 0, 0); __builtin_amdgcn_s_setprio(0); } while (0)
; #define PG8_WAIT_V(n) asm volatile("s_waitcnt vmcnt(" #n ")" ::: "memory")
; #define PG8_WAIT_L(n) asm volatile("s_waitcnt lgkmcnt(" #n ")" ::: "memory")
; #define PG8_BAR __builtin_amdgcn_s_barrier()
; #define PG8_SCHED __builtin_amdgcn_sched_barrier(0)
; template <class Sched, class Epi, bool ALIGN_EPI, bool SP2>
; __device__ __forceinline__ void gemm_phase(LAS unsigned char* lds, const int K, const int lda, const int ldb, const Sched& S, const Epi& E) {
;     ...
;             PG8_LDA(At, 1, 1); PG8_STAGE(PG8_SB(1, 0), b3, voffB); PG8_STAGE(PG8_SB(1, 1), b3 + hstepB, voffB); PG8_STAGE(PG8_SA(1, 0), a3, voffA);
;             PG8_WAIT_V(8); PG8_WAIT_L(0); PG8_BAR; PG8_MMA(1, 0, At, B0); PG8_MMA(1, 1, At, B1); PG8_BAR; PG8_SCHED;
	s_add_i32 s44, s58, s21
	v_lshl_add_u64 v[216:217], v[216:217], 0, s[14:15]
	s_mov_b32 m0, s44
	ds_read_b128 v[172:175], v185 offset:49152
	ds_read_b128 v[188:191], v185 offset:50176
	ds_read_b128 v[192:195], v185 offset:51200
	ds_read_b128 v[196:199], v185 offset:52224
	ds_read_b128 v[200:203], v185 offset:53248
	ds_read_b128 v[204:207], v185 offset:54272
	ds_read_b128 v[208:211], v185 offset:55296
	ds_read_b128 v[212:215], v185 offset:56320
	global_load_lds_dwordx4 v[216:217], off
	s_add_i32 m0, s44, 0x2000
	s_add_u32 s42, s42, 0x80080
	v_lshl_add_u64 v[216:217], v[218:219], 0, s[14:15]
	s_addc_u32 s43, s43, 0
	s_add_i32 s44, s59, s21
	global_load_lds_dwordx4 v[216:217], off
	v_lshl_add_u64 v[216:217], s[42:43], 0, v[150:151]
	s_mov_b32 m0, s44
	s_nop 0
	global_load_lds_dwordx4 v[216:217], off
	v_lshl_add_u64 v[216:217], s[42:43], 0, v[154:155]
	s_add_i32 m0, s44, 0x2000
	s_nop 0
	global_load_lds_dwordx4 v[216:217], off
	v_lshl_add_u64 v[216:217], v[220:221], 0, s[14:15]
	s_mov_b32 m0, s49
	s_nop 0
	global_load_lds_dwordx4 v[216:217], off
	v_lshl_add_u64 v[216:217], v[222:223], 0, s[14:15]
	s_mov_b32 m0, s50
	s_nop 0
	global_load_lds_dwordx4 v[216:217], off
	s_waitcnt vmcnt(8) lgkmcnt(0)
	s_barrier
	v_mfma_f32_16x16x32_bf16 v[60:63], v[64:67], v[172:175], v[60:63]
	v_mfma_f32_16x16x32_bf16 v[56:59], v[72:75], v[172:175], v[56:59]
	v_mfma_f32_16x16x32_bf16 v[44:47], v[64:67], v[192:195], v[44:47]
	v_mfma_f32_16x16x32_bf16 v[40:43], v[72:75], v[192:195], v[40:43]
	v_mfma_f32_16x16x32_bf16 v[24:27], v[64:67], v[200:203], v[24:27]
	v_mfma_f32_16x16x32_bf16 v[20:23], v[72:75], v[200:203], v[20:23]
	v_mfma_f32_16x16x32_bf16 v[8:11], v[64:67], v[208:211], v[8:11]
	v_mfma_f32_16x16x32_bf16 v[0:3], v[72:75], v[208:211], v[0:3]
	v_mfma_f32_16x16x32_bf16 v[60:63], v[68:71], v[188:191], v[60:63]
	v_mfma_f32_16x16x32_bf16 v[56:59], v[76:79], v[188:191], v[56:59]
	v_mfma_f32_16x16x32_bf16 v[44:47], v[68:71], v[196:199], v[44:47]
	v_mfma_f32_16x16x32_bf16 v[40:43], v[76:79], v[196:199], v[40:43]
	v_mfma_f32_16x16x32_bf16 v[24:27], v[68:71], v[204:207], v[24:27]
	v_mfma_f32_16x16x32_bf16 v[20:23], v[76:79], v[204:207], v[20:23]
	v_mfma_f32_16x16x32_bf16 v[8:11], v[68:71], v[212:215], v[8:11]
	v_mfma_f32_16x16x32_bf16 v[0:3], v[76:79], v[212:215], v[0:3]
	v_mfma_f32_16x16x32_bf16 v[52:55], v[144:147], v[172:175], v[52:55]
	v_mfma_f32_16x16x32_bf16 v[48:51], v[164:167], v[172:175], v[48:51]
	v_mfma_f32_16x16x32_bf16 v[36:39], v[144:147], v[192:195], v[36:39]
	v_mfma_f32_16x16x32_bf16 v[32:35], v[164:167], v[192:195], v[32:35]
	v_mfma_f32_16x16x32_bf16 v[28:31], v[144:147], v[200:203], v[28:31]
	v_mfma_f32_16x16x32_bf16 v[16:19], v[164:167], v[200:203], v[16:19]
	v_mfma_f32_16x16x32_bf16 v[12:15], v[144:147], v[208:211], v[12:15]
	v_mfma_f32_16x16x32_bf16 v[4:7], v[164:167], v[208:211], v[4:7]
	v_mfma_f32_16x16x32_bf16 v[52:55], v[160:163], v[188:191], v[52:55]
	v_mfma_f32_16x16x32_bf16 v[48:51], v[168:171], v[188:191], v[48:51]
	v_mfma_f32_16x16x32_bf16 v[36:39], v[160:163], v[196:199], v[36:39]
	v_mfma_f32_16x16x32_bf16 v[32:35], v[168:171], v[196:199], v[32:35]
	v_mfma_f32_16x16x32_bf16 v[28:31], v[160:163], v[204:207], v[28:31]
	v_mfma_f32_16x16x32_bf16 v[16:19], v[168:171], v[204:207], v[16:19]
	v_mfma_f32_16x16x32_bf16 v[12:15], v[160:163], v[212:215], v[12:15]
	v_mfma_f32_16x16x32_bf16 v[4:7], v[168:171], v[212:215], v[4:7]
	s_barrier
	s_add_i32 s57, s57, 2
	s_add_u32 s36, s36, 0x100
	s_addc_u32 s37, s37, 0
	s_add_u32 s25, s25, 0x100
	s_addc_u32 s56, s56, 0
	s_cmp_gt_u32 s57, 29
	s_cbranch_scc0 .LBB0_1037
	s_setprio 0
	s_and_b64 vcc, exec, s[16:17]
	s_mov_b32 s56, s62
	s_cbranch_vccz .LBB0_1040
	s_barrier

; #define PG8_STAGE(bufoff, gbase, voff) do { _Pragma("unroll") for (int _i = 0; _i < 2; ++_i) \
;         __builtin_amdgcn_global_load_lds((const unsigned*)((const char*)(gbase) + (voff)[_i]), (LAS unsigned*)(lds + (bufoff) + ldsw + _i * 8192), 16, 0, 0); } while (0)
; #define PG8_LDA(dst, b, h) do { _Pragma("unroll") for (int m = 0; m < 4; ++m) _Pragma("unroll") for (int k = 0; k < 2; ++k) dst[m][k] = *(const LAS bf16x8*)(lds + PG8_SA(b, h) + aoff + m * 2048 + k * 1024); } while (0)
; #define PG8_LDB(dst, b, h) do { _Pragma("unroll") for (int n = 0; n < 2; ++n) _Pragma("unroll") for (int k = 0; k < 2; ++k) dst[n][k] = *(const LAS bf16x8*)(lds + PG8_SB(b, h) + boff + n * 2048 + k * 1024); } while (0)
; #define PG8_MMA(ai, bj, At, Bt) do { __builtin_amdgcn_s_setprio(1); _Pragma("unroll") for (int m = 0; m < 4; ++m) _Pragma("unroll") for (int n = 0; n < 2; ++n) _Pragma("unroll") for (int k = 0; k < 2; ++k) \
;         acc[ai][bj][m][n] = __builtin_amdgcn_mfma_f32_16x16x32_bf16(Bt[n][k], At[m][k], acc[ai][bj][m][n], 0, 0, 0); __builtin_amdgcn_s_setprio(0); } while (0)
; #define PG8_WAIT_V(n) asm volatile("s_waitcnt vmcnt(" #n ")" ::: "memory")
; #define PG8_WAIT_L(n) asm volatile("s_waitcnt lgkmcnt(" #n ")" ::: "memory")
; #define PG8_BAR __builtin_amdgcn_s_barrier()
; #define PG8_SCHED __builtin_amdgcn_sched_barrier(0)
; template <class Sched, class Epi, bool ALIGN_EPI, bool SP2>
; __device__ __forceinline__ void gemm_phase(LAS unsigned char* lds, const int K, const int lda, const int ldb, const Sched& S, const Epi& E) {
;     ...
;         for (int t = 0; t < nt; t += 2) {
;             const bool last = (t == nt - 2);
;             const char* a1 = cA + (size_t)(t + 1) * kstep;
;             const char* a2 = last ? nA : cA + (size_t)(t + 2) * kstep; const char* b2 = last ? nB : cB + (size_t)(t + 2) * kstep;
;             const char* a3 = a2 + kstep; const char* b3 = b2 + kstep;
;             if constexpr (SP2) {
;             PG8_LDB(B0, 0, 0); PG8_LDB(B1, 0, 1); PG8_SCHED; PG8_LDA(At, 0, 0); PG8_STAGE(PG8_SA(1, 1), a1 + hstepA, voffA);
;             PG8_WAIT_V(8); PG8_WAIT_L(0); PG8_BAR; PG8_MMA(0, 0, At, B0); PG8_MMA(0, 1, At, B1); PG8_BAR; PG8_SCHED;
;             PG8_LDA(At, 0, 1); PG8_STAGE(PG8_SB(0, 0), b2, voffB); PG8_STAGE(PG8_SB(0, 1), b2 + hstepB, voffB); PG8_STAGE(PG8_SA(0, 0), a2, voffA);
.Lprio_skip_1120:
.LBB0_1120:
	ds_read_b128 v[96:99], v178
	ds_read_b128 v[100:103], v178 offset:1024
	ds_read_b128 v[104:107], v178 offset:2048
	ds_read_b128 v[108:111], v178 offset:3072
	ds_read_b128 v[112:115], v180
	ds_read_b128 v[116:119], v180 offset:1024
	ds_read_b128 v[120:123], v180 offset:2048
	ds_read_b128 v[124:127], v180 offset:3072
	s_add_u32 s4, s0, 0x100
	s_addc_u32 s5, s1, 0
	s_cmpk_eq_i32 s51, 0x54
	s_cselect_b32 s27, s21, s5
	s_cselect_b32 s26, s20, s4
	s_cselect_b32 s25, s23, s50
	s_cselect_b32 s24, s22, s49
	v_lshl_add_u64 v[172:173], s[0:1], 0, v[164:165]
	s_add_i32 m0, s17, 0xc000
	ds_read_b128 v[168:171], v181
	ds_read_b128 v[184:187], v181 offset:1024
	ds_read_b128 v[188:191], v181 offset:2048
	ds_read_b128 v[192:195], v181 offset:3072
	ds_read_b128 v[196:199], v181 offset:4096
	ds_read_b128 v[200:203], v181 offset:5120
	ds_read_b128 v[204:207], v181 offset:6144
	ds_read_b128 v[208:211], v181 offset:7168
	global_load_lds_dwordx4 v[172:173], off
	v_lshl_add_u64 v[172:173], s[0:1], 0, v[166:167]
	s_add_i32 m0, s17, 0xe000
	s_nop 0
	global_load_lds_dwordx4 v[172:173], off
	s_waitcnt vmcnt(8) lgkmcnt(0)
	s_barrier
	v_mfma_f32_16x16x32_bf16 v[156:159], v[96:99], v[168:171], v[156:159]
	v_mfma_f32_16x16x32_bf16 v[152:155], v[104:107], v[168:171], v[152:155]
	v_mfma_f32_16x16x32_bf16 v[144:147], v[96:99], v[188:191], v[144:147]
	v_mfma_f32_16x16x32_bf16 v[136:139], v[104:107], v[188:191], v[136:139]
	v_mfma_f32_16x16x32_bf16 v[92:95], v[96:99], v[196:199], v[92:95]
	v_mfma_f32_16x16x32_bf16 v[88:91], v[104:107], v[196:199], v[88:91]
	v_mfma_f32_16x16x32_bf16 v[80:83], v[96:99], v[204:207], v[80:83]
	v_mfma_f32_16x16x32_bf16 v[72:75], v[104:107], v[204:207], v[72:75]
	v_mfma_f32_16x16x32_bf16 v[156:159], v[100:103], v[184:187], v[156:159]
	v_mfma_f32_16x16x32_bf16 v[152:155], v[108:111], v[184:187], v[152:155]
	v_mfma_f32_16x16x32_bf16 v[144:147], v[100:103], v[192:195], v[144:147]
	v_mfma_f32_16x16x32_bf16 v[136:139], v[108:111], v[192:195], v[136:139]
	v_mfma_f32_16x16x32_bf16 v[92:95], v[100:103], v[200:203], v[92:95]
	v_mfma_f32_16x16x32_bf16 v[88:91], v[108:111], v[200:203], v[88:91]
	v_mfma_f32_16x16x32_bf16 v[80:83], v[100:103], v[208:211], v[80:83]
	v_mfma_f32_16x16x32_bf16 v[72:75], v[108:111], v[208:211], v[72:75]
	v_mfma_f32_16x16x32_bf16 v[148:151], v[112:115], v[168:171], v[148:151]
	v_mfma_f32_16x16x32_bf16 v[140:143], v[120:123], v[168:171], v[140:143]
	v_mfma_f32_16x16x32_bf16 v[132:135], v[112:115], v[188:191], v[132:135]
	v_mfma_f32_16x16x32_bf16 v[128:131], v[120:123], v[188:191], v[128:131]
	v_mfma_f32_16x16x32_bf16 v[84:87], v[112:115], v[196:199], v[84:87]
	v_mfma_f32_16x16x32_bf16 v[76:79], v[120:123], v[196:199], v[76:79]
	v_mfma_f32_16x16x32_bf16 v[68:71], v[112:115], v[204:207], v[68:71]
	v_mfma_f32_16x16x32_bf16 v[64:67], v[120:123], v[204:207], v[64:67]
	v_mfma_f32_16x16x32_bf16 v[148:151], v[116:119], v[184:187], v[148:151]
	v_mfma_f32_16x16x32_bf16 v[140:143], v[124:127], v[184:187], v[140:143]
	v_mfma_f32_16x16x32_bf16 v[132:135], v[116:119], v[192:195], v[132:135]
	v_mfma_f32_16x16x32_bf16 v[128:131], v[124:127], v[192:195], v[128:131]
	v_mfma_f32_16x16x32_bf16 v[84:87], v[116:119], v[200:203], v[84:87]
	v_mfma_f32_16x16x32_bf16 v[76:79], v[124:127], v[200:203], v[76:79]
	v_mfma_f32_16x16x32_bf16 v[68:71], v[116:119], v[208:211], v[68:71]
	v_mfma_f32_16x16x32_bf16 v[64:67], v[124:127], v[208:211], v[64:67]
	s_barrier
	s_add_i32 s0, s42, s15
	v_lshl_add_u64 v[172:173], s[24:25], 0, v[160:161]
	s_mov_b32 m0, s0
	ds_read_b128 v[168:171], v181 offset:16384
	ds_read_b128 v[184:187], v181 offset:17408
	ds_read_b128 v[188:191], v181 offset:18432
	ds_read_b128 v[192:195], v181 offset:19456
	ds_read_b128 v[196:199], v181 offset:20480
	ds_read_b128 v[200:203], v181 offset:21504
	ds_read_b128 v[204:207], v181 offset:22528
	ds_read_b128 v[208:211], v181 offset:23552
	global_load_lds_dwordx4 v[172:173], off
	s_add_i32 m0, s0, 0x2000
	s_add_u32 s0, s24, 0x160000
	v_lshl_add_u64 v[212:213], s[24:25], 0, v[162:163]
	s_addc_u32 s1, s25, 0
	s_add_i32 s52, s43, s15
	global_load_lds_dwordx4 v[212:213], off
	v_lshl_add_u64 v[214:215], s[0:1], 0, v[160:161]
	s_mov_b32 m0, s52
	v_lshl_add_u64 v[216:217], s[26:27], 0, v[162:163]
	global_load_lds_dwordx4 v[214:215], off
	v_lshl_add_u64 v[214:215], s[0:1], 0, v[162:163]
	s_add_i32 m0, s52, 0x2000
	s_nop 0
	global_load_lds_dwordx4 v[214:215], off
	v_lshl_add_u64 v[214:215], s[26:27], 0, v[160:161]
	s_mov_b32 m0, s17
	s_nop 0
	global_load_lds_dwordx4 v[214:215], off
	s_mov_b32 m0, s28
	s_nop 0
	global_load_lds_dwordx4 v[216:217], off
	s_waitcnt vmcnt(8) lgkmcnt(0)
	s_barrier
; #define PG8_STAGE(bufoff, gbase, voff) do { _Pragma("unroll") for (int _i = 0; _i < 2; ++_i) \
;         __builtin_amdgcn_global_load_lds((const unsigned*)((const char*)(gbase) + (voff)[_i]), (LAS unsigned*)(lds + (bufoff) + ldsw + _i * 8192), 16, 0, 0); } while (0)
; #define PG8_LDA(dst, b, h) do { _Pragma("unroll") for (int m = 0; m < 4; ++m) _Pragma("unroll") for (int k = 0; k < 2; ++k) dst[m][k] = *(const LAS bf16x8*)(lds + PG8_SA(b, h) + aoff + m * 2048 + k * 1024); } while (0)
; #define PG8_LDB(dst, b, h) do { _Pragma("unroll") for (int n = 0; n < 2; ++n) _Pragma("unroll") for (int k = 0; k < 2; ++k) dst[n][k] = *(const LAS bf16x8*)(lds + PG8_SB(b, h) + boff + n * 2048 + k * 1024); } while (0)
; #define PG8_MMA(ai, bj, At, Bt) do { __builtin_amdgcn_s_setprio(1); _Pragma("unroll") for (int m = 0; m < 4; ++m) _Pragma("unroll") for (int n = 0; n < 2; ++n) _Pragma("unroll") for (int k = 0; k < 2; ++k) \
;         acc[ai][bj][m][n] = __builtin_amdgcn_mfma_f32_16x16x32_bf16(Bt[n][k], At[m][k], acc[ai][bj][m][n], 0, 0, 0); __builtin_amdgcn_s_setprio(0); } while (0)
; #define PG8_WAIT_V(n) asm volatile("s_waitcnt vmcnt(" #n ")" ::: "memory")
; #define PG8_WAIT_L(n) asm volatile("s_waitcnt lgkmcnt(" #n ")" ::: "memory")
; #define PG8_BAR __builtin_amdgcn_s_barrier()
; #define PG8_SCHED __builtin_amdgcn_sched_barrier(0)
; template <class Sched, class Epi, bool ALIGN_EPI, bool SP2>
; __device__ __forceinline__ void gemm_phase(LAS unsigned char* lds, const int K, const int lda, const int ldb, const Sched& S, const Epi& E) {
;     ...
;             PG8_WAIT_V(8); PG8_WAIT_L(0); PG8_BAR; PG8_MMA(1, 0, At, B0); PG8_MMA(1, 1, At, B1); PG8_BAR; PG8_SCHED;
;             PG8_LDB(B0, 1, 0); PG8_LDB(B1, 1, 1); PG8_SCHED; PG8_LDA(At, 1, 0); PG8_STAGE(PG8_SA(0, 1), a2 + hstepA, voffA);
;             PG8_WAIT_V(8); PG8_WAIT_L(0); PG8_BAR; PG8_MMA(0, 0, At, B0); PG8_MMA(0, 1, At, B1); PG8_BAR; PG8_SCHED;
	v_mfma_f32_16x16x32_bf16 v[60:63], v[96:99], v[168:171], v[60:63]
	v_mfma_f32_16x16x32_bf16 v[56:59], v[104:107], v[168:171], v[56:59]
	v_mfma_f32_16x16x32_bf16 v[48:51], v[96:99], v[188:191], v[48:51]
	v_mfma_f32_16x16x32_bf16 v[40:43], v[104:107], v[188:191], v[40:43]
	v_mfma_f32_16x16x32_bf16 v[28:31], v[96:99], v[196:199], v[28:31]
	v_mfma_f32_16x16x32_bf16 v[24:27], v[104:107], v[196:199], v[24:27]
	v_mfma_f32_16x16x32_bf16 v[16:19], v[96:99], v[204:207], v[16:19]
	v_mfma_f32_16x16x32_bf16 v[8:11], v[104:107], v[204:207], v[8:11]
	v_mfma_f32_16x16x32_bf16 v[60:63], v[100:103], v[184:187], v[60:63]
	v_mfma_f32_16x16x32_bf16 v[56:59], v[108:111], v[184:187], v[56:59]
	v_mfma_f32_16x16x32_bf16 v[48:51], v[100:103], v[192:195], v[48:51]
	v_mfma_f32_16x16x32_bf16 v[40:43], v[108:111], v[192:195], v[40:43]
	v_mfma_f32_16x16x32_bf16 v[28:31], v[100:103], v[200:203], v[28:31]
	v_mfma_f32_16x16x32_bf16 v[24:27], v[108:111], v[200:203], v[24:27]
	v_mfma_f32_16x16x32_bf16 v[16:19], v[100:103], v[208:211], v[16:19]
	v_mfma_f32_16x16x32_bf16 v[8:11], v[108:111], v[208:211], v[8:11]
	v_mfma_f32_16x16x32_bf16 v[52:55], v[112:115], v[168:171], v[52:55]
	v_mfma_f32_16x16x32_bf16 v[44:47], v[120:123], v[168:171], v[44:47]
	v_mfma_f32_16x16x32_bf16 v[36:39], v[112:115], v[188:191], v[36:39]
	v_mfma_f32_16x16x32_bf16 v[32:35], v[120:123], v[188:191], v[32:35]
	v_mfma_f32_16x16x32_bf16 v[20:23], v[112:115], v[196:199], v[20:23]
	v_mfma_f32_16x16x32_bf16 v[12:15], v[120:123], v[196:199], v[12:15]
	v_mfma_f32_16x16x32_bf16 v[4:7], v[112:115], v[204:207], v[4:7]
	v_mfma_f32_16x16x32_bf16 v[0:3], v[120:123], v[204:207], v[0:3]
	v_mfma_f32_16x16x32_bf16 v[52:55], v[116:119], v[184:187], v[52:55]
	v_mfma_f32_16x16x32_bf16 v[44:47], v[124:127], v[184:187], v[44:47]
	v_mfma_f32_16x16x32_bf16 v[36:39], v[116:119], v[192:195], v[36:39]
	v_mfma_f32_16x16x32_bf16 v[32:35], v[124:127], v[192:195], v[32:35]
	v_mfma_f32_16x16x32_bf16 v[20:23], v[116:119], v[200:203], v[20:23]
	v_mfma_f32_16x16x32_bf16 v[12:15], v[124:127], v[200:203], v[12:15]
	v_mfma_f32_16x16x32_bf16 v[4:7], v[116:119], v[208:211], v[4:7]
	v_mfma_f32_16x16x32_bf16 v[0:3], v[124:127], v[208:211], v[0:3]
	s_barrier
	s_add_i32 s52, 0, 0x18000
	s_add_i32 s53, 0, 0x1c000
	v_add_u32_e32 v108, s52, v175
	v_add_u32_e32 v124, s53, v175
	ds_read_b128 v[96:99], v108
	ds_read_b128 v[100:103], v108 offset:1024
	ds_read_b128 v[104:107], v108 offset:2048
	ds_read_b128 v[108:111], v108 offset:3072
	ds_read_b128 v[112:115], v124
	ds_read_b128 v[116:119], v124 offset:1024
	ds_read_b128 v[120:123], v124 offset:2048
	ds_read_b128 v[124:127], v124 offset:3072
	s_add_u32 s0, s26, 0x160000
	s_addc_u32 s1, s27, 0
	s_mov_b32 m0, s29
	v_lshl_add_u64 v[218:219], s[0:1], 0, v[160:161]
	ds_read_b128 v[168:171], v181 offset:32768
	ds_read_b128 v[184:187], v181 offset:33792
	ds_read_b128 v[188:191], v181 offset:34816
	ds_read_b128 v[192:195], v181 offset:35840
	ds_read_b128 v[196:199], v181 offset:36864
	ds_read_b128 v[200:203], v181 offset:37888
	ds_read_b128 v[204:207], v181 offset:38912
	ds_read_b128 v[208:211], v181 offset:39936
	global_load_lds_dwordx4 v[218:219], off
	v_lshl_add_u64 v[218:219], s[0:1], 0, v[162:163]
	s_mov_b32 m0, s33
	s_nop 0
	global_load_lds_dwordx4 v[218:219], off
	s_waitcnt vmcnt(8) lgkmcnt(0)
	s_barrier
	v_mfma_f32_16x16x32_bf16 v[156:159], v[96:99], v[168:171], v[156:159]
	v_mfma_f32_16x16x32_bf16 v[152:155], v[104:107], v[168:171], v[152:155]
	v_mfma_f32_16x16x32_bf16 v[144:147], v[96:99], v[188:191], v[144:147]
	v_mfma_f32_16x16x32_bf16 v[136:139], v[104:107], v[188:191], v[136:139]
	v_mfma_f32_16x16x32_bf16 v[92:95], v[96:99], v[196:199], v[92:95]
	v_mfma_f32_16x16x32_bf16 v[88:91], v[104:107], v[196:199], v[88:91]
	v_mfma_f32_16x16x32_bf16 v[80:83], v[96:99], v[204:207], v[80:83]
	v_mfma_f32_16x16x32_bf16 v[72:75], v[104:107], v[204:207], v[72:75]
	v_mfma_f32_16x16x32_bf16 v[156:159], v[100:103], v[184:187], v[156:159]
	v_mfma_f32_16x16x32_bf16 v[152:155], v[108:111], v[184:187], v[152:155]
	v_mfma_f32_16x16x32_bf16 v[144:147], v[100:103], v[192:195], v[144:147]
	v_mfma_f32_16x16x32_bf16 v[136:139], v[108:111], v[192:195], v[136:139]
	v_mfma_f32_16x16x32_bf16 v[92:95], v[100:103], v[200:203], v[92:95]
	v_mfma_f32_16x16x32_bf16 v[88:91], v[108:111], v[200:203], v[88:91]
	v_mfma_f32_16x16x32_bf16 v[80:83], v[100:103], v[208:211], v[80:83]
	v_mfma_f32_16x16x32_bf16 v[72:75], v[108:111], v[208:211], v[72:75]
	v_mfma_f32_16x16x32_bf16 v[148:151], v[112:115], v[168:171], v[148:151]
	v_mfma_f32_16x16x32_bf16 v[140:143], v[120:123], v[168:171], v[140:143]
	v_mfma_f32_16x16x32_bf16 v[132:135], v[112:115], v[188:191], v[132:135]
	v_mfma_f32_16x16x32_bf16 v[128:131], v[120:123], v[188:191], v[128:131]
	v_mfma_f32_16x16x32_bf16 v[84:87], v[112:115], v[196:199], v[84:87]
	v_mfma_f32_16x16x32_bf16 v[76:79], v[120:123], v[196:199], v[76:79]
	v_mfma_f32_16x16x32_bf16 v[68:71], v[112:115], v[204:207], v[68:71]
	v_mfma_f32_16x16x32_bf16 v[64:67], v[120:123], v[204:207], v[64:67]
	v_mfma_f32_16x16x32_bf16 v[148:151], v[116:119], v[184:187], v[148:151]
	v_mfma_f32_16x16x32_bf16 v[140:143], v[124:127], v[184:187], v[140:143]
	v_mfma_f32_16x16x32_bf16 v[132:135], v[116:119], v[192:195], v[132:135]
	v_mfma_f32_16x16x32_bf16 v[128:131], v[124:127], v[192:195], v[128:131]
	v_mfma_f32_16x16x32_bf16 v[84:87], v[116:119], v[200:203], v[84:87]
	v_mfma_f32_16x16x32_bf16 v[76:79], v[124:127], v[200:203], v[76:79]
	v_mfma_f32_16x16x32_bf16 v[68:71], v[116:119], v[208:211], v[68:71]
	v_mfma_f32_16x16x32_bf16 v[64:67], v[124:127], v[208:211], v[64:67]
	s_barrier
; #define PG8_STAGE(bufoff, gbase, voff) do { _Pragma("unroll") for (int _i = 0; _i < 2; ++_i) \
;         __builtin_amdgcn_global_load_lds((const unsigned*)((const char*)(gbase) + (voff)[_i]), (LAS unsigned*)(lds + (bufoff) + ldsw + _i * 8192), 16, 0, 0); } while (0)
; #define PG8_LDA(dst, b, h) do { _Pragma("unroll") for (int m = 0; m < 4; ++m) _Pragma("unroll") for (int k = 0; k < 2; ++k) dst[m][k] = *(const LAS bf16x8*)(lds + PG8_SA(b, h) + aoff + m * 2048 + k * 1024); } while (0)
; #define PG8_MMA(ai, bj, At, Bt) do { __builtin_amdgcn_s_setprio(1); _Pragma("unroll") for (int m = 0; m < 4; ++m) _Pragma("unroll") for (int n = 0; n < 2; ++n) _Pragma("unroll") for (int k = 0; k < 2; ++k) \
;         acc[ai][bj][m][n] = __builtin_amdgcn_mfma_f32_16x16x32_bf16(Bt[n][k], At[m][k], acc[ai][bj][m][n], 0, 0, 0); __builtin_amdgcn_s_setprio(0); } while (0)
; #define PG8_WAIT_V(n) asm volatile("s_waitcnt vmcnt(" #n ")" ::: "memory")
; #define PG8_WAIT_L(n) asm volatile("s_waitcnt lgkmcnt(" #n ")" ::: "memory")
; #define PG8_BAR __builtin_amdgcn_s_barrier()
; #define PG8_SCHED __builtin_amdgcn_sched_barrier(0)
; template <class Sched, class Epi, bool ALIGN_EPI, bool SP2>
; __device__ __forceinline__ void gemm_phase(LAS unsigned char* lds, const int K, const int lda, const int ldb, const Sched& S, const Epi& E) {
;     ...
;             PG8_LDA(At, 1, 1); PG8_STAGE(PG8_SB(1, 0), b3, voffB); PG8_STAGE(PG8_SB(1, 1), b3 + hstepB, voffB); PG8_STAGE(PG8_SA(1, 0), a3, voffA);
;             PG8_WAIT_V(8); PG8_WAIT_L(0); PG8_BAR; PG8_MMA(1, 0, At, B0); PG8_MMA(1, 1, At, B1); PG8_BAR; PG8_SCHED;
	s_add_i32 s0, s52, s15
	v_lshl_add_u64 v[172:173], v[172:173], 0, s[10:11]
	s_mov_b32 m0, s0
	ds_read_b128 v[168:171], v181 offset:49152
	ds_read_b128 v[184:187], v181 offset:50176
	ds_read_b128 v[188:191], v181 offset:51200
	ds_read_b128 v[192:195], v181 offset:52224
	ds_read_b128 v[196:199], v181 offset:53248
	ds_read_b128 v[200:203], v181 offset:54272
	ds_read_b128 v[204:207], v181 offset:55296
	ds_read_b128 v[208:211], v181 offset:56320
	global_load_lds_dwordx4 v[172:173], off
	s_add_i32 m0, s0, 0x2000
	s_add_u32 s0, s24, 0x160080
	v_lshl_add_u64 v[172:173], v[212:213], 0, s[10:11]
	s_addc_u32 s1, s25, 0
	s_add_i32 s24, s53, s15
	global_load_lds_dwordx4 v[172:173], off
	v_lshl_add_u64 v[172:173], s[0:1], 0, v[160:161]
	s_mov_b32 m0, s24
	s_nop 0
	global_load_lds_dwordx4 v[172:173], off
	v_lshl_add_u64 v[172:173], s[0:1], 0, v[162:163]
	s_add_i32 m0, s24, 0x2000
	s_nop 0
	global_load_lds_dwordx4 v[172:173], off
	v_lshl_add_u64 v[172:173], v[214:215], 0, s[10:11]
	s_mov_b32 m0, s36
	s_nop 0
	global_load_lds_dwordx4 v[172:173], off
	v_lshl_add_u64 v[172:173], v[216:217], 0, s[10:11]
	s_mov_b32 m0, s37
	s_nop 0
	global_load_lds_dwordx4 v[172:173], off
	s_waitcnt vmcnt(8) lgkmcnt(0)
	s_barrier
	v_mfma_f32_16x16x32_bf16 v[60:63], v[96:99], v[168:171], v[60:63]
	v_mfma_f32_16x16x32_bf16 v[56:59], v[104:107], v[168:171], v[56:59]
	v_mfma_f32_16x16x32_bf16 v[48:51], v[96:99], v[188:191], v[48:51]
	v_mfma_f32_16x16x32_bf16 v[40:43], v[104:107], v[188:191], v[40:43]
	v_mfma_f32_16x16x32_bf16 v[28:31], v[96:99], v[196:199], v[28:31]
	v_mfma_f32_16x16x32_bf16 v[24:27], v[104:107], v[196:199], v[24:27]
	v_mfma_f32_16x16x32_bf16 v[16:19], v[96:99], v[204:207], v[16:19]
	v_mfma_f32_16x16x32_bf16 v[8:11], v[104:107], v[204:207], v[8:11]
	v_mfma_f32_16x16x32_bf16 v[60:63], v[100:103], v[184:187], v[60:63]
	v_mfma_f32_16x16x32_bf16 v[56:59], v[108:111], v[184:187], v[56:59]
	v_mfma_f32_16x16x32_bf16 v[48:51], v[100:103], v[192:195], v[48:51]
	v_mfma_f32_16x16x32_bf16 v[40:43], v[108:111], v[192:195], v[40:43]
	v_mfma_f32_16x16x32_bf16 v[28:31], v[100:103], v[200:203], v[28:31]
	v_mfma_f32_16x16x32_bf16 v[24:27], v[108:111], v[200:203], v[24:27]
	v_mfma_f32_16x16x32_bf16 v[16:19], v[100:103], v[208:211], v[16:19]
	v_mfma_f32_16x16x32_bf16 v[8:11], v[108:111], v[208:211], v[8:11]
	v_mfma_f32_16x16x32_bf16 v[52:55], v[112:115], v[168:171], v[52:55]
	v_mfma_f32_16x16x32_bf16 v[44:47], v[120:123], v[168:171], v[44:47]
	v_mfma_f32_16x16x32_bf16 v[36:39], v[112:115], v[188:191], v[36:39]
	v_mfma_f32_16x16x32_bf16 v[32:35], v[120:123], v[188:191], v[32:35]
	v_mfma_f32_16x16x32_bf16 v[20:23], v[112:115], v[196:199], v[20:23]
	v_mfma_f32_16x16x32_bf16 v[12:15], v[120:123], v[196:199], v[12:15]
	v_mfma_f32_16x16x32_bf16 v[4:7], v[112:115], v[204:207], v[4:7]
	v_mfma_f32_16x16x32_bf16 v[0:3], v[120:123], v[204:207], v[0:3]
	v_mfma_f32_16x16x32_bf16 v[52:55], v[116:119], v[184:187], v[52:55]
	v_mfma_f32_16x16x32_bf16 v[44:47], v[124:127], v[184:187], v[44:47]
	v_mfma_f32_16x16x32_bf16 v[36:39], v[116:119], v[192:195], v[36:39]
	v_mfma_f32_16x16x32_bf16 v[32:35], v[124:127], v[192:195], v[32:35]
	v_mfma_f32_16x16x32_bf16 v[20:23], v[116:119], v[200:203], v[20:23]
	v_mfma_f32_16x16x32_bf16 v[12:15], v[124:127], v[200:203], v[12:15]
	v_mfma_f32_16x16x32_bf16 v[4:7], v[116:119], v[208:211], v[4:7]
	v_mfma_f32_16x16x32_bf16 v[0:3], v[124:127], v[208:211], v[0:3]
	s_barrier
	s_add_i32 s51, s51, 2
	s_add_u32 s49, s49, 0x100
	s_addc_u32 s50, s50, 0
	s_cmpk_gt_u32 s51, 0x55
	s_mov_b64 s[0:1], s[4:5]
	s_cbranch_scc0 .LBB0_1120
	s_setprio 0
	s_and_b64 vcc, exec, s[12:13]
	s_cbranch_vccz .LBB0_1123
	s_barrier
